# previous (handoff2) + post-MFMA s_barrier moved up so the last 2 MFMAs of each block issue after it
# baseline (speedup 1.0000x reference)
.LBB0_197:
	s_ashr_i32 s47, s46, 31
	ds_read_b128 v[18:21], v190
	ds_read_b128 v[22:25], v190 offset:1024
	ds_read_b128 v[26:29], v190 offset:2048
	ds_read_b128 v[30:33], v190 offset:3072
	ds_read_b128 v[2:5], v190 offset:16384
	ds_read_b128 v[6:9], v190 offset:17408
	ds_read_b128 v[10:13], v190 offset:18432
	ds_read_b128 v[14:17], v190 offset:19456
	s_lshl_b64 s[8:9], s[46:47], 20
	s_add_u32 s48, s22, s8
	s_addc_u32 s49, s23, s9
	s_and_b64 s[8:9], s[2:3], exec
	s_cselect_b32 s47, s49, s73
	s_cselect_b32 s70, s48, s72
	s_ashr_i32 s45, s44, 31
	s_lshl_b64 s[8:9], s[44:45], 20
	s_add_u32 s50, s27, s8
	s_addc_u32 s51, s68, s9
	s_and_b64 s[8:9], s[2:3], exec
	s_cselect_b32 s45, s51, s55
	s_cselect_b32 s71, s50, s54
	s_add_u32 s8, s72, 0x80080
	s_addc_u32 s9, s73, 0
	s_mov_b32 m0, s92
	v_lshl_add_u64 v[216:217], s[8:9], 0, v[164:165]
	ds_read_b128 v[180:183], v191
	ds_read_b128 v[184:187], v191 offset:1024
	ds_read_b128 v[192:195], v191 offset:2048
	ds_read_b128 v[196:199], v191 offset:3072
	ds_read_b128 v[200:203], v191 offset:4096
	ds_read_b128 v[204:207], v191 offset:5120
	ds_read_b128 v[208:211], v191 offset:6144
	ds_read_b128 v[212:215], v191 offset:7168
	global_load_lds_dwordx4 v[216:217], off
	v_lshl_add_u64 v[216:217], s[8:9], 0, v[168:169]
	s_mov_b32 m0, s93
	s_nop 0
	global_load_lds_dwordx4 v[216:217], off
	s_waitcnt vmcnt(8)
	s_waitcnt lgkmcnt(0)
	s_setprio 1
	s_barrier
	v_mfma_f32_16x16x128_f8f6f4 v[158:161], v[18:25], v[180:187], 0
	v_mfma_f32_16x16x128_f8f6f4 v[154:157], v[26:33], v[180:187], 0
	v_mfma_f32_16x16x128_f8f6f4 v[146:149], v[26:33], v[192:199], 0
	v_mfma_f32_16x16x128_f8f6f4 v[150:153], v[18:25], v[192:199], 0
	v_mfma_f32_16x16x128_f8f6f4 v[142:145], v[18:25], v[200:207], 0
	v_mfma_f32_16x16x128_f8f6f4 v[138:141], v[26:33], v[200:207], 0
	v_mfma_f32_16x16x128_f8f6f4 v[130:133], v[26:33], v[208:215], 0
	v_mfma_f32_16x16x128_f8f6f4 v[134:137], v[18:25], v[208:215], 0
	s_setprio 0
	s_setprio 1
	v_mfma_f32_16x16x128_f8f6f4 v[102:105], v[2:9], v[208:215], 0
	v_mfma_f32_16x16x128_f8f6f4 v[98:101], v[10:17], v[208:215], 0
	v_mfma_f32_16x16x128_f8f6f4 v[106:109], v[10:17], v[200:207], 0
	v_mfma_f32_16x16x128_f8f6f4 v[110:113], v[2:9], v[200:207], 0
	v_mfma_f32_16x16x128_f8f6f4 v[118:121], v[2:9], v[192:199], 0
	v_mfma_f32_16x16x128_f8f6f4 v[114:117], v[10:17], v[192:199], 0
	s_barrier
	v_mfma_f32_16x16x128_f8f6f4 v[122:125], v[10:17], v[180:187], 0
	v_mfma_f32_16x16x128_f8f6f4 v[126:129], v[2:9], v[180:187], 0
	s_setprio 0
	v_lshl_add_u64 v[180:181], s[54:55], 0, v[166:167]
	s_mov_b32 m0, s77
	v_lshl_add_u64 v[182:183], v[180:181], 0, s[16:17]
	ds_read_b128 v[192:195], v191 offset:16384
	ds_read_b128 v[196:199], v191 offset:17408
	ds_read_b128 v[200:203], v191 offset:18432
	ds_read_b128 v[204:207], v191 offset:19456
	ds_read_b128 v[208:211], v191 offset:20480
	ds_read_b128 v[212:215], v191 offset:21504
	ds_read_b128 v[216:219], v191 offset:22528
	ds_read_b128 v[220:223], v191 offset:23552
	global_load_lds_dwordx4 v[182:183], off
	v_lshl_add_u64 v[182:183], s[54:55], 0, v[170:171]
	s_add_u32 s8, s54, 0x80100
	v_lshl_add_u64 v[184:185], v[182:183], 0, s[16:17]
	s_mov_b32 m0, s78
	s_addc_u32 s9, s55, 0
	global_load_lds_dwordx4 v[184:185], off
	v_lshl_add_u64 v[184:185], s[8:9], 0, v[166:167]
	s_mov_b32 m0, s79
	s_nop 0
	global_load_lds_dwordx4 v[184:185], off
	v_lshl_add_u64 v[184:185], s[8:9], 0, v[170:171]
	s_mov_b32 m0, s80
	s_nop 0
	global_load_lds_dwordx4 v[184:185], off
	v_lshl_add_u64 v[184:185], s[72:73], 0, v[164:165]
	v_lshl_add_u64 v[186:187], v[184:185], 0, s[16:17]
	s_mov_b32 m0, s53
	s_nop 0
	global_load_lds_dwordx4 v[186:187], off
	v_lshl_add_u64 v[186:187], s[72:73], 0, v[168:169]
	v_lshl_add_u64 v[224:225], v[186:187], 0, s[16:17]
	s_mov_b32 m0, s81
	s_nop 0
	global_load_lds_dwordx4 v[224:225], off
	s_waitcnt vmcnt(8)
	s_waitcnt lgkmcnt(0)
	s_setprio 1
	s_barrier
	v_mfma_f32_16x16x128_f8f6f4 v[94:97], v[18:25], v[192:199], 0
	v_mfma_f32_16x16x128_f8f6f4 v[90:93], v[26:33], v[192:199], 0
	v_mfma_f32_16x16x128_f8f6f4 v[82:85], v[26:33], v[200:207], 0
	v_mfma_f32_16x16x128_f8f6f4 v[86:89], v[18:25], v[200:207], 0
	v_mfma_f32_16x16x128_f8f6f4 v[78:81], v[18:25], v[208:215], 0
	v_mfma_f32_16x16x128_f8f6f4 v[74:77], v[26:33], v[208:215], 0
	v_mfma_f32_16x16x128_f8f6f4 v[66:69], v[26:33], v[216:223], 0
	v_mfma_f32_16x16x128_f8f6f4 v[70:73], v[18:25], v[216:223], 0
	s_setprio 0
	s_setprio 1
	v_mfma_f32_16x16x128_f8f6f4 v[38:41], v[2:9], v[216:223], 0
	v_mfma_f32_16x16x128_f8f6f4 v[34:37], v[10:17], v[216:223], 0
	v_mfma_f32_16x16x128_f8f6f4 v[42:45], v[10:17], v[208:215], 0
	v_mfma_f32_16x16x128_f8f6f4 v[46:49], v[2:9], v[208:215], 0
	v_mfma_f32_16x16x128_f8f6f4 v[54:57], v[2:9], v[200:207], 0
	v_mfma_f32_16x16x128_f8f6f4 v[50:53], v[10:17], v[200:207], 0
	s_barrier
	v_mfma_f32_16x16x128_f8f6f4 v[58:61], v[10:17], v[192:199], 0
	v_mfma_f32_16x16x128_f8f6f4 v[62:65], v[2:9], v[192:199], 0
	s_setprio 0
	ds_read_b128 v[18:21], v190 offset:32768
	ds_read_b128 v[22:25], v190 offset:33792
	ds_read_b128 v[26:29], v190 offset:34816
	ds_read_b128 v[30:33], v190 offset:35840
	ds_read_b128 v[2:5], v190 offset:49152
	ds_read_b128 v[6:9], v190 offset:50176
	ds_read_b128 v[10:13], v190 offset:51200
	ds_read_b128 v[14:17], v190 offset:52224
	s_add_u32 s8, s72, 0x80100
	s_addc_u32 s9, s73, 0
	s_mov_b32 m0, s82
	v_lshl_add_u64 v[224:225], s[8:9], 0, v[164:165]
	ds_read_b128 v[192:195], v191 offset:32768
	ds_read_b128 v[196:199], v191 offset:33792
	ds_read_b128 v[200:203], v191 offset:34816
	ds_read_b128 v[204:207], v191 offset:35840
	ds_read_b128 v[208:211], v191 offset:36864
	ds_read_b128 v[212:215], v191 offset:37888
	ds_read_b128 v[216:219], v191 offset:38912
	ds_read_b128 v[220:223], v191 offset:39936
	global_load_lds_dwordx4 v[224:225], off
	v_lshl_add_u64 v[224:225], s[8:9], 0, v[168:169]
	s_mov_b32 m0, s83
	s_nop 0
	global_load_lds_dwordx4 v[224:225], off
	s_waitcnt vmcnt(8)
	s_waitcnt lgkmcnt(0)
	s_setprio 1
	s_barrier
	v_mfma_f32_16x16x128_f8f6f4 v[158:161], v[18:25], v[192:199], v[158:161]
	v_mfma_f32_16x16x128_f8f6f4 v[154:157], v[26:33], v[192:199], v[154:157]
	v_mfma_f32_16x16x128_f8f6f4 v[146:149], v[26:33], v[200:207], v[146:149]
	v_mfma_f32_16x16x128_f8f6f4 v[150:153], v[18:25], v[200:207], v[150:153]
	v_mfma_f32_16x16x128_f8f6f4 v[142:145], v[18:25], v[208:215], v[142:145]
	v_mfma_f32_16x16x128_f8f6f4 v[138:141], v[26:33], v[208:215], v[138:141]
	v_mfma_f32_16x16x128_f8f6f4 v[130:133], v[26:33], v[216:223], v[130:133]
	v_mfma_f32_16x16x128_f8f6f4 v[134:137], v[18:25], v[216:223], v[134:137]
	s_setprio 0
	s_setprio 1
	v_mfma_f32_16x16x128_f8f6f4 v[102:105], v[2:9], v[216:223], v[102:105]
	v_mfma_f32_16x16x128_f8f6f4 v[98:101], v[10:17], v[216:223], v[98:101]
	v_mfma_f32_16x16x128_f8f6f4 v[106:109], v[10:17], v[208:215], v[106:109]
	v_mfma_f32_16x16x128_f8f6f4 v[110:113], v[2:9], v[208:215], v[110:113]
	v_mfma_f32_16x16x128_f8f6f4 v[118:121], v[2:9], v[200:207], v[118:121]
	v_mfma_f32_16x16x128_f8f6f4 v[114:117], v[10:17], v[200:207], v[114:117]
	s_barrier
	v_mfma_f32_16x16x128_f8f6f4 v[122:125], v[10:17], v[192:199], v[122:125]
	v_mfma_f32_16x16x128_f8f6f4 v[126:129], v[2:9], v[192:199], v[126:129]
	s_setprio 0
	s_mov_b32 m0, s86
	v_lshl_add_u64 v[180:181], v[180:181], 0, s[20:21]
	s_add_u32 s8, s54, 0x80180
	ds_read_b128 v[192:195], v191 offset:49152
	ds_read_b128 v[196:199], v191 offset:50176
	ds_read_b128 v[200:203], v191 offset:51200
	ds_read_b128 v[204:207], v191 offset:52224
	ds_read_b128 v[208:211], v191 offset:53248
	ds_read_b128 v[212:215], v191 offset:54272
	ds_read_b128 v[216:219], v191 offset:55296
	ds_read_b128 v[220:223], v191 offset:56320
	global_load_lds_dwordx4 v[180:181], off
	v_lshl_add_u64 v[180:181], v[182:183], 0, s[20:21]
	s_mov_b32 m0, s87
	s_addc_u32 s9, s55, 0
	global_load_lds_dwordx4 v[180:181], off
	v_lshl_add_u64 v[180:181], s[8:9], 0, v[166:167]
	s_mov_b32 m0, s90
	s_nop 0
	global_load_lds_dwordx4 v[180:181], off
	v_lshl_add_u64 v[180:181], s[8:9], 0, v[170:171]
	s_mov_b32 m0, s91
	s_nop 0
	global_load_lds_dwordx4 v[180:181], off
	v_lshl_add_u64 v[180:181], v[184:185], 0, s[20:21]
	s_mov_b32 m0, s88
	s_nop 0
	global_load_lds_dwordx4 v[180:181], off
	v_lshl_add_u64 v[180:181], v[186:187], 0, s[20:21]
	s_mov_b32 m0, s89
	s_nop 0
	global_load_lds_dwordx4 v[180:181], off
	s_waitcnt vmcnt(8)
	s_waitcnt lgkmcnt(0)
	s_setprio 1
	s_barrier
	v_mfma_f32_16x16x128_f8f6f4 v[94:97], v[18:25], v[192:199], v[94:97]
	v_mfma_f32_16x16x128_f8f6f4 v[90:93], v[26:33], v[192:199], v[90:93]
	v_mfma_f32_16x16x128_f8f6f4 v[82:85], v[26:33], v[200:207], v[82:85]
	v_mfma_f32_16x16x128_f8f6f4 v[86:89], v[18:25], v[200:207], v[86:89]
	v_mfma_f32_16x16x128_f8f6f4 v[78:81], v[18:25], v[208:215], v[78:81]
	v_mfma_f32_16x16x128_f8f6f4 v[74:77], v[26:33], v[208:215], v[74:77]
	v_mfma_f32_16x16x128_f8f6f4 v[66:69], v[26:33], v[216:223], v[66:69]
	v_mfma_f32_16x16x128_f8f6f4 v[70:73], v[18:25], v[216:223], v[70:73]
	s_setprio 0
	s_setprio 1
	v_mfma_f32_16x16x128_f8f6f4 v[38:41], v[2:9], v[216:223], v[38:41]
	v_mfma_f32_16x16x128_f8f6f4 v[34:37], v[10:17], v[216:223], v[34:37]
	v_mfma_f32_16x16x128_f8f6f4 v[42:45], v[10:17], v[208:215], v[42:45]
	v_mfma_f32_16x16x128_f8f6f4 v[46:49], v[2:9], v[208:215], v[46:49]
	v_mfma_f32_16x16x128_f8f6f4 v[54:57], v[2:9], v[200:207], v[54:57]
	v_mfma_f32_16x16x128_f8f6f4 v[50:53], v[10:17], v[200:207], v[50:53]
	s_barrier
	v_mfma_f32_16x16x128_f8f6f4 v[58:61], v[10:17], v[192:199], v[58:61]
	v_mfma_f32_16x16x128_f8f6f4 v[62:65], v[2:9], v[192:199], v[62:65]
	s_setprio 0
	s_add_u32 s72, s72, 0x80180
	s_addc_u32 s73, s73, 0
	s_add_u32 s8, s54, 0x200
	s_addc_u32 s9, s55, 0
	s_mov_b32 s62, 0
.LBB0_198:
	ds_read_b128 v[2:5], v190
	ds_read_b128 v[6:9], v190 offset:1024
	ds_read_b128 v[18:21], v190 offset:2048
	ds_read_b128 v[22:25], v190 offset:3072
	ds_read_b128 v[26:29], v190 offset:16384
	ds_read_b128 v[30:33], v190 offset:17408
	ds_read_b128 v[180:183], v190 offset:18432
	ds_read_b128 v[184:187], v190 offset:19456
	s_add_u32 s54, s72, 0xfff80080
	s_addc_u32 s55, s73, -1
	s_cmp_eq_u32 s62, 28
	s_cselect_b32 s75, s47, s55
	s_cselect_b32 s74, s70, s54
	s_cselect_b32 s55, s45, s9
	s_cselect_b32 s54, s71, s8
	s_mov_b32 m0, s92
	v_lshl_add_u64 v[216:217], s[72:73], 0, v[172:173]
	ds_read_b128 v[10:13], v191
	ds_read_b128 v[14:17], v191 offset:1024
	ds_read_b128 v[192:195], v191 offset:2048
	ds_read_b128 v[196:199], v191 offset:3072
	ds_read_b128 v[200:203], v191 offset:4096
	ds_read_b128 v[204:207], v191 offset:5120
	ds_read_b128 v[208:211], v191 offset:6144
	ds_read_b128 v[212:215], v191 offset:7168
	global_load_lds_dwordx4 v[216:217], off
	v_lshl_add_u64 v[216:217], s[72:73], 0, v[174:175]
	s_mov_b32 m0, s93
	s_nop 0
	global_load_lds_dwordx4 v[216:217], off
	s_waitcnt vmcnt(8)
	s_waitcnt lgkmcnt(0)
	s_setprio 1
	s_barrier
	v_mfma_f32_16x16x128_f8f6f4 v[158:161], v[2:9], v[10:17], v[158:161]
	v_mfma_f32_16x16x128_f8f6f4 v[154:157], v[18:25], v[10:17], v[154:157]
	v_mfma_f32_16x16x128_f8f6f4 v[146:149], v[18:25], v[192:199], v[146:149]
	v_mfma_f32_16x16x128_f8f6f4 v[150:153], v[2:9], v[192:199], v[150:153]
	v_mfma_f32_16x16x128_f8f6f4 v[142:145], v[2:9], v[200:207], v[142:145]
	v_mfma_f32_16x16x128_f8f6f4 v[138:141], v[18:25], v[200:207], v[138:141]
	v_mfma_f32_16x16x128_f8f6f4 v[130:133], v[18:25], v[208:215], v[130:133]
	v_mfma_f32_16x16x128_f8f6f4 v[134:137], v[2:9], v[208:215], v[134:137]
	s_setprio 0
	s_setprio 1
	v_mfma_f32_16x16x128_f8f6f4 v[102:105], v[26:33], v[208:215], v[102:105]
	v_mfma_f32_16x16x128_f8f6f4 v[98:101], v[180:187], v[208:215], v[98:101]
	v_mfma_f32_16x16x128_f8f6f4 v[106:109], v[180:187], v[200:207], v[106:109]
	v_mfma_f32_16x16x128_f8f6f4 v[110:113], v[26:33], v[200:207], v[110:113]
	v_mfma_f32_16x16x128_f8f6f4 v[118:121], v[26:33], v[192:199], v[118:121]
	v_mfma_f32_16x16x128_f8f6f4 v[114:117], v[180:187], v[192:199], v[114:117]
	s_barrier
	v_mfma_f32_16x16x128_f8f6f4 v[122:125], v[180:187], v[10:17], v[122:125]
	v_mfma_f32_16x16x128_f8f6f4 v[126:129], v[26:33], v[10:17], v[126:129]
	s_setprio 0
	s_mov_b32 m0, s77
	v_lshl_add_u64 v[10:11], s[54:55], 0, v[166:167]
	s_add_u32 vcc_lo, s54, 0x80000
	ds_read_b128 v[192:195], v191 offset:16384
	ds_read_b128 v[196:199], v191 offset:17408
	ds_read_b128 v[200:203], v191 offset:18432
	ds_read_b128 v[204:207], v191 offset:19456
	ds_read_b128 v[208:211], v191 offset:20480
	ds_read_b128 v[212:215], v191 offset:21504
	ds_read_b128 v[216:219], v191 offset:22528
	ds_read_b128 v[220:223], v191 offset:23552
	global_load_lds_dwordx4 v[10:11], off
	v_lshl_add_u64 v[12:13], s[54:55], 0, v[170:171]
	s_mov_b32 m0, s78
	s_addc_u32 vcc_hi, s55, 0
	global_load_lds_dwordx4 v[12:13], off
	v_lshl_add_u64 v[14:15], vcc, 0, v[166:167]
	s_mov_b32 m0, s79
	v_lshl_add_u64 v[16:17], s[74:75], 0, v[168:169]
	global_load_lds_dwordx4 v[14:15], off
	v_lshl_add_u64 v[14:15], vcc, 0, v[170:171]
	s_mov_b32 m0, s80
	s_nop 0
	global_load_lds_dwordx4 v[14:15], off
	v_lshl_add_u64 v[14:15], s[74:75], 0, v[164:165]
	s_mov_b32 m0, s53
	s_nop 0
	global_load_lds_dwordx4 v[14:15], off
	s_mov_b32 m0, s81
	s_nop 0
	global_load_lds_dwordx4 v[16:17], off
	s_waitcnt vmcnt(8)
	s_waitcnt lgkmcnt(0)
	s_setprio 1
	s_barrier
	v_mfma_f32_16x16x128_f8f6f4 v[94:97], v[2:9], v[192:199], v[94:97]
	v_mfma_f32_16x16x128_f8f6f4 v[90:93], v[18:25], v[192:199], v[90:93]
	v_mfma_f32_16x16x128_f8f6f4 v[82:85], v[18:25], v[200:207], v[82:85]
	v_mfma_f32_16x16x128_f8f6f4 v[86:89], v[2:9], v[200:207], v[86:89]
	v_mfma_f32_16x16x128_f8f6f4 v[78:81], v[2:9], v[208:215], v[78:81]
	v_mfma_f32_16x16x128_f8f6f4 v[74:77], v[18:25], v[208:215], v[74:77]
	v_mfma_f32_16x16x128_f8f6f4 v[66:69], v[18:25], v[216:223], v[66:69]
	v_mfma_f32_16x16x128_f8f6f4 v[70:73], v[2:9], v[216:223], v[70:73]
	s_setprio 0
	s_setprio 1
	v_mfma_f32_16x16x128_f8f6f4 v[38:41], v[26:33], v[216:223], v[38:41]
	v_mfma_f32_16x16x128_f8f6f4 v[34:37], v[180:187], v[216:223], v[34:37]
	v_mfma_f32_16x16x128_f8f6f4 v[42:45], v[180:187], v[208:215], v[42:45]
	v_mfma_f32_16x16x128_f8f6f4 v[46:49], v[26:33], v[208:215], v[46:49]
	v_mfma_f32_16x16x128_f8f6f4 v[54:57], v[26:33], v[200:207], v[54:57]
	v_mfma_f32_16x16x128_f8f6f4 v[50:53], v[180:187], v[200:207], v[50:53]
	s_barrier
	v_mfma_f32_16x16x128_f8f6f4 v[58:61], v[180:187], v[192:199], v[58:61]
	v_mfma_f32_16x16x128_f8f6f4 v[62:65], v[26:33], v[192:199], v[62:65]
	s_setprio 0
	ds_read_b128 v[18:21], v190 offset:32768
	ds_read_b128 v[22:25], v190 offset:33792
	ds_read_b128 v[26:29], v190 offset:34816
	ds_read_b128 v[30:33], v190 offset:35840
	ds_read_b128 v[2:5], v190 offset:49152
	ds_read_b128 v[6:9], v190 offset:50176
	ds_read_b128 v[180:183], v190 offset:51200
	ds_read_b128 v[184:187], v190 offset:52224
	s_add_u32 s74, s74, 0x80000
	s_addc_u32 s75, s75, 0
	s_mov_b32 m0, s82
	v_lshl_add_u64 v[224:225], s[74:75], 0, v[164:165]
	ds_read_b128 v[192:195], v191 offset:32768
	ds_read_b128 v[196:199], v191 offset:33792
	ds_read_b128 v[200:203], v191 offset:34816
	ds_read_b128 v[204:207], v191 offset:35840
	ds_read_b128 v[208:211], v191 offset:36864
	ds_read_b128 v[212:215], v191 offset:37888
	ds_read_b128 v[216:219], v191 offset:38912
	ds_read_b128 v[220:223], v191 offset:39936
	global_load_lds_dwordx4 v[224:225], off
	v_lshl_add_u64 v[224:225], s[74:75], 0, v[168:169]
	s_mov_b32 m0, s83
	s_nop 0
	global_load_lds_dwordx4 v[224:225], off
	s_waitcnt vmcnt(8)
	s_waitcnt lgkmcnt(0)
	s_setprio 1
	s_barrier
	v_mfma_f32_16x16x128_f8f6f4 v[158:161], v[18:25], v[192:199], v[158:161]
	v_mfma_f32_16x16x128_f8f6f4 v[154:157], v[26:33], v[192:199], v[154:157]
	v_mfma_f32_16x16x128_f8f6f4 v[146:149], v[26:33], v[200:207], v[146:149]
	v_mfma_f32_16x16x128_f8f6f4 v[150:153], v[18:25], v[200:207], v[150:153]
	v_mfma_f32_16x16x128_f8f6f4 v[142:145], v[18:25], v[208:215], v[142:145]
	v_mfma_f32_16x16x128_f8f6f4 v[138:141], v[26:33], v[208:215], v[138:141]
	v_mfma_f32_16x16x128_f8f6f4 v[130:133], v[26:33], v[216:223], v[130:133]
	v_mfma_f32_16x16x128_f8f6f4 v[134:137], v[18:25], v[216:223], v[134:137]
	s_setprio 0
	s_setprio 1
	v_mfma_f32_16x16x128_f8f6f4 v[102:105], v[2:9], v[216:223], v[102:105]
	v_mfma_f32_16x16x128_f8f6f4 v[98:101], v[180:187], v[216:223], v[98:101]
	v_mfma_f32_16x16x128_f8f6f4 v[106:109], v[180:187], v[208:215], v[106:109]
	v_mfma_f32_16x16x128_f8f6f4 v[110:113], v[2:9], v[208:215], v[110:113]
	v_mfma_f32_16x16x128_f8f6f4 v[118:121], v[2:9], v[200:207], v[118:121]
	v_mfma_f32_16x16x128_f8f6f4 v[114:117], v[180:187], v[200:207], v[114:117]
	s_barrier
	v_mfma_f32_16x16x128_f8f6f4 v[122:125], v[180:187], v[192:199], v[122:125]
	v_mfma_f32_16x16x128_f8f6f4 v[126:129], v[2:9], v[192:199], v[126:129]
	s_setprio 0
	s_mov_b32 m0, s86
	v_lshl_add_u64 v[10:11], v[10:11], 0, s[4:5]
	s_add_u32 s54, s54, 0x80080
	ds_read_b128 v[192:195], v191 offset:49152
	ds_read_b128 v[196:199], v191 offset:50176
	ds_read_b128 v[200:203], v191 offset:51200
	ds_read_b128 v[204:207], v191 offset:52224
	ds_read_b128 v[208:211], v191 offset:53248
	ds_read_b128 v[212:215], v191 offset:54272
	ds_read_b128 v[216:219], v191 offset:55296
	ds_read_b128 v[220:223], v191 offset:56320
	global_load_lds_dwordx4 v[10:11], off
	v_lshl_add_u64 v[10:11], v[12:13], 0, s[4:5]
	s_mov_b32 m0, s87
	s_addc_u32 s55, s55, 0
	global_load_lds_dwordx4 v[10:11], off
	v_lshl_add_u64 v[10:11], s[54:55], 0, v[166:167]
	s_mov_b32 m0, s90
	s_nop 0
	global_load_lds_dwordx4 v[10:11], off
	v_lshl_add_u64 v[10:11], s[54:55], 0, v[170:171]
	s_mov_b32 m0, s91
	s_nop 0
	global_load_lds_dwordx4 v[10:11], off
	v_lshl_add_u64 v[10:11], v[14:15], 0, s[4:5]
	s_mov_b32 m0, s88
	s_nop 0
	global_load_lds_dwordx4 v[10:11], off
	v_lshl_add_u64 v[10:11], v[16:17], 0, s[4:5]
	s_mov_b32 m0, s89
	s_nop 0
	global_load_lds_dwordx4 v[10:11], off
	s_waitcnt vmcnt(8)
	s_waitcnt lgkmcnt(0)
	s_setprio 1
	s_barrier
	v_mfma_f32_16x16x128_f8f6f4 v[94:97], v[18:25], v[192:199], v[94:97]
	v_mfma_f32_16x16x128_f8f6f4 v[90:93], v[26:33], v[192:199], v[90:93]
	v_mfma_f32_16x16x128_f8f6f4 v[82:85], v[26:33], v[200:207], v[82:85]
	v_mfma_f32_16x16x128_f8f6f4 v[86:89], v[18:25], v[200:207], v[86:89]
	v_mfma_f32_16x16x128_f8f6f4 v[78:81], v[18:25], v[208:215], v[78:81]
	v_mfma_f32_16x16x128_f8f6f4 v[74:77], v[26:33], v[208:215], v[74:77]
	v_mfma_f32_16x16x128_f8f6f4 v[66:69], v[26:33], v[216:223], v[66:69]
	v_mfma_f32_16x16x128_f8f6f4 v[70:73], v[18:25], v[216:223], v[70:73]
	s_setprio 0
	s_setprio 1
	v_mfma_f32_16x16x128_f8f6f4 v[38:41], v[2:9], v[216:223], v[38:41]
	v_mfma_f32_16x16x128_f8f6f4 v[34:37], v[180:187], v[216:223], v[34:37]
	v_mfma_f32_16x16x128_f8f6f4 v[42:45], v[180:187], v[208:215], v[42:45]
	v_mfma_f32_16x16x128_f8f6f4 v[46:49], v[2:9], v[208:215], v[46:49]
	v_mfma_f32_16x16x128_f8f6f4 v[54:57], v[2:9], v[200:207], v[54:57]
	v_mfma_f32_16x16x128_f8f6f4 v[50:53], v[180:187], v[200:207], v[50:53]
	s_barrier
	v_mfma_f32_16x16x128_f8f6f4 v[58:61], v[180:187], v[192:199], v[58:61]
	v_mfma_f32_16x16x128_f8f6f4 v[62:65], v[2:9], v[192:199], v[62:65]
	s_setprio 0
	s_add_i32 s62, s62, 2
	s_add_u32 s72, s72, 0x100
	s_addc_u32 s73, s73, 0
	s_add_u32 s8, s8, 0x100
	s_addc_u32 s9, s9, 0
	s_cmp_gt_u32 s62, 29
	s_cbranch_scc0 .LBB0_198
	s_and_b64 vcc, exec, s[6:7]
	s_cbranch_vccz .LBB0_201
	s_barrier

.LBB0_282:
	ds_read_b128 v[2:5], v187
	ds_read_b128 v[6:9], v187 offset:1024
	ds_read_b128 v[174:177], v187 offset:2048
	ds_read_b128 v[178:181], v187 offset:3072
	ds_read_b128 v[190:193], v187 offset:16384
	ds_read_b128 v[194:197], v187 offset:17408
	ds_read_b128 v[198:201], v187 offset:18432
	ds_read_b128 v[202:205], v187 offset:19456
	s_add_u32 s49, s52, 0x100
	s_addc_u32 s71, s53, 0
	s_and_b64 s[62:63], s[54:55], exec
	s_cselect_b32 s73, s1, s71
	s_cselect_b32 s72, s0, s49
	s_add_u32 s49, s50, 0x100
	s_addc_u32 s62, s51, 0
	s_and_b64 s[54:55], s[54:55], exec
	s_cselect_b32 s55, s5, s62
	s_cselect_b32 s54, s4, s49
	s_add_u32 s62, s52, 0x158080
	s_addc_u32 s63, s53, 0
	s_add_i32 s49, s33, 0xc000
	v_lshl_add_u64 v[182:183], s[62:63], 0, v[154:155]
	s_mov_b32 m0, s49
	s_add_i32 s71, s33, 0xe000
	ds_read_b128 v[206:209], v188
	ds_read_b128 v[210:213], v188 offset:1024
	ds_read_b128 v[214:217], v188 offset:2048
	ds_read_b128 v[218:221], v188 offset:3072
	ds_read_b128 v[222:225], v188 offset:4096
	ds_read_b128 v[226:229], v188 offset:5120
	ds_read_b128 v[230:233], v188 offset:6144
	ds_read_b128 v[234:237], v188 offset:7168
	global_load_lds_dwordx4 v[182:183], off
	v_lshl_add_u64 v[182:183], s[62:63], 0, v[158:159]
	s_mov_b32 m0, s71
	s_nop 0
	global_load_lds_dwordx4 v[182:183], off
	s_waitcnt vmcnt(8)
	s_waitcnt lgkmcnt(0)
	s_setprio 1
	s_barrier
	v_mfma_f32_16x16x128_f8f6f4 v[134:137], v[2:9], v[206:213], 0
	v_mfma_f32_16x16x128_f8f6f4 v[130:133], v[174:181], v[206:213], 0
	v_mfma_f32_16x16x128_f8f6f4 v[122:125], v[174:181], v[214:221], 0
	v_mfma_f32_16x16x128_f8f6f4 v[126:129], v[2:9], v[214:221], 0
	v_mfma_f32_16x16x128_f8f6f4 v[118:121], v[2:9], v[222:229], 0
	v_mfma_f32_16x16x128_f8f6f4 v[114:117], v[174:181], v[222:229], 0
	v_mfma_f32_16x16x128_f8f6f4 v[106:109], v[174:181], v[230:237], 0
	v_mfma_f32_16x16x128_f8f6f4 v[110:113], v[2:9], v[230:237], 0
	s_setprio 0
	s_setprio 1
	v_mfma_f32_16x16x128_f8f6f4 v[78:81], v[190:197], v[230:237], 0
	v_mfma_f32_16x16x128_f8f6f4 v[74:77], v[198:205], v[230:237], 0
	v_mfma_f32_16x16x128_f8f6f4 v[82:85], v[198:205], v[222:229], 0
	v_mfma_f32_16x16x128_f8f6f4 v[86:89], v[190:197], v[222:229], 0
	v_mfma_f32_16x16x128_f8f6f4 v[94:97], v[190:197], v[214:221], 0
	v_mfma_f32_16x16x128_f8f6f4 v[90:93], v[198:205], v[214:221], 0
	s_barrier
	v_mfma_f32_16x16x128_f8f6f4 v[98:101], v[198:205], v[206:213], 0
	v_mfma_f32_16x16x128_f8f6f4 v[102:105], v[190:197], v[206:213], 0
	s_setprio 0
	s_mov_b32 m0, s47
	v_lshl_add_u64 v[182:183], s[54:55], 0, v[156:157]
	s_add_u32 s62, s54, 0x158000
	ds_read_b128 v[206:209], v188 offset:16384
	ds_read_b128 v[210:213], v188 offset:17408
	ds_read_b128 v[214:217], v188 offset:18432
	ds_read_b128 v[218:221], v188 offset:19456
	ds_read_b128 v[222:225], v188 offset:20480
	ds_read_b128 v[226:229], v188 offset:21504
	ds_read_b128 v[230:233], v188 offset:22528
	ds_read_b128 v[234:237], v188 offset:23552
	global_load_lds_dwordx4 v[182:183], off
	v_lshl_add_u64 v[238:239], s[54:55], 0, v[160:161]
	s_mov_b32 m0, s68
	s_addc_u32 s63, s55, 0
	global_load_lds_dwordx4 v[238:239], off
	v_lshl_add_u64 v[242:243], s[62:63], 0, v[156:157]
	s_mov_b32 m0, s69
	v_lshl_add_u64 v[244:245], s[72:73], 0, v[158:159]
	global_load_lds_dwordx4 v[242:243], off
	v_lshl_add_u64 v[242:243], s[62:63], 0, v[160:161]
	s_mov_b32 m0, s74
	s_nop 0
	global_load_lds_dwordx4 v[242:243], off
	v_lshl_add_u64 v[242:243], s[72:73], 0, v[154:155]
	s_mov_b32 m0, s33
	s_nop 0
	global_load_lds_dwordx4 v[242:243], off
	s_mov_b32 m0, s75
	s_nop 0
	global_load_lds_dwordx4 v[244:245], off
	s_waitcnt vmcnt(8)
	s_waitcnt lgkmcnt(0)
	s_setprio 1
	s_barrier
	v_mfma_f32_16x16x128_f8f6f4 v[70:73], v[2:9], v[206:213], 0
	v_mfma_f32_16x16x128_f8f6f4 v[66:69], v[174:181], v[206:213], 0
	v_mfma_f32_16x16x128_f8f6f4 v[58:61], v[174:181], v[214:221], 0
	v_mfma_f32_16x16x128_f8f6f4 v[62:65], v[2:9], v[214:221], 0
	v_mfma_f32_16x16x128_f8f6f4 v[54:57], v[2:9], v[222:229], 0
	v_mfma_f32_16x16x128_f8f6f4 v[50:53], v[174:181], v[222:229], 0
	v_mfma_f32_16x16x128_f8f6f4 v[42:45], v[174:181], v[230:237], 0
	v_mfma_f32_16x16x128_f8f6f4 v[46:49], v[2:9], v[230:237], 0
	s_setprio 0
	s_setprio 1
	v_mfma_f32_16x16x128_f8f6f4 v[14:17], v[190:197], v[230:237], 0
	v_mfma_f32_16x16x128_f8f6f4 v[10:13], v[198:205], v[230:237], 0
	v_mfma_f32_16x16x128_f8f6f4 v[18:21], v[198:205], v[222:229], 0
	v_mfma_f32_16x16x128_f8f6f4 v[22:25], v[190:197], v[222:229], 0
	v_mfma_f32_16x16x128_f8f6f4 v[30:33], v[190:197], v[214:221], 0
	v_mfma_f32_16x16x128_f8f6f4 v[26:29], v[198:205], v[214:221], 0
	s_barrier
	v_mfma_f32_16x16x128_f8f6f4 v[34:37], v[198:205], v[206:213], 0
	v_mfma_f32_16x16x128_f8f6f4 v[38:41], v[190:197], v[206:213], 0
	s_setprio 0
	ds_read_b128 v[2:5], v187 offset:32768
	ds_read_b128 v[6:9], v187 offset:33792
	ds_read_b128 v[174:177], v187 offset:34816
	ds_read_b128 v[178:181], v187 offset:35840
	ds_read_b128 v[190:193], v187 offset:49152
	ds_read_b128 v[194:197], v187 offset:50176
	ds_read_b128 v[198:201], v187 offset:51200
	ds_read_b128 v[202:205], v187 offset:52224
	s_add_u32 s62, s72, 0x158000
	s_addc_u32 s63, s73, 0
	s_mov_b32 m0, s76
	v_lshl_add_u64 v[246:247], s[62:63], 0, v[154:155]
	ds_read_b128 v[206:209], v188 offset:32768
	ds_read_b128 v[210:213], v188 offset:33792
	ds_read_b128 v[214:217], v188 offset:34816
	ds_read_b128 v[218:221], v188 offset:35840
	ds_read_b128 v[222:225], v188 offset:36864
	ds_read_b128 v[226:229], v188 offset:37888
	ds_read_b128 v[230:233], v188 offset:38912
	ds_read_b128 v[234:237], v188 offset:39936
	global_load_lds_dwordx4 v[246:247], off
	v_lshl_add_u64 v[246:247], s[62:63], 0, v[158:159]
	s_mov_b32 m0, s77
	s_nop 0
	global_load_lds_dwordx4 v[246:247], off
	s_waitcnt vmcnt(8)
	s_waitcnt lgkmcnt(0)
	s_setprio 1
	s_barrier
	v_mfma_f32_16x16x128_f8f6f4 v[134:137], v[2:9], v[206:213], v[134:137]
	v_mfma_f32_16x16x128_f8f6f4 v[130:133], v[174:181], v[206:213], v[130:133]
	v_mfma_f32_16x16x128_f8f6f4 v[122:125], v[174:181], v[214:221], v[122:125]
	v_mfma_f32_16x16x128_f8f6f4 v[126:129], v[2:9], v[214:221], v[126:129]
	v_mfma_f32_16x16x128_f8f6f4 v[118:121], v[2:9], v[222:229], v[118:121]
	v_mfma_f32_16x16x128_f8f6f4 v[114:117], v[174:181], v[222:229], v[114:117]
	v_mfma_f32_16x16x128_f8f6f4 v[106:109], v[174:181], v[230:237], v[106:109]
	v_mfma_f32_16x16x128_f8f6f4 v[110:113], v[2:9], v[230:237], v[110:113]
	s_setprio 0
	s_setprio 1
	v_mfma_f32_16x16x128_f8f6f4 v[78:81], v[190:197], v[230:237], v[78:81]
	v_mfma_f32_16x16x128_f8f6f4 v[74:77], v[198:205], v[230:237], v[74:77]
	v_mfma_f32_16x16x128_f8f6f4 v[82:85], v[198:205], v[222:229], v[82:85]
	v_mfma_f32_16x16x128_f8f6f4 v[86:89], v[190:197], v[222:229], v[86:89]
	v_mfma_f32_16x16x128_f8f6f4 v[94:97], v[190:197], v[214:221], v[94:97]
	v_mfma_f32_16x16x128_f8f6f4 v[90:93], v[198:205], v[214:221], v[90:93]
	s_barrier
	v_mfma_f32_16x16x128_f8f6f4 v[98:101], v[198:205], v[206:213], v[98:101]
	v_mfma_f32_16x16x128_f8f6f4 v[102:105], v[190:197], v[206:213], v[102:105]
	s_setprio 0
	s_mov_b32 m0, s83
	v_lshl_add_u64 v[182:183], v[182:183], 0, s[26:27]
	s_add_u32 s54, s54, 0x158080
	ds_read_b128 v[206:209], v188 offset:49152
	ds_read_b128 v[210:213], v188 offset:50176
	ds_read_b128 v[214:217], v188 offset:51200
	ds_read_b128 v[218:221], v188 offset:52224
	ds_read_b128 v[222:225], v188 offset:53248
	ds_read_b128 v[226:229], v188 offset:54272
	ds_read_b128 v[230:233], v188 offset:55296
	ds_read_b128 v[234:237], v188 offset:56320
	global_load_lds_dwordx4 v[182:183], off
	v_lshl_add_u64 v[182:183], v[238:239], 0, s[26:27]
	s_mov_b32 m0, s84
	s_addc_u32 s55, s55, 0
	global_load_lds_dwordx4 v[182:183], off
	v_lshl_add_u64 v[182:183], s[54:55], 0, v[156:157]
	s_mov_b32 m0, s87
	s_nop 0
	global_load_lds_dwordx4 v[182:183], off
	v_lshl_add_u64 v[182:183], s[54:55], 0, v[160:161]
	s_mov_b32 m0, s88
	s_nop 0
	global_load_lds_dwordx4 v[182:183], off
	v_lshl_add_u64 v[182:183], v[242:243], 0, s[26:27]
	s_mov_b32 m0, s85
	s_nop 0
	global_load_lds_dwordx4 v[182:183], off
	v_lshl_add_u64 v[182:183], v[244:245], 0, s[26:27]
	s_mov_b32 m0, s86
	s_nop 0
	global_load_lds_dwordx4 v[182:183], off
	s_waitcnt vmcnt(8)
	s_waitcnt lgkmcnt(0)
	s_setprio 1
	s_barrier
	v_mfma_f32_16x16x128_f8f6f4 v[70:73], v[2:9], v[206:213], v[70:73]
	v_mfma_f32_16x16x128_f8f6f4 v[66:69], v[174:181], v[206:213], v[66:69]
	v_mfma_f32_16x16x128_f8f6f4 v[58:61], v[174:181], v[214:221], v[58:61]
	v_mfma_f32_16x16x128_f8f6f4 v[62:65], v[2:9], v[214:221], v[62:65]
	v_mfma_f32_16x16x128_f8f6f4 v[54:57], v[2:9], v[222:229], v[54:57]
	v_mfma_f32_16x16x128_f8f6f4 v[50:53], v[174:181], v[222:229], v[50:53]
	v_mfma_f32_16x16x128_f8f6f4 v[42:45], v[174:181], v[230:237], v[42:45]
	v_mfma_f32_16x16x128_f8f6f4 v[46:49], v[2:9], v[230:237], v[46:49]
	s_setprio 0
	s_setprio 1
	v_mfma_f32_16x16x128_f8f6f4 v[14:17], v[190:197], v[230:237], v[14:17]
	v_mfma_f32_16x16x128_f8f6f4 v[10:13], v[198:205], v[230:237], v[10:13]
	v_mfma_f32_16x16x128_f8f6f4 v[18:21], v[198:205], v[222:229], v[18:21]
	v_mfma_f32_16x16x128_f8f6f4 v[22:25], v[190:197], v[222:229], v[22:25]
	v_mfma_f32_16x16x128_f8f6f4 v[30:33], v[190:197], v[214:221], v[30:33]
	v_mfma_f32_16x16x128_f8f6f4 v[26:29], v[198:205], v[214:221], v[26:29]
	s_barrier
	v_mfma_f32_16x16x128_f8f6f4 v[34:37], v[198:205], v[206:213], v[34:37]
	v_mfma_f32_16x16x128_f8f6f4 v[38:41], v[190:197], v[206:213], v[38:41]
	s_setprio 0
	s_cmp_lt_u32 s95, 3
	s_cbranch_scc1 .LBB0_287
	s_add_u32 s54, s79, s9
	s_addc_u32 s55, s80, s8
	s_add_u32 s52, s52, 0x158180
	s_addc_u32 s53, s53, 0
	s_add_u32 s8, s50, 0x200
	v_lshl_add_u64 v[174:175], v[172:173], 2, s[54:55]
	s_addc_u32 s9, s51, 0
	s_mov_b32 s72, 4
	s_cmp_eq_u32 s95, s72
	s_cselect_b64 s[50:51], -1, 0
	s_cmp_lg_u32 s95, s72
	s_cbranch_scc1 .LBB0_285

.LBB0_285:
	ds_read_b128 v[2:5], v187
	ds_read_b128 v[6:9], v187 offset:1024
	ds_read_b128 v[190:193], v187 offset:2048
	ds_read_b128 v[194:197], v187 offset:3072
	ds_read_b128 v[198:201], v187 offset:16384
	ds_read_b128 v[202:205], v187 offset:17408
	ds_read_b128 v[206:209], v187 offset:18432
	ds_read_b128 v[210:213], v187 offset:19456
	s_add_u32 s54, s52, 0xffea8080
	s_addc_u32 s55, s53, -1
	s_and_b64 s[50:51], s[50:51], exec
	s_cselect_b32 s50, s4, s8
	s_cselect_b32 s55, s1, s55
	s_cselect_b32 s54, s0, s54
	s_cselect_b32 s51, s5, s9
	s_mov_b32 m0, s49
	v_lshl_add_u64 v[238:239], s[52:53], 0, v[162:163]
	ds_read_b128 v[176:179], v188
	ds_read_b128 v[180:183], v188 offset:1024
	ds_read_b128 v[214:217], v188 offset:2048
	ds_read_b128 v[218:221], v188 offset:3072
	ds_read_b128 v[222:225], v188 offset:4096
	ds_read_b128 v[226:229], v188 offset:5120
	ds_read_b128 v[230:233], v188 offset:6144
	ds_read_b128 v[234:237], v188 offset:7168
	global_load_lds_dwordx4 v[238:239], off
	v_lshl_add_u64 v[238:239], s[52:53], 0, v[164:165]
	s_mov_b32 m0, s71
	s_nop 0
	global_load_lds_dwordx4 v[238:239], off
	s_waitcnt vmcnt(8)
	s_waitcnt lgkmcnt(0)
	s_setprio 1
	s_barrier
	v_mfma_f32_16x16x128_f8f6f4 v[134:137], v[2:9], v[176:183], v[134:137]
	v_mfma_f32_16x16x128_f8f6f4 v[130:133], v[190:197], v[176:183], v[130:133]
	v_mfma_f32_16x16x128_f8f6f4 v[122:125], v[190:197], v[214:221], v[122:125]
	v_mfma_f32_16x16x128_f8f6f4 v[126:129], v[2:9], v[214:221], v[126:129]
	v_mfma_f32_16x16x128_f8f6f4 v[118:121], v[2:9], v[222:229], v[118:121]
	v_mfma_f32_16x16x128_f8f6f4 v[114:117], v[190:197], v[222:229], v[114:117]
	v_mfma_f32_16x16x128_f8f6f4 v[106:109], v[190:197], v[230:237], v[106:109]
	v_mfma_f32_16x16x128_f8f6f4 v[110:113], v[2:9], v[230:237], v[110:113]
	s_setprio 0
	s_setprio 1
	v_mfma_f32_16x16x128_f8f6f4 v[78:81], v[198:205], v[230:237], v[78:81]
	v_mfma_f32_16x16x128_f8f6f4 v[74:77], v[206:213], v[230:237], v[74:77]
	v_mfma_f32_16x16x128_f8f6f4 v[82:85], v[206:213], v[222:229], v[82:85]
	v_mfma_f32_16x16x128_f8f6f4 v[86:89], v[198:205], v[222:229], v[86:89]
	v_mfma_f32_16x16x128_f8f6f4 v[94:97], v[198:205], v[214:221], v[94:97]
	v_mfma_f32_16x16x128_f8f6f4 v[90:93], v[206:213], v[214:221], v[90:93]
	s_barrier
	v_mfma_f32_16x16x128_f8f6f4 v[98:101], v[206:213], v[176:183], v[98:101]
	v_mfma_f32_16x16x128_f8f6f4 v[102:105], v[198:205], v[176:183], v[102:105]
	s_setprio 0
	s_mov_b32 m0, s47
	v_lshl_add_u64 v[176:177], s[50:51], 0, v[156:157]
	s_add_u32 s62, s50, 0x158000
	ds_read_b128 v[214:217], v188 offset:16384
	ds_read_b128 v[218:221], v188 offset:17408
	ds_read_b128 v[222:225], v188 offset:18432
	ds_read_b128 v[226:229], v188 offset:19456
	ds_read_b128 v[230:233], v188 offset:20480
	ds_read_b128 v[234:237], v188 offset:21504
	ds_read_b128 v[242:245], v188 offset:22528
	ds_read_b128 v[246:249], v188 offset:23552
	global_load_lds_dwordx4 v[176:177], off
	v_lshl_add_u64 v[178:179], s[50:51], 0, v[160:161]
	s_mov_b32 m0, s68
	s_addc_u32 s63, s51, 0
	global_load_lds_dwordx4 v[178:179], off
	v_lshl_add_u64 v[180:181], s[62:63], 0, v[156:157]
	s_mov_b32 m0, s69
	v_lshl_add_u64 v[182:183], s[54:55], 0, v[158:159]
	global_load_lds_dwordx4 v[180:181], off
	v_lshl_add_u64 v[180:181], s[62:63], 0, v[160:161]
	s_mov_b32 m0, s74
	s_nop 0
	global_load_lds_dwordx4 v[180:181], off
	v_lshl_add_u64 v[180:181], s[54:55], 0, v[154:155]
	s_mov_b32 m0, s33
	s_nop 0
	global_load_lds_dwordx4 v[180:181], off
	s_mov_b32 m0, s75
	s_nop 0
	global_load_lds_dwordx4 v[182:183], off
	s_waitcnt vmcnt(8)
	s_waitcnt lgkmcnt(0)
	s_setprio 1
	s_barrier
	v_mfma_f32_16x16x128_f8f6f4 v[70:73], v[2:9], v[214:221], v[70:73]
	v_mfma_f32_16x16x128_f8f6f4 v[66:69], v[190:197], v[214:221], v[66:69]
	v_mfma_f32_16x16x128_f8f6f4 v[58:61], v[190:197], v[222:229], v[58:61]
	v_mfma_f32_16x16x128_f8f6f4 v[62:65], v[2:9], v[222:229], v[62:65]
	v_mfma_f32_16x16x128_f8f6f4 v[54:57], v[2:9], v[230:237], v[54:57]
	v_mfma_f32_16x16x128_f8f6f4 v[50:53], v[190:197], v[230:237], v[50:53]
	v_mfma_f32_16x16x128_f8f6f4 v[42:45], v[190:197], v[242:249], v[42:45]
	v_mfma_f32_16x16x128_f8f6f4 v[46:49], v[2:9], v[242:249], v[46:49]
	s_setprio 0
	s_setprio 1
	v_mfma_f32_16x16x128_f8f6f4 v[14:17], v[198:205], v[242:249], v[14:17]
	v_mfma_f32_16x16x128_f8f6f4 v[10:13], v[206:213], v[242:249], v[10:13]
	v_mfma_f32_16x16x128_f8f6f4 v[18:21], v[206:213], v[230:237], v[18:21]
	v_mfma_f32_16x16x128_f8f6f4 v[22:25], v[198:205], v[230:237], v[22:25]
	v_mfma_f32_16x16x128_f8f6f4 v[30:33], v[198:205], v[222:229], v[30:33]
	v_mfma_f32_16x16x128_f8f6f4 v[26:29], v[206:213], v[222:229], v[26:29]
	s_barrier
	v_mfma_f32_16x16x128_f8f6f4 v[34:37], v[206:213], v[214:221], v[34:37]
	v_mfma_f32_16x16x128_f8f6f4 v[38:41], v[198:205], v[214:221], v[38:41]
	s_setprio 0
	ds_read_b128 v[190:193], v187 offset:32768
	ds_read_b128 v[194:197], v187 offset:33792
	ds_read_b128 v[198:201], v187 offset:34816
	ds_read_b128 v[202:205], v187 offset:35840
	ds_read_b128 v[2:5], v187 offset:49152
	ds_read_b128 v[6:9], v187 offset:50176
	ds_read_b128 v[206:209], v187 offset:51200
	ds_read_b128 v[210:213], v187 offset:52224
	s_add_u32 s54, s54, 0x158000
	s_addc_u32 s55, s55, 0
	s_mov_b32 m0, s76
	v_lshl_add_u64 v[238:239], s[54:55], 0, v[154:155]
	ds_read_b128 v[214:217], v188 offset:32768
	ds_read_b128 v[218:221], v188 offset:33792
	ds_read_b128 v[222:225], v188 offset:34816
	ds_read_b128 v[226:229], v188 offset:35840
	ds_read_b128 v[230:233], v188 offset:36864
	ds_read_b128 v[234:237], v188 offset:37888
	ds_read_b128 v[242:245], v188 offset:38912
	ds_read_b128 v[246:249], v188 offset:39936
	global_load_lds_dwordx4 v[238:239], off
	v_lshl_add_u64 v[238:239], s[54:55], 0, v[158:159]
	s_mov_b32 m0, s77
	s_nop 0
	global_load_lds_dwordx4 v[238:239], off
	s_waitcnt vmcnt(8)
	s_waitcnt lgkmcnt(0)
	s_setprio 1
	s_barrier
	v_mfma_f32_16x16x128_f8f6f4 v[134:137], v[190:197], v[214:221], v[134:137]
	v_mfma_f32_16x16x128_f8f6f4 v[130:133], v[198:205], v[214:221], v[130:133]
	v_mfma_f32_16x16x128_f8f6f4 v[122:125], v[198:205], v[222:229], v[122:125]
	v_mfma_f32_16x16x128_f8f6f4 v[126:129], v[190:197], v[222:229], v[126:129]
	v_mfma_f32_16x16x128_f8f6f4 v[118:121], v[190:197], v[230:237], v[118:121]
	v_mfma_f32_16x16x128_f8f6f4 v[114:117], v[198:205], v[230:237], v[114:117]
	v_mfma_f32_16x16x128_f8f6f4 v[106:109], v[198:205], v[242:249], v[106:109]
	v_mfma_f32_16x16x128_f8f6f4 v[110:113], v[190:197], v[242:249], v[110:113]
	s_setprio 0
	s_setprio 1
	v_mfma_f32_16x16x128_f8f6f4 v[78:81], v[2:9], v[242:249], v[78:81]
	v_mfma_f32_16x16x128_f8f6f4 v[74:77], v[206:213], v[242:249], v[74:77]
	v_mfma_f32_16x16x128_f8f6f4 v[82:85], v[206:213], v[230:237], v[82:85]
	v_mfma_f32_16x16x128_f8f6f4 v[86:89], v[2:9], v[230:237], v[86:89]
	v_mfma_f32_16x16x128_f8f6f4 v[94:97], v[2:9], v[222:229], v[94:97]
	v_mfma_f32_16x16x128_f8f6f4 v[90:93], v[206:213], v[222:229], v[90:93]
	s_barrier
	v_mfma_f32_16x16x128_f8f6f4 v[98:101], v[206:213], v[214:221], v[98:101]
	v_mfma_f32_16x16x128_f8f6f4 v[102:105], v[2:9], v[214:221], v[102:105]
	s_setprio 0
	s_mov_b32 m0, s83
	v_lshl_add_u64 v[176:177], v[176:177], 0, s[26:27]
	s_add_u32 s50, s50, 0x158080
	ds_read_b128 v[214:217], v188 offset:49152
	ds_read_b128 v[218:221], v188 offset:50176
	ds_read_b128 v[222:225], v188 offset:51200
	ds_read_b128 v[226:229], v188 offset:52224
	ds_read_b128 v[230:233], v188 offset:53248
	ds_read_b128 v[234:237], v188 offset:54272
	ds_read_b128 v[242:245], v188 offset:55296
	ds_read_b128 v[246:249], v188 offset:56320
	global_load_lds_dwordx4 v[176:177], off
	v_lshl_add_u64 v[176:177], v[178:179], 0, s[26:27]
	s_mov_b32 m0, s84
	s_addc_u32 s51, s51, 0
	global_load_lds_dwordx4 v[176:177], off
	v_lshl_add_u64 v[176:177], s[50:51], 0, v[156:157]
	s_mov_b32 m0, s87
	s_nop 0
	global_load_lds_dwordx4 v[176:177], off
	v_lshl_add_u64 v[176:177], s[50:51], 0, v[160:161]
	s_mov_b32 m0, s88
	s_nop 0
	global_load_lds_dwordx4 v[176:177], off
	v_lshl_add_u64 v[176:177], v[180:181], 0, s[26:27]
	s_mov_b32 m0, s85
	s_nop 0
	global_load_lds_dwordx4 v[176:177], off
	v_lshl_add_u64 v[176:177], v[182:183], 0, s[26:27]
	s_mov_b32 m0, s86
	s_nop 0
	global_load_lds_dwordx4 v[176:177], off
	s_waitcnt vmcnt(8)
	s_waitcnt lgkmcnt(0)
	s_setprio 1
	s_barrier
	v_mfma_f32_16x16x128_f8f6f4 v[70:73], v[190:197], v[214:221], v[70:73]
	v_mfma_f32_16x16x128_f8f6f4 v[66:69], v[198:205], v[214:221], v[66:69]
	v_mfma_f32_16x16x128_f8f6f4 v[58:61], v[198:205], v[222:229], v[58:61]
	v_mfma_f32_16x16x128_f8f6f4 v[62:65], v[190:197], v[222:229], v[62:65]
	v_mfma_f32_16x16x128_f8f6f4 v[54:57], v[190:197], v[230:237], v[54:57]
	v_mfma_f32_16x16x128_f8f6f4 v[50:53], v[198:205], v[230:237], v[50:53]
	v_mfma_f32_16x16x128_f8f6f4 v[42:45], v[198:205], v[242:249], v[42:45]
	v_mfma_f32_16x16x128_f8f6f4 v[46:49], v[190:197], v[242:249], v[46:49]
	s_setprio 0
	s_setprio 1
	v_mfma_f32_16x16x128_f8f6f4 v[14:17], v[2:9], v[242:249], v[14:17]
	v_mfma_f32_16x16x128_f8f6f4 v[10:13], v[206:213], v[242:249], v[10:13]
	v_mfma_f32_16x16x128_f8f6f4 v[18:21], v[206:213], v[230:237], v[18:21]
	v_mfma_f32_16x16x128_f8f6f4 v[22:25], v[2:9], v[230:237], v[22:25]
	v_mfma_f32_16x16x128_f8f6f4 v[30:33], v[2:9], v[222:229], v[30:33]
	v_mfma_f32_16x16x128_f8f6f4 v[26:29], v[206:213], v[222:229], v[26:29]
	s_barrier
	v_mfma_f32_16x16x128_f8f6f4 v[34:37], v[206:213], v[214:221], v[34:37]
	v_mfma_f32_16x16x128_f8f6f4 v[38:41], v[2:9], v[214:221], v[38:41]
	s_setprio 0
	s_add_i32 s50, s72, 2
	s_add_u32 s52, s52, 0x100
	s_addc_u32 s53, s53, 0
	s_add_u32 s8, s8, 0x100
	s_addc_u32 s9, s9, 0
	s_cmp_ge_i32 s72, s95
	s_cbranch_scc1 .LBB0_287
	s_mov_b32 s72, s50
	s_cmp_eq_u32 s95, s72
	s_cselect_b64 s[50:51], -1, 0
	s_cmp_lg_u32 s95, s72
	s_cbranch_scc0 .LBB0_284
	s_branch .LBB0_285

.LBB0_437:
	s_ashr_i32 s47, s46, 31
	ds_read_b128 v[18:21], v200
	ds_read_b128 v[22:25], v200 offset:1024
	ds_read_b128 v[26:29], v200 offset:2048
	ds_read_b128 v[30:33], v200 offset:3072
	ds_read_b128 v[2:5], v200 offset:16384
	ds_read_b128 v[6:9], v200 offset:17408
	ds_read_b128 v[10:13], v200 offset:18432
	ds_read_b128 v[14:17], v200 offset:19456
	s_lshl_b64 s[8:9], s[46:47], 20
	s_add_u32 s48, s12, s8
	s_addc_u32 s49, s13, s9
	s_and_b64 s[8:9], s[2:3], exec
	s_cselect_b32 s47, s49, s73
	s_cselect_b32 s71, s48, s72
	s_ashr_i32 s45, s44, 31
	s_lshl_b64 s[8:9], s[44:45], 20
	s_add_u32 s50, s39, s8
	s_addc_u32 s51, s76, s9
	s_and_b64 s[8:9], s[2:3], exec
	s_cselect_b32 s45, s51, s55
	s_cselect_b32 s94, s50, s54
	s_add_u32 s8, s72, 0x80080
	s_addc_u32 s9, s73, 0
	s_mov_b32 m0, s33
	v_lshl_add_u64 v[226:227], s[8:9], 0, v[162:163]
	ds_read_b128 v[180:183], v201
	ds_read_b128 v[184:187], v201 offset:1024
	ds_read_b128 v[202:205], v201 offset:2048
	ds_read_b128 v[206:209], v201 offset:3072
	ds_read_b128 v[210:213], v201 offset:4096
	ds_read_b128 v[214:217], v201 offset:5120
	ds_read_b128 v[218:221], v201 offset:6144
	ds_read_b128 v[222:225], v201 offset:7168
	global_load_lds_dwordx4 v[226:227], off
	v_lshl_add_u64 v[226:227], s[8:9], 0, v[166:167]
	s_mov_b32 m0, s93
	s_nop 0
	global_load_lds_dwordx4 v[226:227], off
	s_waitcnt vmcnt(8)
	s_waitcnt lgkmcnt(0)
	s_setprio 1
	s_barrier
	v_mfma_f32_16x16x128_f8f6f4 v[158:161], v[18:25], v[180:187], 0
	v_mfma_f32_16x16x128_f8f6f4 v[154:157], v[26:33], v[180:187], 0
	v_mfma_f32_16x16x128_f8f6f4 v[146:149], v[26:33], v[202:209], 0
	v_mfma_f32_16x16x128_f8f6f4 v[150:153], v[18:25], v[202:209], 0
	v_mfma_f32_16x16x128_f8f6f4 v[142:145], v[18:25], v[210:217], 0
	v_mfma_f32_16x16x128_f8f6f4 v[138:141], v[26:33], v[210:217], 0
	v_mfma_f32_16x16x128_f8f6f4 v[130:133], v[26:33], v[218:225], 0
	v_mfma_f32_16x16x128_f8f6f4 v[134:137], v[18:25], v[218:225], 0
	s_setprio 0
	s_setprio 1
	v_mfma_f32_16x16x128_f8f6f4 v[102:105], v[2:9], v[218:225], 0
	v_mfma_f32_16x16x128_f8f6f4 v[98:101], v[10:17], v[218:225], 0
	v_mfma_f32_16x16x128_f8f6f4 v[106:109], v[10:17], v[210:217], 0
	v_mfma_f32_16x16x128_f8f6f4 v[110:113], v[2:9], v[210:217], 0
	v_mfma_f32_16x16x128_f8f6f4 v[118:121], v[2:9], v[202:209], 0
	v_mfma_f32_16x16x128_f8f6f4 v[114:117], v[10:17], v[202:209], 0
	s_barrier
	v_mfma_f32_16x16x128_f8f6f4 v[122:125], v[10:17], v[180:187], 0
	v_mfma_f32_16x16x128_f8f6f4 v[126:129], v[2:9], v[180:187], 0
	s_setprio 0
	v_lshl_add_u64 v[180:181], s[54:55], 0, v[164:165]
	s_mov_b32 m0, s78
	v_lshl_add_u64 v[182:183], v[180:181], 0, s[26:27]
	ds_read_b128 v[202:205], v201 offset:16384
	ds_read_b128 v[206:209], v201 offset:17408
	ds_read_b128 v[210:213], v201 offset:18432
	ds_read_b128 v[214:217], v201 offset:19456
	ds_read_b128 v[218:221], v201 offset:20480
	ds_read_b128 v[222:225], v201 offset:21504
	ds_read_b128 v[226:229], v201 offset:22528
	ds_read_b128 v[230:233], v201 offset:23552
	global_load_lds_dwordx4 v[182:183], off
	v_lshl_add_u64 v[182:183], s[54:55], 0, v[168:169]
	s_add_u32 s8, s54, 0x80100
	v_lshl_add_u64 v[184:185], v[182:183], 0, s[26:27]
	s_mov_b32 m0, s79
	s_addc_u32 s9, s55, 0
	global_load_lds_dwordx4 v[184:185], off
	v_lshl_add_u64 v[184:185], s[8:9], 0, v[164:165]
	s_mov_b32 m0, s80
	s_nop 0
	global_load_lds_dwordx4 v[184:185], off
	v_lshl_add_u64 v[184:185], s[8:9], 0, v[168:169]
	s_mov_b32 m0, s81
	s_nop 0
	global_load_lds_dwordx4 v[184:185], off
	v_lshl_add_u64 v[184:185], s[72:73], 0, v[162:163]
	v_lshl_add_u64 v[186:187], v[184:185], 0, s[26:27]
	s_mov_b32 m0, s53
	s_nop 0
	global_load_lds_dwordx4 v[186:187], off
	v_lshl_add_u64 v[186:187], s[72:73], 0, v[166:167]
	v_lshl_add_u64 v[234:235], v[186:187], 0, s[26:27]
	s_mov_b32 m0, s82
	s_nop 0
	global_load_lds_dwordx4 v[234:235], off
	s_waitcnt vmcnt(8)
	s_waitcnt lgkmcnt(0)
	s_setprio 1
	s_barrier
	v_mfma_f32_16x16x128_f8f6f4 v[94:97], v[18:25], v[202:209], 0
	v_mfma_f32_16x16x128_f8f6f4 v[90:93], v[26:33], v[202:209], 0
	v_mfma_f32_16x16x128_f8f6f4 v[82:85], v[26:33], v[210:217], 0
	v_mfma_f32_16x16x128_f8f6f4 v[86:89], v[18:25], v[210:217], 0
	v_mfma_f32_16x16x128_f8f6f4 v[78:81], v[18:25], v[218:225], 0
	v_mfma_f32_16x16x128_f8f6f4 v[74:77], v[26:33], v[218:225], 0
	v_mfma_f32_16x16x128_f8f6f4 v[66:69], v[26:33], v[226:233], 0
	v_mfma_f32_16x16x128_f8f6f4 v[70:73], v[18:25], v[226:233], 0
	s_setprio 0
	s_setprio 1
	v_mfma_f32_16x16x128_f8f6f4 v[38:41], v[2:9], v[226:233], 0
	v_mfma_f32_16x16x128_f8f6f4 v[34:37], v[10:17], v[226:233], 0
	v_mfma_f32_16x16x128_f8f6f4 v[42:45], v[10:17], v[218:225], 0
	v_mfma_f32_16x16x128_f8f6f4 v[46:49], v[2:9], v[218:225], 0
	v_mfma_f32_16x16x128_f8f6f4 v[54:57], v[2:9], v[210:217], 0
	v_mfma_f32_16x16x128_f8f6f4 v[50:53], v[10:17], v[210:217], 0
	s_barrier
	v_mfma_f32_16x16x128_f8f6f4 v[58:61], v[10:17], v[202:209], 0
	v_mfma_f32_16x16x128_f8f6f4 v[62:65], v[2:9], v[202:209], 0
	s_setprio 0
	ds_read_b128 v[18:21], v200 offset:32768
	ds_read_b128 v[22:25], v200 offset:33792
	ds_read_b128 v[26:29], v200 offset:34816
	ds_read_b128 v[30:33], v200 offset:35840
	ds_read_b128 v[2:5], v200 offset:49152
	ds_read_b128 v[6:9], v200 offset:50176
	ds_read_b128 v[10:13], v200 offset:51200
	ds_read_b128 v[14:17], v200 offset:52224
	s_add_u32 s8, s72, 0x80100
	s_addc_u32 s9, s73, 0
	s_mov_b32 m0, s83
	v_lshl_add_u64 v[234:235], s[8:9], 0, v[162:163]
	ds_read_b128 v[202:205], v201 offset:32768
	ds_read_b128 v[206:209], v201 offset:33792
	ds_read_b128 v[210:213], v201 offset:34816
	ds_read_b128 v[214:217], v201 offset:35840
	ds_read_b128 v[218:221], v201 offset:36864
	ds_read_b128 v[222:225], v201 offset:37888
	ds_read_b128 v[226:229], v201 offset:38912
	ds_read_b128 v[230:233], v201 offset:39936
	global_load_lds_dwordx4 v[234:235], off
	v_lshl_add_u64 v[234:235], s[8:9], 0, v[166:167]
	s_mov_b32 m0, s84
	s_nop 0
	global_load_lds_dwordx4 v[234:235], off
	s_waitcnt vmcnt(8)
	s_waitcnt lgkmcnt(0)
	s_setprio 1
	s_barrier
	v_mfma_f32_16x16x128_f8f6f4 v[158:161], v[18:25], v[202:209], v[158:161]
	v_mfma_f32_16x16x128_f8f6f4 v[154:157], v[26:33], v[202:209], v[154:157]
	v_mfma_f32_16x16x128_f8f6f4 v[146:149], v[26:33], v[210:217], v[146:149]
	v_mfma_f32_16x16x128_f8f6f4 v[150:153], v[18:25], v[210:217], v[150:153]
	v_mfma_f32_16x16x128_f8f6f4 v[142:145], v[18:25], v[218:225], v[142:145]
	v_mfma_f32_16x16x128_f8f6f4 v[138:141], v[26:33], v[218:225], v[138:141]
	v_mfma_f32_16x16x128_f8f6f4 v[130:133], v[26:33], v[226:233], v[130:133]
	v_mfma_f32_16x16x128_f8f6f4 v[134:137], v[18:25], v[226:233], v[134:137]
	s_setprio 0
	s_setprio 1
	v_mfma_f32_16x16x128_f8f6f4 v[102:105], v[2:9], v[226:233], v[102:105]
	v_mfma_f32_16x16x128_f8f6f4 v[98:101], v[10:17], v[226:233], v[98:101]
	v_mfma_f32_16x16x128_f8f6f4 v[106:109], v[10:17], v[218:225], v[106:109]
	v_mfma_f32_16x16x128_f8f6f4 v[110:113], v[2:9], v[218:225], v[110:113]
	v_mfma_f32_16x16x128_f8f6f4 v[118:121], v[2:9], v[210:217], v[118:121]
	v_mfma_f32_16x16x128_f8f6f4 v[114:117], v[10:17], v[210:217], v[114:117]
	s_barrier
	v_mfma_f32_16x16x128_f8f6f4 v[122:125], v[10:17], v[202:209], v[122:125]
	v_mfma_f32_16x16x128_f8f6f4 v[126:129], v[2:9], v[202:209], v[126:129]
	s_setprio 0
	s_mov_b32 m0, s87
	v_lshl_add_u64 v[180:181], v[180:181], 0, s[36:37]
	s_add_u32 s8, s54, 0x80180
	ds_read_b128 v[202:205], v201 offset:49152
	ds_read_b128 v[206:209], v201 offset:50176
	ds_read_b128 v[210:213], v201 offset:51200
	ds_read_b128 v[214:217], v201 offset:52224
	ds_read_b128 v[218:221], v201 offset:53248
	ds_read_b128 v[222:225], v201 offset:54272
	ds_read_b128 v[226:229], v201 offset:55296
	ds_read_b128 v[230:233], v201 offset:56320
	global_load_lds_dwordx4 v[180:181], off
	v_lshl_add_u64 v[180:181], v[182:183], 0, s[36:37]
	s_mov_b32 m0, s88
	s_addc_u32 s9, s55, 0
	global_load_lds_dwordx4 v[180:181], off
	v_lshl_add_u64 v[180:181], s[8:9], 0, v[164:165]
	s_mov_b32 m0, s91
	s_nop 0
	global_load_lds_dwordx4 v[180:181], off
	v_lshl_add_u64 v[180:181], s[8:9], 0, v[168:169]
	s_mov_b32 m0, s92
	s_nop 0
	global_load_lds_dwordx4 v[180:181], off
	v_lshl_add_u64 v[180:181], v[184:185], 0, s[36:37]
	s_mov_b32 m0, s89
	s_nop 0
	global_load_lds_dwordx4 v[180:181], off
	v_lshl_add_u64 v[180:181], v[186:187], 0, s[36:37]
	s_mov_b32 m0, s90
	s_nop 0
	global_load_lds_dwordx4 v[180:181], off
	s_waitcnt vmcnt(8)
	s_waitcnt lgkmcnt(0)
	s_setprio 1
	s_barrier
	v_mfma_f32_16x16x128_f8f6f4 v[94:97], v[18:25], v[202:209], v[94:97]
	v_mfma_f32_16x16x128_f8f6f4 v[90:93], v[26:33], v[202:209], v[90:93]
	v_mfma_f32_16x16x128_f8f6f4 v[82:85], v[26:33], v[210:217], v[82:85]
	v_mfma_f32_16x16x128_f8f6f4 v[86:89], v[18:25], v[210:217], v[86:89]
	v_mfma_f32_16x16x128_f8f6f4 v[78:81], v[18:25], v[218:225], v[78:81]
	v_mfma_f32_16x16x128_f8f6f4 v[74:77], v[26:33], v[218:225], v[74:77]
	v_mfma_f32_16x16x128_f8f6f4 v[66:69], v[26:33], v[226:233], v[66:69]
	v_mfma_f32_16x16x128_f8f6f4 v[70:73], v[18:25], v[226:233], v[70:73]
	s_setprio 0
	s_setprio 1
	v_mfma_f32_16x16x128_f8f6f4 v[38:41], v[2:9], v[226:233], v[38:41]
	v_mfma_f32_16x16x128_f8f6f4 v[34:37], v[10:17], v[226:233], v[34:37]
	v_mfma_f32_16x16x128_f8f6f4 v[42:45], v[10:17], v[218:225], v[42:45]
	v_mfma_f32_16x16x128_f8f6f4 v[46:49], v[2:9], v[218:225], v[46:49]
	v_mfma_f32_16x16x128_f8f6f4 v[54:57], v[2:9], v[210:217], v[54:57]
	v_mfma_f32_16x16x128_f8f6f4 v[50:53], v[10:17], v[210:217], v[50:53]
	s_barrier
	v_mfma_f32_16x16x128_f8f6f4 v[58:61], v[10:17], v[202:209], v[58:61]
	v_mfma_f32_16x16x128_f8f6f4 v[62:65], v[2:9], v[202:209], v[62:65]
	s_setprio 0
	s_add_u32 s72, s72, 0x80180
	s_addc_u32 s73, s73, 0
	s_add_u32 s8, s54, 0x200
	s_addc_u32 s9, s55, 0
	s_mov_b32 s62, 0
.LBB0_438:
	ds_read_b128 v[2:5], v200
	ds_read_b128 v[6:9], v200 offset:1024
	ds_read_b128 v[18:21], v200 offset:2048
	ds_read_b128 v[22:25], v200 offset:3072
	ds_read_b128 v[26:29], v200 offset:16384
	ds_read_b128 v[30:33], v200 offset:17408
	ds_read_b128 v[180:183], v200 offset:18432
	ds_read_b128 v[184:187], v200 offset:19456
	s_add_u32 s54, s72, 0xfff80080
	s_addc_u32 s55, s73, -1
	s_cmp_eq_u32 s62, 28
	s_cselect_b32 s75, s47, s55
	s_cselect_b32 s74, s71, s54
	s_cselect_b32 s55, s45, s9
	s_cselect_b32 s54, s94, s8
	s_mov_b32 m0, s33
	v_lshl_add_u64 v[226:227], s[72:73], 0, v[170:171]
	ds_read_b128 v[10:13], v201
	ds_read_b128 v[14:17], v201 offset:1024
	ds_read_b128 v[202:205], v201 offset:2048
	ds_read_b128 v[206:209], v201 offset:3072
	ds_read_b128 v[210:213], v201 offset:4096
	ds_read_b128 v[214:217], v201 offset:5120
	ds_read_b128 v[218:221], v201 offset:6144
	ds_read_b128 v[222:225], v201 offset:7168
	global_load_lds_dwordx4 v[226:227], off
	v_lshl_add_u64 v[226:227], s[72:73], 0, v[172:173]
	s_mov_b32 m0, s93
	s_nop 0
	global_load_lds_dwordx4 v[226:227], off
	s_waitcnt vmcnt(8)
	s_waitcnt lgkmcnt(0)
	s_setprio 1
	s_barrier
	v_mfma_f32_16x16x128_f8f6f4 v[158:161], v[2:9], v[10:17], v[158:161]
	v_mfma_f32_16x16x128_f8f6f4 v[154:157], v[18:25], v[10:17], v[154:157]
	v_mfma_f32_16x16x128_f8f6f4 v[146:149], v[18:25], v[202:209], v[146:149]
	v_mfma_f32_16x16x128_f8f6f4 v[150:153], v[2:9], v[202:209], v[150:153]
	v_mfma_f32_16x16x128_f8f6f4 v[142:145], v[2:9], v[210:217], v[142:145]
	v_mfma_f32_16x16x128_f8f6f4 v[138:141], v[18:25], v[210:217], v[138:141]
	v_mfma_f32_16x16x128_f8f6f4 v[130:133], v[18:25], v[218:225], v[130:133]
	v_mfma_f32_16x16x128_f8f6f4 v[134:137], v[2:9], v[218:225], v[134:137]
	s_setprio 0
	s_setprio 1
	v_mfma_f32_16x16x128_f8f6f4 v[102:105], v[26:33], v[218:225], v[102:105]
	v_mfma_f32_16x16x128_f8f6f4 v[98:101], v[180:187], v[218:225], v[98:101]
	v_mfma_f32_16x16x128_f8f6f4 v[106:109], v[180:187], v[210:217], v[106:109]
	v_mfma_f32_16x16x128_f8f6f4 v[110:113], v[26:33], v[210:217], v[110:113]
	v_mfma_f32_16x16x128_f8f6f4 v[118:121], v[26:33], v[202:209], v[118:121]
	v_mfma_f32_16x16x128_f8f6f4 v[114:117], v[180:187], v[202:209], v[114:117]
	s_barrier
	v_mfma_f32_16x16x128_f8f6f4 v[122:125], v[180:187], v[10:17], v[122:125]
	v_mfma_f32_16x16x128_f8f6f4 v[126:129], v[26:33], v[10:17], v[126:129]
	s_setprio 0
	s_mov_b32 m0, s78
	v_lshl_add_u64 v[10:11], s[54:55], 0, v[164:165]
	s_add_u32 s96, s54, 0x80000
	ds_read_b128 v[202:205], v201 offset:16384
	ds_read_b128 v[206:209], v201 offset:17408
	ds_read_b128 v[210:213], v201 offset:18432
	ds_read_b128 v[214:217], v201 offset:19456
	ds_read_b128 v[218:221], v201 offset:20480
	ds_read_b128 v[222:225], v201 offset:21504
	ds_read_b128 v[226:229], v201 offset:22528
	ds_read_b128 v[230:233], v201 offset:23552
	global_load_lds_dwordx4 v[10:11], off
	v_lshl_add_u64 v[12:13], s[54:55], 0, v[168:169]
	s_mov_b32 m0, s79
	s_addc_u32 s97, s55, 0
	global_load_lds_dwordx4 v[12:13], off
	v_lshl_add_u64 v[14:15], s[96:97], 0, v[164:165]
	s_mov_b32 m0, s80
	v_lshl_add_u64 v[16:17], s[74:75], 0, v[166:167]
	global_load_lds_dwordx4 v[14:15], off
	v_lshl_add_u64 v[14:15], s[96:97], 0, v[168:169]
	s_mov_b32 m0, s81
	s_nop 0
	global_load_lds_dwordx4 v[14:15], off
	v_lshl_add_u64 v[14:15], s[74:75], 0, v[162:163]
	s_mov_b32 m0, s53
	s_nop 0
	global_load_lds_dwordx4 v[14:15], off
	s_mov_b32 m0, s82
	s_nop 0
	global_load_lds_dwordx4 v[16:17], off
	s_waitcnt vmcnt(8)
	s_waitcnt lgkmcnt(0)
	s_setprio 1
	s_barrier
	v_mfma_f32_16x16x128_f8f6f4 v[94:97], v[2:9], v[202:209], v[94:97]
	v_mfma_f32_16x16x128_f8f6f4 v[90:93], v[18:25], v[202:209], v[90:93]
	v_mfma_f32_16x16x128_f8f6f4 v[82:85], v[18:25], v[210:217], v[82:85]
	v_mfma_f32_16x16x128_f8f6f4 v[86:89], v[2:9], v[210:217], v[86:89]
	v_mfma_f32_16x16x128_f8f6f4 v[78:81], v[2:9], v[218:225], v[78:81]
	v_mfma_f32_16x16x128_f8f6f4 v[74:77], v[18:25], v[218:225], v[74:77]
	v_mfma_f32_16x16x128_f8f6f4 v[66:69], v[18:25], v[226:233], v[66:69]
	v_mfma_f32_16x16x128_f8f6f4 v[70:73], v[2:9], v[226:233], v[70:73]
	s_setprio 0
	s_setprio 1
	v_mfma_f32_16x16x128_f8f6f4 v[38:41], v[26:33], v[226:233], v[38:41]
	v_mfma_f32_16x16x128_f8f6f4 v[34:37], v[180:187], v[226:233], v[34:37]
	v_mfma_f32_16x16x128_f8f6f4 v[42:45], v[180:187], v[218:225], v[42:45]
	v_mfma_f32_16x16x128_f8f6f4 v[46:49], v[26:33], v[218:225], v[46:49]
	v_mfma_f32_16x16x128_f8f6f4 v[54:57], v[26:33], v[210:217], v[54:57]
	v_mfma_f32_16x16x128_f8f6f4 v[50:53], v[180:187], v[210:217], v[50:53]
	s_barrier
	v_mfma_f32_16x16x128_f8f6f4 v[58:61], v[180:187], v[202:209], v[58:61]
	v_mfma_f32_16x16x128_f8f6f4 v[62:65], v[26:33], v[202:209], v[62:65]
	s_setprio 0
	ds_read_b128 v[18:21], v200 offset:32768
	ds_read_b128 v[22:25], v200 offset:33792
	ds_read_b128 v[26:29], v200 offset:34816
	ds_read_b128 v[30:33], v200 offset:35840
	ds_read_b128 v[2:5], v200 offset:49152
	ds_read_b128 v[6:9], v200 offset:50176
	ds_read_b128 v[180:183], v200 offset:51200
	ds_read_b128 v[184:187], v200 offset:52224
	s_add_u32 s74, s74, 0x80000
	s_addc_u32 s75, s75, 0
	s_mov_b32 m0, s83
	v_lshl_add_u64 v[234:235], s[74:75], 0, v[162:163]
	ds_read_b128 v[202:205], v201 offset:32768
	ds_read_b128 v[206:209], v201 offset:33792
	ds_read_b128 v[210:213], v201 offset:34816
	ds_read_b128 v[214:217], v201 offset:35840
	ds_read_b128 v[218:221], v201 offset:36864
	ds_read_b128 v[222:225], v201 offset:37888
	ds_read_b128 v[226:229], v201 offset:38912
	ds_read_b128 v[230:233], v201 offset:39936
	global_load_lds_dwordx4 v[234:235], off
	v_lshl_add_u64 v[234:235], s[74:75], 0, v[166:167]
	s_mov_b32 m0, s84
	s_nop 0
	global_load_lds_dwordx4 v[234:235], off
	s_waitcnt vmcnt(8)
	s_waitcnt lgkmcnt(0)
	s_setprio 1
	s_barrier
	v_mfma_f32_16x16x128_f8f6f4 v[158:161], v[18:25], v[202:209], v[158:161]
	v_mfma_f32_16x16x128_f8f6f4 v[154:157], v[26:33], v[202:209], v[154:157]
	v_mfma_f32_16x16x128_f8f6f4 v[146:149], v[26:33], v[210:217], v[146:149]
	v_mfma_f32_16x16x128_f8f6f4 v[150:153], v[18:25], v[210:217], v[150:153]
	v_mfma_f32_16x16x128_f8f6f4 v[142:145], v[18:25], v[218:225], v[142:145]
	v_mfma_f32_16x16x128_f8f6f4 v[138:141], v[26:33], v[218:225], v[138:141]
	v_mfma_f32_16x16x128_f8f6f4 v[130:133], v[26:33], v[226:233], v[130:133]
	v_mfma_f32_16x16x128_f8f6f4 v[134:137], v[18:25], v[226:233], v[134:137]
	s_setprio 0
	s_setprio 1
	v_mfma_f32_16x16x128_f8f6f4 v[102:105], v[2:9], v[226:233], v[102:105]
	v_mfma_f32_16x16x128_f8f6f4 v[98:101], v[180:187], v[226:233], v[98:101]
	v_mfma_f32_16x16x128_f8f6f4 v[106:109], v[180:187], v[218:225], v[106:109]
	v_mfma_f32_16x16x128_f8f6f4 v[110:113], v[2:9], v[218:225], v[110:113]
	v_mfma_f32_16x16x128_f8f6f4 v[118:121], v[2:9], v[210:217], v[118:121]
	v_mfma_f32_16x16x128_f8f6f4 v[114:117], v[180:187], v[210:217], v[114:117]
	s_barrier
	v_mfma_f32_16x16x128_f8f6f4 v[122:125], v[180:187], v[202:209], v[122:125]
	v_mfma_f32_16x16x128_f8f6f4 v[126:129], v[2:9], v[202:209], v[126:129]
	s_setprio 0
	s_mov_b32 m0, s87
	v_lshl_add_u64 v[10:11], v[10:11], 0, s[4:5]
	s_add_u32 s54, s54, 0x80080
	ds_read_b128 v[202:205], v201 offset:49152
	ds_read_b128 v[206:209], v201 offset:50176
	ds_read_b128 v[210:213], v201 offset:51200
	ds_read_b128 v[214:217], v201 offset:52224
	ds_read_b128 v[218:221], v201 offset:53248
	ds_read_b128 v[222:225], v201 offset:54272
	ds_read_b128 v[226:229], v201 offset:55296
	ds_read_b128 v[230:233], v201 offset:56320
	global_load_lds_dwordx4 v[10:11], off
	v_lshl_add_u64 v[10:11], v[12:13], 0, s[4:5]
	s_mov_b32 m0, s88
	s_addc_u32 s55, s55, 0
	global_load_lds_dwordx4 v[10:11], off
	v_lshl_add_u64 v[10:11], s[54:55], 0, v[164:165]
	s_mov_b32 m0, s91
	s_nop 0
	global_load_lds_dwordx4 v[10:11], off
	v_lshl_add_u64 v[10:11], s[54:55], 0, v[168:169]
	s_mov_b32 m0, s92
	s_nop 0
	global_load_lds_dwordx4 v[10:11], off
	v_lshl_add_u64 v[10:11], v[14:15], 0, s[4:5]
	s_mov_b32 m0, s89
	s_nop 0
	global_load_lds_dwordx4 v[10:11], off
	v_lshl_add_u64 v[10:11], v[16:17], 0, s[4:5]
	s_mov_b32 m0, s90
	s_nop 0
	global_load_lds_dwordx4 v[10:11], off
	s_waitcnt vmcnt(8)
	s_waitcnt lgkmcnt(0)
	s_setprio 1
	s_barrier
	v_mfma_f32_16x16x128_f8f6f4 v[94:97], v[18:25], v[202:209], v[94:97]
	v_mfma_f32_16x16x128_f8f6f4 v[90:93], v[26:33], v[202:209], v[90:93]
	v_mfma_f32_16x16x128_f8f6f4 v[82:85], v[26:33], v[210:217], v[82:85]
	v_mfma_f32_16x16x128_f8f6f4 v[86:89], v[18:25], v[210:217], v[86:89]
	v_mfma_f32_16x16x128_f8f6f4 v[78:81], v[18:25], v[218:225], v[78:81]
	v_mfma_f32_16x16x128_f8f6f4 v[74:77], v[26:33], v[218:225], v[74:77]
	v_mfma_f32_16x16x128_f8f6f4 v[66:69], v[26:33], v[226:233], v[66:69]
	v_mfma_f32_16x16x128_f8f6f4 v[70:73], v[18:25], v[226:233], v[70:73]
	s_setprio 0
	s_setprio 1
	v_mfma_f32_16x16x128_f8f6f4 v[38:41], v[2:9], v[226:233], v[38:41]
	v_mfma_f32_16x16x128_f8f6f4 v[34:37], v[180:187], v[226:233], v[34:37]
	v_mfma_f32_16x16x128_f8f6f4 v[42:45], v[180:187], v[218:225], v[42:45]
	v_mfma_f32_16x16x128_f8f6f4 v[46:49], v[2:9], v[218:225], v[46:49]
	v_mfma_f32_16x16x128_f8f6f4 v[54:57], v[2:9], v[210:217], v[54:57]
	v_mfma_f32_16x16x128_f8f6f4 v[50:53], v[180:187], v[210:217], v[50:53]
	s_barrier
	v_mfma_f32_16x16x128_f8f6f4 v[58:61], v[180:187], v[202:209], v[58:61]
	v_mfma_f32_16x16x128_f8f6f4 v[62:65], v[2:9], v[202:209], v[62:65]
	s_setprio 0
	s_add_i32 s62, s62, 2
	s_add_u32 s72, s72, 0x100
	s_addc_u32 s73, s73, 0
	s_add_u32 s8, s8, 0x100
	s_addc_u32 s9, s9, 0
	s_cmp_gt_u32 s62, 29
	s_cbranch_scc0 .LBB0_438
	s_and_b64 vcc, exec, s[6:7]
	s_cbranch_vccz .LBB0_441
	s_barrier

.LBB0_600:
	s_ashr_i32 s55, s54, 31
	ds_read_b128 v[18:21], v200
	ds_read_b128 v[22:25], v200 offset:1024
	ds_read_b128 v[26:29], v200 offset:2048
	ds_read_b128 v[30:33], v200 offset:3072
	ds_read_b128 v[2:5], v200 offset:16384
	ds_read_b128 v[6:9], v200 offset:17408
	ds_read_b128 v[10:13], v200 offset:18432
	ds_read_b128 v[14:17], v200 offset:19456
	s_lshl_b64 s[4:5], s[54:55], 18
	s_add_u32 s72, s38, s4
	s_addc_u32 s73, s39, s5
	s_and_b64 s[4:5], s[2:3], exec
	s_cselect_b32 s4, s73, s81
	s_cselect_b32 s5, s72, s80
	s_ashr_i32 s53, s52, 31
	s_lshl_b64 s[8:9], s[52:53], 18
	s_add_u32 s74, s94, s8
	v_readlane_b32 s8, v254, 6
	s_addc_u32 s75, s8, s9
	s_and_b64 s[8:9], s[2:3], exec
	s_cselect_b32 s53, s75, s79
	s_cselect_b32 s55, s74, s78
	s_add_u32 s8, s80, 0x20080
	s_addc_u32 s9, s81, 0
	s_mov_b32 m0, s96
	v_lshl_add_u64 v[226:227], s[8:9], 0, v[162:163]
	ds_read_b128 v[182:185], v201
	ds_read_b128 v[186:189], v201 offset:1024
	ds_read_b128 v[202:205], v201 offset:2048
	ds_read_b128 v[206:209], v201 offset:3072
	ds_read_b128 v[210:213], v201 offset:4096
	ds_read_b128 v[214:217], v201 offset:5120
	ds_read_b128 v[218:221], v201 offset:6144
	ds_read_b128 v[222:225], v201 offset:7168
	global_load_lds_dwordx4 v[226:227], off
	v_lshl_add_u64 v[226:227], s[8:9], 0, v[166:167]
	s_mov_b32 m0, s61
	s_nop 0
	global_load_lds_dwordx4 v[226:227], off
	s_waitcnt vmcnt(8)
	s_waitcnt lgkmcnt(0)
	s_setprio 1
	s_barrier
	v_mfma_f32_16x16x128_f8f6f4 v[158:161], v[18:25], v[182:189], 0
	v_mfma_f32_16x16x128_f8f6f4 v[154:157], v[26:33], v[182:189], 0
	v_mfma_f32_16x16x128_f8f6f4 v[146:149], v[26:33], v[202:209], 0
	v_mfma_f32_16x16x128_f8f6f4 v[150:153], v[18:25], v[202:209], 0
	v_mfma_f32_16x16x128_f8f6f4 v[142:145], v[18:25], v[210:217], 0
	v_mfma_f32_16x16x128_f8f6f4 v[138:141], v[26:33], v[210:217], 0
	v_mfma_f32_16x16x128_f8f6f4 v[130:133], v[26:33], v[218:225], 0
	v_mfma_f32_16x16x128_f8f6f4 v[134:137], v[18:25], v[218:225], 0
	s_setprio 0
	s_setprio 1
	v_mfma_f32_16x16x128_f8f6f4 v[102:105], v[2:9], v[218:225], 0
	v_mfma_f32_16x16x128_f8f6f4 v[98:101], v[10:17], v[218:225], 0
	v_mfma_f32_16x16x128_f8f6f4 v[106:109], v[10:17], v[210:217], 0
	v_mfma_f32_16x16x128_f8f6f4 v[110:113], v[2:9], v[210:217], 0
	v_mfma_f32_16x16x128_f8f6f4 v[118:121], v[2:9], v[202:209], 0
	v_mfma_f32_16x16x128_f8f6f4 v[114:117], v[10:17], v[202:209], 0
	s_barrier
	v_mfma_f32_16x16x128_f8f6f4 v[122:125], v[10:17], v[182:189], 0
	v_mfma_f32_16x16x128_f8f6f4 v[126:129], v[2:9], v[182:189], 0
	s_setprio 0
	v_lshl_add_u64 v[182:183], s[78:79], 0, v[164:165]
	s_mov_b32 m0, s68
	v_lshl_add_u64 v[184:185], v[182:183], 0, s[46:47]
	ds_read_b128 v[202:205], v201 offset:16384
	ds_read_b128 v[206:209], v201 offset:17408
	ds_read_b128 v[210:213], v201 offset:18432
	ds_read_b128 v[214:217], v201 offset:19456
	ds_read_b128 v[218:221], v201 offset:20480
	ds_read_b128 v[222:225], v201 offset:21504
	ds_read_b128 v[226:229], v201 offset:22528
	ds_read_b128 v[230:233], v201 offset:23552
	global_load_lds_dwordx4 v[184:185], off
	v_lshl_add_u64 v[184:185], s[78:79], 0, v[168:169]
	s_add_u32 s8, s78, 0x20100
	v_lshl_add_u64 v[186:187], v[184:185], 0, s[46:47]
	s_mov_b32 m0, s69
	s_addc_u32 s9, s79, 0
	global_load_lds_dwordx4 v[186:187], off
	v_lshl_add_u64 v[186:187], s[8:9], 0, v[164:165]
	s_mov_b32 m0, s77
	s_nop 0
	global_load_lds_dwordx4 v[186:187], off
	v_lshl_add_u64 v[186:187], s[8:9], 0, v[168:169]
	s_mov_b32 m0, s84
	s_nop 0
	global_load_lds_dwordx4 v[186:187], off
	v_lshl_add_u64 v[186:187], s[80:81], 0, v[162:163]
	v_lshl_add_u64 v[188:189], v[186:187], 0, s[46:47]
	s_mov_b32 m0, s33
	s_nop 0
	global_load_lds_dwordx4 v[188:189], off
	v_lshl_add_u64 v[188:189], s[80:81], 0, v[166:167]
	v_lshl_add_u64 v[234:235], v[188:189], 0, s[46:47]
	s_mov_b32 m0, s85
	s_nop 0
	global_load_lds_dwordx4 v[234:235], off
	s_waitcnt vmcnt(8)
	s_waitcnt lgkmcnt(0)
	s_setprio 1
	s_barrier
	v_mfma_f32_16x16x128_f8f6f4 v[94:97], v[18:25], v[202:209], 0
	v_mfma_f32_16x16x128_f8f6f4 v[90:93], v[26:33], v[202:209], 0
	v_mfma_f32_16x16x128_f8f6f4 v[82:85], v[26:33], v[210:217], 0
	v_mfma_f32_16x16x128_f8f6f4 v[86:89], v[18:25], v[210:217], 0
	v_mfma_f32_16x16x128_f8f6f4 v[78:81], v[18:25], v[218:225], 0
	v_mfma_f32_16x16x128_f8f6f4 v[74:77], v[26:33], v[218:225], 0
	v_mfma_f32_16x16x128_f8f6f4 v[66:69], v[26:33], v[226:233], 0
	v_mfma_f32_16x16x128_f8f6f4 v[70:73], v[18:25], v[226:233], 0
	s_setprio 0
	s_setprio 1
	v_mfma_f32_16x16x128_f8f6f4 v[38:41], v[2:9], v[226:233], 0
	v_mfma_f32_16x16x128_f8f6f4 v[34:37], v[10:17], v[226:233], 0
	v_mfma_f32_16x16x128_f8f6f4 v[42:45], v[10:17], v[218:225], 0
	v_mfma_f32_16x16x128_f8f6f4 v[46:49], v[2:9], v[218:225], 0
	v_mfma_f32_16x16x128_f8f6f4 v[54:57], v[2:9], v[210:217], 0
	v_mfma_f32_16x16x128_f8f6f4 v[50:53], v[10:17], v[210:217], 0
	s_barrier
	v_mfma_f32_16x16x128_f8f6f4 v[58:61], v[10:17], v[202:209], 0
	v_mfma_f32_16x16x128_f8f6f4 v[62:65], v[2:9], v[202:209], 0
	s_setprio 0
	ds_read_b128 v[18:21], v200 offset:32768
	ds_read_b128 v[22:25], v200 offset:33792
	ds_read_b128 v[26:29], v200 offset:34816
	ds_read_b128 v[30:33], v200 offset:35840
	ds_read_b128 v[2:5], v200 offset:49152
	ds_read_b128 v[6:9], v200 offset:50176
	ds_read_b128 v[10:13], v200 offset:51200
	ds_read_b128 v[14:17], v200 offset:52224
	s_add_u32 s8, s80, 0x20100
	s_addc_u32 s9, s81, 0
	s_mov_b32 m0, s86
	v_lshl_add_u64 v[234:235], s[8:9], 0, v[162:163]
	ds_read_b128 v[202:205], v201 offset:32768
	ds_read_b128 v[206:209], v201 offset:33792
	ds_read_b128 v[210:213], v201 offset:34816
	ds_read_b128 v[214:217], v201 offset:35840
	ds_read_b128 v[218:221], v201 offset:36864
	ds_read_b128 v[222:225], v201 offset:37888
	ds_read_b128 v[226:229], v201 offset:38912
	ds_read_b128 v[230:233], v201 offset:39936
	global_load_lds_dwordx4 v[234:235], off
	v_lshl_add_u64 v[234:235], s[8:9], 0, v[166:167]
	s_mov_b32 m0, s87
	s_nop 0
	global_load_lds_dwordx4 v[234:235], off
	s_waitcnt vmcnt(8)
	s_waitcnt lgkmcnt(0)
	s_setprio 1
	s_barrier
	v_mfma_f32_16x16x128_f8f6f4 v[158:161], v[18:25], v[202:209], v[158:161]
	v_mfma_f32_16x16x128_f8f6f4 v[154:157], v[26:33], v[202:209], v[154:157]
	v_mfma_f32_16x16x128_f8f6f4 v[146:149], v[26:33], v[210:217], v[146:149]
	v_mfma_f32_16x16x128_f8f6f4 v[150:153], v[18:25], v[210:217], v[150:153]
	v_mfma_f32_16x16x128_f8f6f4 v[142:145], v[18:25], v[218:225], v[142:145]
	v_mfma_f32_16x16x128_f8f6f4 v[138:141], v[26:33], v[218:225], v[138:141]
	v_mfma_f32_16x16x128_f8f6f4 v[130:133], v[26:33], v[226:233], v[130:133]
	v_mfma_f32_16x16x128_f8f6f4 v[134:137], v[18:25], v[226:233], v[134:137]
	s_setprio 0
	s_setprio 1
	v_mfma_f32_16x16x128_f8f6f4 v[102:105], v[2:9], v[226:233], v[102:105]
	v_mfma_f32_16x16x128_f8f6f4 v[98:101], v[10:17], v[226:233], v[98:101]
	v_mfma_f32_16x16x128_f8f6f4 v[106:109], v[10:17], v[218:225], v[106:109]
	v_mfma_f32_16x16x128_f8f6f4 v[110:113], v[2:9], v[218:225], v[110:113]
	v_mfma_f32_16x16x128_f8f6f4 v[118:121], v[2:9], v[210:217], v[118:121]
	v_mfma_f32_16x16x128_f8f6f4 v[114:117], v[10:17], v[210:217], v[114:117]
	s_barrier
	v_mfma_f32_16x16x128_f8f6f4 v[122:125], v[10:17], v[202:209], v[122:125]
	v_mfma_f32_16x16x128_f8f6f4 v[126:129], v[2:9], v[202:209], v[126:129]
	s_setprio 0
	s_mov_b32 m0, s89
	v_lshl_add_u64 v[182:183], v[182:183], 0, s[48:49]
	s_add_u32 s8, s78, 0x20180
	ds_read_b128 v[202:205], v201 offset:49152
	ds_read_b128 v[206:209], v201 offset:50176
	ds_read_b128 v[210:213], v201 offset:51200
	ds_read_b128 v[214:217], v201 offset:52224
	ds_read_b128 v[218:221], v201 offset:53248
	ds_read_b128 v[222:225], v201 offset:54272
	ds_read_b128 v[226:229], v201 offset:55296
	ds_read_b128 v[230:233], v201 offset:56320
	global_load_lds_dwordx4 v[182:183], off
	v_lshl_add_u64 v[182:183], v[184:185], 0, s[48:49]
	s_mov_b32 m0, s90
	s_addc_u32 s9, s79, 0
	global_load_lds_dwordx4 v[182:183], off
	v_lshl_add_u64 v[182:183], s[8:9], 0, v[164:165]
	s_mov_b32 m0, s93
	s_nop 0
	global_load_lds_dwordx4 v[182:183], off
	v_lshl_add_u64 v[182:183], s[8:9], 0, v[168:169]
	s_mov_b32 m0, s95
	s_nop 0
	global_load_lds_dwordx4 v[182:183], off
	v_lshl_add_u64 v[182:183], v[186:187], 0, s[48:49]
	s_mov_b32 m0, s91
	s_nop 0
	global_load_lds_dwordx4 v[182:183], off
	v_lshl_add_u64 v[182:183], v[188:189], 0, s[48:49]
	s_mov_b32 m0, s92
	s_nop 0
	global_load_lds_dwordx4 v[182:183], off
	s_waitcnt vmcnt(8)
	s_waitcnt lgkmcnt(0)
	s_setprio 1
	s_barrier
	v_mfma_f32_16x16x128_f8f6f4 v[94:97], v[18:25], v[202:209], v[94:97]
	v_mfma_f32_16x16x128_f8f6f4 v[90:93], v[26:33], v[202:209], v[90:93]
	v_mfma_f32_16x16x128_f8f6f4 v[82:85], v[26:33], v[210:217], v[82:85]
	v_mfma_f32_16x16x128_f8f6f4 v[86:89], v[18:25], v[210:217], v[86:89]
	v_mfma_f32_16x16x128_f8f6f4 v[78:81], v[18:25], v[218:225], v[78:81]
	v_mfma_f32_16x16x128_f8f6f4 v[74:77], v[26:33], v[218:225], v[74:77]
	v_mfma_f32_16x16x128_f8f6f4 v[66:69], v[26:33], v[226:233], v[66:69]
	v_mfma_f32_16x16x128_f8f6f4 v[70:73], v[18:25], v[226:233], v[70:73]
	s_setprio 0
	s_setprio 1
	v_mfma_f32_16x16x128_f8f6f4 v[38:41], v[2:9], v[226:233], v[38:41]
	v_mfma_f32_16x16x128_f8f6f4 v[34:37], v[10:17], v[226:233], v[34:37]
	v_mfma_f32_16x16x128_f8f6f4 v[42:45], v[10:17], v[218:225], v[42:45]
	v_mfma_f32_16x16x128_f8f6f4 v[46:49], v[2:9], v[218:225], v[46:49]
	v_mfma_f32_16x16x128_f8f6f4 v[54:57], v[2:9], v[210:217], v[54:57]
	v_mfma_f32_16x16x128_f8f6f4 v[50:53], v[10:17], v[210:217], v[50:53]
	s_barrier
	v_mfma_f32_16x16x128_f8f6f4 v[58:61], v[10:17], v[202:209], v[58:61]
	v_mfma_f32_16x16x128_f8f6f4 v[62:65], v[2:9], v[202:209], v[62:65]
	s_setprio 0
	s_add_u32 s80, s80, 0x20180
	s_addc_u32 s81, s81, 0
	s_add_u32 s8, s78, 0x200
	s_addc_u32 s9, s79, 0
	s_mov_b32 s62, 0
.LBB0_601:
	ds_read_b128 v[2:5], v200
	ds_read_b128 v[6:9], v200 offset:1024
	ds_read_b128 v[18:21], v200 offset:2048
	ds_read_b128 v[22:25], v200 offset:3072
	ds_read_b128 v[26:29], v200 offset:16384
	ds_read_b128 v[30:33], v200 offset:17408
	ds_read_b128 v[182:185], v200 offset:18432
	ds_read_b128 v[186:189], v200 offset:19456
	s_add_u32 s63, s80, 0xfffe0080
	s_addc_u32 s71, s81, -1
	s_cmp_eq_u32 s62, 4
	s_cselect_b32 s83, s4, s71
	s_cselect_b32 s82, s5, s63
	s_cselect_b32 s79, s53, s9
	s_cselect_b32 s78, s55, s8
	s_mov_b32 m0, s96
	v_lshl_add_u64 v[226:227], s[80:81], 0, v[170:171]
	ds_read_b128 v[10:13], v201
	ds_read_b128 v[14:17], v201 offset:1024
	ds_read_b128 v[202:205], v201 offset:2048
	ds_read_b128 v[206:209], v201 offset:3072
	ds_read_b128 v[210:213], v201 offset:4096
	ds_read_b128 v[214:217], v201 offset:5120
	ds_read_b128 v[218:221], v201 offset:6144
	ds_read_b128 v[222:225], v201 offset:7168
	global_load_lds_dwordx4 v[226:227], off
	v_lshl_add_u64 v[226:227], s[80:81], 0, v[172:173]
	s_mov_b32 m0, s61
	s_nop 0
	global_load_lds_dwordx4 v[226:227], off
	s_waitcnt vmcnt(8)
	s_waitcnt lgkmcnt(0)
	s_setprio 1
	s_barrier
	v_mfma_f32_16x16x128_f8f6f4 v[158:161], v[2:9], v[10:17], v[158:161]
	v_mfma_f32_16x16x128_f8f6f4 v[154:157], v[18:25], v[10:17], v[154:157]
	v_mfma_f32_16x16x128_f8f6f4 v[146:149], v[18:25], v[202:209], v[146:149]
	v_mfma_f32_16x16x128_f8f6f4 v[150:153], v[2:9], v[202:209], v[150:153]
	v_mfma_f32_16x16x128_f8f6f4 v[142:145], v[2:9], v[210:217], v[142:145]
	v_mfma_f32_16x16x128_f8f6f4 v[138:141], v[18:25], v[210:217], v[138:141]
	v_mfma_f32_16x16x128_f8f6f4 v[130:133], v[18:25], v[218:225], v[130:133]
	v_mfma_f32_16x16x128_f8f6f4 v[134:137], v[2:9], v[218:225], v[134:137]
	s_setprio 0
	s_setprio 1
	v_mfma_f32_16x16x128_f8f6f4 v[102:105], v[26:33], v[218:225], v[102:105]
	v_mfma_f32_16x16x128_f8f6f4 v[98:101], v[182:189], v[218:225], v[98:101]
	v_mfma_f32_16x16x128_f8f6f4 v[106:109], v[182:189], v[210:217], v[106:109]
	v_mfma_f32_16x16x128_f8f6f4 v[110:113], v[26:33], v[210:217], v[110:113]
	v_mfma_f32_16x16x128_f8f6f4 v[118:121], v[26:33], v[202:209], v[118:121]
	v_mfma_f32_16x16x128_f8f6f4 v[114:117], v[182:189], v[202:209], v[114:117]
	s_barrier
	v_mfma_f32_16x16x128_f8f6f4 v[122:125], v[182:189], v[10:17], v[122:125]
	v_mfma_f32_16x16x128_f8f6f4 v[126:129], v[26:33], v[10:17], v[126:129]
	s_setprio 0
	s_mov_b32 m0, s68
	v_lshl_add_u64 v[10:11], s[78:79], 0, v[164:165]
	s_add_u32 vcc_lo, s78, 0x20000
	ds_read_b128 v[202:205], v201 offset:16384
	ds_read_b128 v[206:209], v201 offset:17408
	ds_read_b128 v[210:213], v201 offset:18432
	ds_read_b128 v[214:217], v201 offset:19456
	ds_read_b128 v[218:221], v201 offset:20480
	ds_read_b128 v[222:225], v201 offset:21504
	ds_read_b128 v[226:229], v201 offset:22528
	ds_read_b128 v[230:233], v201 offset:23552
	global_load_lds_dwordx4 v[10:11], off
	v_lshl_add_u64 v[12:13], s[78:79], 0, v[168:169]
	s_mov_b32 m0, s69
	s_addc_u32 vcc_hi, s79, 0
	global_load_lds_dwordx4 v[12:13], off
	v_lshl_add_u64 v[14:15], vcc, 0, v[164:165]
	s_mov_b32 m0, s77
	v_lshl_add_u64 v[16:17], s[82:83], 0, v[166:167]
	global_load_lds_dwordx4 v[14:15], off
	v_lshl_add_u64 v[14:15], vcc, 0, v[168:169]
	s_mov_b32 m0, s84
	s_nop 0
	global_load_lds_dwordx4 v[14:15], off
	v_lshl_add_u64 v[14:15], s[82:83], 0, v[162:163]
	s_mov_b32 m0, s33
	s_nop 0
	global_load_lds_dwordx4 v[14:15], off
	s_mov_b32 m0, s85
	s_nop 0
	global_load_lds_dwordx4 v[16:17], off
	s_waitcnt vmcnt(8)
	s_waitcnt lgkmcnt(0)
	s_setprio 1
	s_barrier
	v_mfma_f32_16x16x128_f8f6f4 v[94:97], v[2:9], v[202:209], v[94:97]
	v_mfma_f32_16x16x128_f8f6f4 v[90:93], v[18:25], v[202:209], v[90:93]
	v_mfma_f32_16x16x128_f8f6f4 v[82:85], v[18:25], v[210:217], v[82:85]
	v_mfma_f32_16x16x128_f8f6f4 v[86:89], v[2:9], v[210:217], v[86:89]
	v_mfma_f32_16x16x128_f8f6f4 v[78:81], v[2:9], v[218:225], v[78:81]
	v_mfma_f32_16x16x128_f8f6f4 v[74:77], v[18:25], v[218:225], v[74:77]
	v_mfma_f32_16x16x128_f8f6f4 v[66:69], v[18:25], v[226:233], v[66:69]
	v_mfma_f32_16x16x128_f8f6f4 v[70:73], v[2:9], v[226:233], v[70:73]
	s_setprio 0
	s_setprio 1
	v_mfma_f32_16x16x128_f8f6f4 v[38:41], v[26:33], v[226:233], v[38:41]
	v_mfma_f32_16x16x128_f8f6f4 v[34:37], v[182:189], v[226:233], v[34:37]
	v_mfma_f32_16x16x128_f8f6f4 v[42:45], v[182:189], v[218:225], v[42:45]
	v_mfma_f32_16x16x128_f8f6f4 v[46:49], v[26:33], v[218:225], v[46:49]
	v_mfma_f32_16x16x128_f8f6f4 v[54:57], v[26:33], v[210:217], v[54:57]
	v_mfma_f32_16x16x128_f8f6f4 v[50:53], v[182:189], v[210:217], v[50:53]
	s_barrier
	v_mfma_f32_16x16x128_f8f6f4 v[58:61], v[182:189], v[202:209], v[58:61]
	v_mfma_f32_16x16x128_f8f6f4 v[62:65], v[26:33], v[202:209], v[62:65]
	s_setprio 0
	ds_read_b128 v[18:21], v200 offset:32768
	ds_read_b128 v[22:25], v200 offset:33792
	ds_read_b128 v[26:29], v200 offset:34816
	ds_read_b128 v[30:33], v200 offset:35840
	ds_read_b128 v[2:5], v200 offset:49152
	ds_read_b128 v[6:9], v200 offset:50176
	ds_read_b128 v[182:185], v200 offset:51200
	ds_read_b128 v[186:189], v200 offset:52224
	s_add_u32 s82, s82, 0x20000
	s_addc_u32 s83, s83, 0
	s_mov_b32 m0, s86
	v_lshl_add_u64 v[234:235], s[82:83], 0, v[162:163]
	ds_read_b128 v[202:205], v201 offset:32768
	ds_read_b128 v[206:209], v201 offset:33792
	ds_read_b128 v[210:213], v201 offset:34816
	ds_read_b128 v[214:217], v201 offset:35840
	ds_read_b128 v[218:221], v201 offset:36864
	ds_read_b128 v[222:225], v201 offset:37888
	ds_read_b128 v[226:229], v201 offset:38912
	ds_read_b128 v[230:233], v201 offset:39936
	global_load_lds_dwordx4 v[234:235], off
	v_lshl_add_u64 v[234:235], s[82:83], 0, v[166:167]
	s_mov_b32 m0, s87
	s_nop 0
	global_load_lds_dwordx4 v[234:235], off
	s_waitcnt vmcnt(8)
	s_waitcnt lgkmcnt(0)
	s_setprio 1
	s_barrier
	v_mfma_f32_16x16x128_f8f6f4 v[158:161], v[18:25], v[202:209], v[158:161]
	v_mfma_f32_16x16x128_f8f6f4 v[154:157], v[26:33], v[202:209], v[154:157]
	v_mfma_f32_16x16x128_f8f6f4 v[146:149], v[26:33], v[210:217], v[146:149]
	v_mfma_f32_16x16x128_f8f6f4 v[150:153], v[18:25], v[210:217], v[150:153]
	v_mfma_f32_16x16x128_f8f6f4 v[142:145], v[18:25], v[218:225], v[142:145]
	v_mfma_f32_16x16x128_f8f6f4 v[138:141], v[26:33], v[218:225], v[138:141]
	v_mfma_f32_16x16x128_f8f6f4 v[130:133], v[26:33], v[226:233], v[130:133]
	v_mfma_f32_16x16x128_f8f6f4 v[134:137], v[18:25], v[226:233], v[134:137]
	s_setprio 0
	s_setprio 1
	v_mfma_f32_16x16x128_f8f6f4 v[102:105], v[2:9], v[226:233], v[102:105]
	v_mfma_f32_16x16x128_f8f6f4 v[98:101], v[182:189], v[226:233], v[98:101]
	v_mfma_f32_16x16x128_f8f6f4 v[106:109], v[182:189], v[218:225], v[106:109]
	v_mfma_f32_16x16x128_f8f6f4 v[110:113], v[2:9], v[218:225], v[110:113]
	v_mfma_f32_16x16x128_f8f6f4 v[118:121], v[2:9], v[210:217], v[118:121]
	v_mfma_f32_16x16x128_f8f6f4 v[114:117], v[182:189], v[210:217], v[114:117]
	s_barrier
	v_mfma_f32_16x16x128_f8f6f4 v[122:125], v[182:189], v[202:209], v[122:125]
	v_mfma_f32_16x16x128_f8f6f4 v[126:129], v[2:9], v[202:209], v[126:129]
	s_setprio 0
	s_mov_b32 m0, s89
	v_lshl_add_u64 v[10:11], v[10:11], 0, s[42:43]
	s_add_u32 s78, s78, 0x20080
	ds_read_b128 v[202:205], v201 offset:49152
	ds_read_b128 v[206:209], v201 offset:50176
	ds_read_b128 v[210:213], v201 offset:51200
	ds_read_b128 v[214:217], v201 offset:52224
	ds_read_b128 v[218:221], v201 offset:53248
	ds_read_b128 v[222:225], v201 offset:54272
	ds_read_b128 v[226:229], v201 offset:55296
	ds_read_b128 v[230:233], v201 offset:56320
	global_load_lds_dwordx4 v[10:11], off
	v_lshl_add_u64 v[10:11], v[12:13], 0, s[42:43]
	s_mov_b32 m0, s90
	s_addc_u32 s79, s79, 0
	global_load_lds_dwordx4 v[10:11], off
	v_lshl_add_u64 v[10:11], s[78:79], 0, v[164:165]
	s_mov_b32 m0, s93
	s_nop 0
	global_load_lds_dwordx4 v[10:11], off
	v_lshl_add_u64 v[10:11], s[78:79], 0, v[168:169]
	s_mov_b32 m0, s95
	s_nop 0
	global_load_lds_dwordx4 v[10:11], off
	v_lshl_add_u64 v[10:11], v[14:15], 0, s[42:43]
	s_mov_b32 m0, s91
	s_nop 0
	global_load_lds_dwordx4 v[10:11], off
	v_lshl_add_u64 v[10:11], v[16:17], 0, s[42:43]
	s_mov_b32 m0, s92
	s_nop 0
	global_load_lds_dwordx4 v[10:11], off
	s_waitcnt vmcnt(8)
	s_waitcnt lgkmcnt(0)
	s_setprio 1
	s_barrier
	v_mfma_f32_16x16x128_f8f6f4 v[94:97], v[18:25], v[202:209], v[94:97]
	v_mfma_f32_16x16x128_f8f6f4 v[90:93], v[26:33], v[202:209], v[90:93]
	v_mfma_f32_16x16x128_f8f6f4 v[82:85], v[26:33], v[210:217], v[82:85]
	v_mfma_f32_16x16x128_f8f6f4 v[86:89], v[18:25], v[210:217], v[86:89]
	v_mfma_f32_16x16x128_f8f6f4 v[78:81], v[18:25], v[218:225], v[78:81]
	v_mfma_f32_16x16x128_f8f6f4 v[74:77], v[26:33], v[218:225], v[74:77]
	v_mfma_f32_16x16x128_f8f6f4 v[66:69], v[26:33], v[226:233], v[66:69]
	v_mfma_f32_16x16x128_f8f6f4 v[70:73], v[18:25], v[226:233], v[70:73]
	s_setprio 0
	s_setprio 1
	v_mfma_f32_16x16x128_f8f6f4 v[38:41], v[2:9], v[226:233], v[38:41]
	v_mfma_f32_16x16x128_f8f6f4 v[34:37], v[182:189], v[226:233], v[34:37]
	v_mfma_f32_16x16x128_f8f6f4 v[42:45], v[182:189], v[218:225], v[42:45]
	v_mfma_f32_16x16x128_f8f6f4 v[46:49], v[2:9], v[218:225], v[46:49]
	v_mfma_f32_16x16x128_f8f6f4 v[54:57], v[2:9], v[210:217], v[54:57]
	v_mfma_f32_16x16x128_f8f6f4 v[50:53], v[182:189], v[210:217], v[50:53]
	s_barrier
	v_mfma_f32_16x16x128_f8f6f4 v[58:61], v[182:189], v[202:209], v[58:61]
	v_mfma_f32_16x16x128_f8f6f4 v[62:65], v[2:9], v[202:209], v[62:65]
	s_setprio 0
	s_add_i32 s62, s62, 2
	s_add_u32 s80, s80, 0x100
	s_addc_u32 s81, s81, 0
	s_add_u32 s8, s8, 0x100
	s_addc_u32 s9, s9, 0
	s_cmp_gt_u32 s62, 5
	s_cbranch_scc0 .LBB0_601
	s_and_b64 vcc, exec, s[44:45]
	s_cbranch_vccz .LBB0_604
	s_barrier

.LBB0_616:
	ds_read_b128 v[18:21], v188
	ds_read_b128 v[22:25], v188 offset:1024
	ds_read_b128 v[26:29], v188 offset:2048
	ds_read_b128 v[30:33], v188 offset:3072
	ds_read_b128 v[2:5], v188 offset:16384
	ds_read_b128 v[6:9], v188 offset:17408
	ds_read_b128 v[10:13], v188 offset:18432
	ds_read_b128 v[14:17], v188 offset:19456
	s_ashr_i32 s55, s54, 31
	s_lshl_b64 s[62:63], s[54:55], 17
	s_add_u32 s72, s36, s62
	s_addc_u32 s73, s37, s63
	s_and_b64 s[62:63], s[2:3], exec
	s_cselect_b32 s85, s73, s79
	s_cselect_b32 s84, s72, s78
	s_ashr_i32 s53, s52, 31
	s_lshl_b64 s[62:63], s[52:53], 17
	s_add_u32 s74, s94, s62
	v_readlane_b32 s5, v254, 8
	s_addc_u32 s75, s5, s63
	s_and_b64 s[62:63], s[2:3], exec
	s_cselect_b32 s83, s75, s81
	s_cselect_b32 s82, s74, s80
	s_add_u32 s62, s78, 0x10080
	s_addc_u32 s63, s79, 0
	s_mov_b32 m0, s96
	v_lshl_add_u64 v[174:175], s[62:63], 0, v[166:167]
	ds_read_b128 v[196:199], v189
	ds_read_b128 v[200:203], v189 offset:1024
	ds_read_b128 v[204:207], v189 offset:2048
	ds_read_b128 v[208:211], v189 offset:3072
	ds_read_b128 v[212:215], v189 offset:4096
	ds_read_b128 v[216:219], v189 offset:5120
	ds_read_b128 v[220:223], v189 offset:6144
	ds_read_b128 v[224:227], v189 offset:7168
	global_load_lds_dwordx4 v[174:175], off
	v_lshl_add_u64 v[174:175], s[62:63], 0, v[168:169]
	s_mov_b32 m0, s97
	s_nop 0
	global_load_lds_dwordx4 v[174:175], off
	s_waitcnt vmcnt(8)
	s_waitcnt lgkmcnt(0)
	s_setprio 1
	s_barrier
	v_mfma_f32_16x16x128_f8f6f4 v[158:161], v[18:25], v[196:203], 0
	v_mfma_f32_16x16x128_f8f6f4 v[154:157], v[26:33], v[196:203], 0
	v_mfma_f32_16x16x128_f8f6f4 v[146:149], v[26:33], v[204:211], 0
	v_mfma_f32_16x16x128_f8f6f4 v[150:153], v[18:25], v[204:211], 0
	v_mfma_f32_16x16x128_f8f6f4 v[142:145], v[18:25], v[212:219], 0
	v_mfma_f32_16x16x128_f8f6f4 v[138:141], v[26:33], v[212:219], 0
	v_mfma_f32_16x16x128_f8f6f4 v[130:133], v[26:33], v[220:227], 0
	v_mfma_f32_16x16x128_f8f6f4 v[134:137], v[18:25], v[220:227], 0
	s_setprio 0
	s_setprio 1
	v_mfma_f32_16x16x128_f8f6f4 v[102:105], v[2:9], v[220:227], 0
	v_mfma_f32_16x16x128_f8f6f4 v[98:101], v[10:17], v[220:227], 0
	v_mfma_f32_16x16x128_f8f6f4 v[106:109], v[10:17], v[212:219], 0
	v_mfma_f32_16x16x128_f8f6f4 v[110:113], v[2:9], v[212:219], 0
	v_mfma_f32_16x16x128_f8f6f4 v[118:121], v[2:9], v[204:211], 0
	v_mfma_f32_16x16x128_f8f6f4 v[114:117], v[10:17], v[204:211], 0
	s_barrier
	v_mfma_f32_16x16x128_f8f6f4 v[122:125], v[10:17], v[196:203], 0
	v_mfma_f32_16x16x128_f8f6f4 v[126:129], v[2:9], v[196:203], 0
	s_setprio 0
	v_lshl_add_u64 v[174:175], s[80:81], 0, v[162:163]
	s_mov_b32 m0, s61
	v_lshl_add_u64 v[176:177], v[174:175], 0, s[46:47]
	ds_read_b128 v[196:199], v189 offset:16384
	ds_read_b128 v[200:203], v189 offset:17408
	ds_read_b128 v[204:207], v189 offset:18432
	ds_read_b128 v[208:211], v189 offset:19456
	ds_read_b128 v[212:215], v189 offset:20480
	ds_read_b128 v[216:219], v189 offset:21504
	ds_read_b128 v[220:223], v189 offset:22528
	ds_read_b128 v[224:227], v189 offset:23552
	global_load_lds_dwordx4 v[176:177], off
	v_lshl_add_u64 v[176:177], s[80:81], 0, v[164:165]
	s_add_u32 s62, s80, 0x10100
	v_lshl_add_u64 v[182:183], v[176:177], 0, s[46:47]
	s_mov_b32 m0, s68
	s_addc_u32 s63, s81, 0
	global_load_lds_dwordx4 v[182:183], off
	v_lshl_add_u64 v[182:183], s[62:63], 0, v[162:163]
	s_mov_b32 m0, s69
	s_nop 0
	global_load_lds_dwordx4 v[182:183], off
	v_lshl_add_u64 v[182:183], s[62:63], 0, v[164:165]
	s_mov_b32 m0, s77
	s_nop 0
	global_load_lds_dwordx4 v[182:183], off
	v_lshl_add_u64 v[182:183], s[78:79], 0, v[166:167]
	v_lshl_add_u64 v[184:185], v[182:183], 0, s[46:47]
	s_mov_b32 m0, s51
	s_nop 0
	global_load_lds_dwordx4 v[184:185], off
	v_lshl_add_u64 v[184:185], s[78:79], 0, v[168:169]
	v_lshl_add_u64 v[228:229], v[184:185], 0, s[46:47]
	s_mov_b32 m0, s86
	s_nop 0
	global_load_lds_dwordx4 v[228:229], off
	s_waitcnt vmcnt(8)
	s_waitcnt lgkmcnt(0)
	s_setprio 1
	s_barrier
	v_mfma_f32_16x16x128_f8f6f4 v[94:97], v[18:25], v[196:203], 0
	v_mfma_f32_16x16x128_f8f6f4 v[90:93], v[26:33], v[196:203], 0
	v_mfma_f32_16x16x128_f8f6f4 v[82:85], v[26:33], v[204:211], 0
	v_mfma_f32_16x16x128_f8f6f4 v[86:89], v[18:25], v[204:211], 0
	v_mfma_f32_16x16x128_f8f6f4 v[78:81], v[18:25], v[212:219], 0
	v_mfma_f32_16x16x128_f8f6f4 v[74:77], v[26:33], v[212:219], 0
	v_mfma_f32_16x16x128_f8f6f4 v[66:69], v[26:33], v[220:227], 0
	v_mfma_f32_16x16x128_f8f6f4 v[70:73], v[18:25], v[220:227], 0
	s_setprio 0
	s_setprio 1
	v_mfma_f32_16x16x128_f8f6f4 v[38:41], v[2:9], v[220:227], 0
	v_mfma_f32_16x16x128_f8f6f4 v[34:37], v[10:17], v[220:227], 0
	v_mfma_f32_16x16x128_f8f6f4 v[42:45], v[10:17], v[212:219], 0
	v_mfma_f32_16x16x128_f8f6f4 v[46:49], v[2:9], v[212:219], 0
	v_mfma_f32_16x16x128_f8f6f4 v[54:57], v[2:9], v[204:211], 0
	v_mfma_f32_16x16x128_f8f6f4 v[50:53], v[10:17], v[204:211], 0
	s_barrier
	v_mfma_f32_16x16x128_f8f6f4 v[58:61], v[10:17], v[196:203], 0
	v_mfma_f32_16x16x128_f8f6f4 v[62:65], v[2:9], v[196:203], 0
	s_setprio 0
	ds_read_b128 v[2:5], v188 offset:32768
	ds_read_b128 v[6:9], v188 offset:33792
	ds_read_b128 v[10:13], v188 offset:34816
	ds_read_b128 v[14:17], v188 offset:35840
	ds_read_b128 v[18:21], v188 offset:49152
	ds_read_b128 v[22:25], v188 offset:50176
	ds_read_b128 v[26:29], v188 offset:51200
	ds_read_b128 v[30:33], v188 offset:52224
	s_add_u32 s62, s78, 0x10100
	s_addc_u32 s63, s79, 0
	s_mov_b32 m0, s87
	v_lshl_add_u64 v[228:229], s[62:63], 0, v[166:167]
	ds_read_b128 v[196:199], v189 offset:32768
	ds_read_b128 v[200:203], v189 offset:33792
	ds_read_b128 v[204:207], v189 offset:34816
	ds_read_b128 v[208:211], v189 offset:35840
	ds_read_b128 v[212:215], v189 offset:36864
	ds_read_b128 v[216:219], v189 offset:37888
	ds_read_b128 v[220:223], v189 offset:38912
	ds_read_b128 v[224:227], v189 offset:39936
	global_load_lds_dwordx4 v[228:229], off
	v_lshl_add_u64 v[228:229], s[62:63], 0, v[168:169]
	s_mov_b32 m0, s88
	s_nop 0
	global_load_lds_dwordx4 v[228:229], off
	s_waitcnt vmcnt(8)
	s_waitcnt lgkmcnt(0)
	s_setprio 1
	s_barrier
	v_mfma_f32_16x16x128_f8f6f4 v[158:161], v[2:9], v[196:203], v[158:161]
	v_mfma_f32_16x16x128_f8f6f4 v[154:157], v[10:17], v[196:203], v[154:157]
	v_mfma_f32_16x16x128_f8f6f4 v[146:149], v[10:17], v[204:211], v[146:149]
	v_mfma_f32_16x16x128_f8f6f4 v[150:153], v[2:9], v[204:211], v[150:153]
	v_mfma_f32_16x16x128_f8f6f4 v[142:145], v[2:9], v[212:219], v[142:145]
	v_mfma_f32_16x16x128_f8f6f4 v[138:141], v[10:17], v[212:219], v[138:141]
	v_mfma_f32_16x16x128_f8f6f4 v[130:133], v[10:17], v[220:227], v[130:133]
	v_mfma_f32_16x16x128_f8f6f4 v[134:137], v[2:9], v[220:227], v[134:137]
	s_setprio 0
	s_setprio 1
	v_mfma_f32_16x16x128_f8f6f4 v[102:105], v[18:25], v[220:227], v[102:105]
	v_mfma_f32_16x16x128_f8f6f4 v[98:101], v[26:33], v[220:227], v[98:101]
	v_mfma_f32_16x16x128_f8f6f4 v[106:109], v[26:33], v[212:219], v[106:109]
	v_mfma_f32_16x16x128_f8f6f4 v[110:113], v[18:25], v[212:219], v[110:113]
	v_mfma_f32_16x16x128_f8f6f4 v[118:121], v[18:25], v[204:211], v[118:121]
	v_mfma_f32_16x16x128_f8f6f4 v[114:117], v[26:33], v[204:211], v[114:117]
	s_barrier
	v_mfma_f32_16x16x128_f8f6f4 v[122:125], v[26:33], v[196:203], v[122:125]
	v_mfma_f32_16x16x128_f8f6f4 v[126:129], v[18:25], v[196:203], v[126:129]
	s_setprio 0
	s_mov_b32 m0, s89
	v_lshl_add_u64 v[174:175], v[174:175], 0, s[48:49]
	s_add_u32 s62, s80, 0x10180
	ds_read_b128 v[196:199], v189 offset:49152
	ds_read_b128 v[200:203], v189 offset:50176
	ds_read_b128 v[204:207], v189 offset:51200
	ds_read_b128 v[208:211], v189 offset:52224
	ds_read_b128 v[212:215], v189 offset:53248
	ds_read_b128 v[216:219], v189 offset:54272
	ds_read_b128 v[220:223], v189 offset:55296
	ds_read_b128 v[224:227], v189 offset:56320
	global_load_lds_dwordx4 v[174:175], off
	v_lshl_add_u64 v[174:175], v[176:177], 0, s[48:49]
	s_mov_b32 m0, s90
	s_addc_u32 s63, s81, 0
	global_load_lds_dwordx4 v[174:175], off
	v_lshl_add_u64 v[174:175], s[62:63], 0, v[162:163]
	s_mov_b32 m0, s93
	s_nop 0
	global_load_lds_dwordx4 v[174:175], off
	v_lshl_add_u64 v[174:175], s[62:63], 0, v[164:165]
	s_mov_b32 m0, s95
	s_nop 0
	global_load_lds_dwordx4 v[174:175], off
	v_lshl_add_u64 v[174:175], v[182:183], 0, s[48:49]
	s_mov_b32 m0, s91
	s_nop 0
	global_load_lds_dwordx4 v[174:175], off
	v_lshl_add_u64 v[174:175], v[184:185], 0, s[48:49]
	s_mov_b32 m0, s92
	s_nop 0
	global_load_lds_dwordx4 v[174:175], off
	s_waitcnt vmcnt(8)
	s_waitcnt lgkmcnt(0)
	s_setprio 1
	s_barrier
	v_mfma_f32_16x16x128_f8f6f4 v[94:97], v[2:9], v[196:203], v[94:97]
	v_mfma_f32_16x16x128_f8f6f4 v[90:93], v[10:17], v[196:203], v[90:93]
	v_mfma_f32_16x16x128_f8f6f4 v[82:85], v[10:17], v[204:211], v[82:85]
	v_mfma_f32_16x16x128_f8f6f4 v[86:89], v[2:9], v[204:211], v[86:89]
	v_mfma_f32_16x16x128_f8f6f4 v[78:81], v[2:9], v[212:219], v[78:81]
	v_mfma_f32_16x16x128_f8f6f4 v[74:77], v[10:17], v[212:219], v[74:77]
	v_mfma_f32_16x16x128_f8f6f4 v[66:69], v[10:17], v[220:227], v[66:69]
	v_mfma_f32_16x16x128_f8f6f4 v[70:73], v[2:9], v[220:227], v[70:73]
	s_setprio 0
	s_setprio 1
	v_mfma_f32_16x16x128_f8f6f4 v[38:41], v[18:25], v[220:227], v[38:41]
	v_mfma_f32_16x16x128_f8f6f4 v[34:37], v[26:33], v[220:227], v[34:37]
	v_mfma_f32_16x16x128_f8f6f4 v[42:45], v[26:33], v[212:219], v[42:45]
	v_mfma_f32_16x16x128_f8f6f4 v[46:49], v[18:25], v[212:219], v[46:49]
	v_mfma_f32_16x16x128_f8f6f4 v[54:57], v[18:25], v[204:211], v[54:57]
	v_mfma_f32_16x16x128_f8f6f4 v[50:53], v[26:33], v[204:211], v[50:53]
	s_barrier
	v_mfma_f32_16x16x128_f8f6f4 v[58:61], v[26:33], v[196:203], v[58:61]
	v_mfma_f32_16x16x128_f8f6f4 v[62:65], v[18:25], v[196:203], v[62:65]
	s_setprio 0
	ds_read_b128 v[2:5], v188
	ds_read_b128 v[6:9], v188 offset:1024
	ds_read_b128 v[10:13], v188 offset:2048
	ds_read_b128 v[14:17], v188 offset:3072
	ds_read_b128 v[18:21], v188 offset:16384
	ds_read_b128 v[22:25], v188 offset:17408
	ds_read_b128 v[26:29], v188 offset:18432
	ds_read_b128 v[30:33], v188 offset:19456
	s_add_u32 s62, s78, 0x10180
	s_addc_u32 s63, s79, 0
	s_mov_b32 m0, s96
	v_lshl_add_u64 v[174:175], s[62:63], 0, v[166:167]
	ds_read_b128 v[196:199], v189
	ds_read_b128 v[200:203], v189 offset:1024
	ds_read_b128 v[204:207], v189 offset:2048
	ds_read_b128 v[208:211], v189 offset:3072
	ds_read_b128 v[212:215], v189 offset:4096
	ds_read_b128 v[216:219], v189 offset:5120
	ds_read_b128 v[220:223], v189 offset:6144
	ds_read_b128 v[224:227], v189 offset:7168
	global_load_lds_dwordx4 v[174:175], off
	v_lshl_add_u64 v[174:175], s[62:63], 0, v[168:169]
	s_mov_b32 m0, s97
	s_nop 0
	global_load_lds_dwordx4 v[174:175], off
	s_waitcnt vmcnt(8)
	s_waitcnt lgkmcnt(0)
	s_setprio 1
	s_barrier
	v_mfma_f32_16x16x128_f8f6f4 v[158:161], v[2:9], v[196:203], v[158:161]
	v_mfma_f32_16x16x128_f8f6f4 v[154:157], v[10:17], v[196:203], v[154:157]
	v_mfma_f32_16x16x128_f8f6f4 v[146:149], v[10:17], v[204:211], v[146:149]
	v_mfma_f32_16x16x128_f8f6f4 v[150:153], v[2:9], v[204:211], v[150:153]
	v_mfma_f32_16x16x128_f8f6f4 v[142:145], v[2:9], v[212:219], v[142:145]
	v_mfma_f32_16x16x128_f8f6f4 v[138:141], v[10:17], v[212:219], v[138:141]
	v_mfma_f32_16x16x128_f8f6f4 v[130:133], v[10:17], v[220:227], v[130:133]
	v_mfma_f32_16x16x128_f8f6f4 v[134:137], v[2:9], v[220:227], v[134:137]
	s_setprio 0
	s_setprio 1
	v_mfma_f32_16x16x128_f8f6f4 v[102:105], v[18:25], v[220:227], v[102:105]
	v_mfma_f32_16x16x128_f8f6f4 v[98:101], v[26:33], v[220:227], v[98:101]
	v_mfma_f32_16x16x128_f8f6f4 v[106:109], v[26:33], v[212:219], v[106:109]
	v_mfma_f32_16x16x128_f8f6f4 v[110:113], v[18:25], v[212:219], v[110:113]
	v_mfma_f32_16x16x128_f8f6f4 v[118:121], v[18:25], v[204:211], v[118:121]
	v_mfma_f32_16x16x128_f8f6f4 v[114:117], v[26:33], v[204:211], v[114:117]
	s_barrier
	v_mfma_f32_16x16x128_f8f6f4 v[122:125], v[26:33], v[196:203], v[122:125]
	v_mfma_f32_16x16x128_f8f6f4 v[126:129], v[18:25], v[196:203], v[126:129]
	s_setprio 0
	s_mov_b32 m0, s61
	v_lshl_add_u64 v[174:175], s[82:83], 0, v[162:163]
	s_add_u32 s62, s82, 0x10000
	ds_read_b128 v[196:199], v189 offset:16384
	ds_read_b128 v[200:203], v189 offset:17408
	ds_read_b128 v[204:207], v189 offset:18432
	ds_read_b128 v[208:211], v189 offset:19456
	ds_read_b128 v[212:215], v189 offset:20480
	ds_read_b128 v[216:219], v189 offset:21504
	ds_read_b128 v[220:223], v189 offset:22528
	ds_read_b128 v[224:227], v189 offset:23552
	global_load_lds_dwordx4 v[174:175], off
	v_lshl_add_u64 v[176:177], s[82:83], 0, v[164:165]
	s_mov_b32 m0, s68
	s_addc_u32 s63, s83, 0
	global_load_lds_dwordx4 v[176:177], off
	v_lshl_add_u64 v[182:183], s[62:63], 0, v[162:163]
	s_mov_b32 m0, s69
	v_lshl_add_u64 v[184:185], s[84:85], 0, v[168:169]
	global_load_lds_dwordx4 v[182:183], off
	v_lshl_add_u64 v[182:183], s[62:63], 0, v[164:165]
	s_mov_b32 m0, s77
	s_nop 0
	global_load_lds_dwordx4 v[182:183], off
	v_lshl_add_u64 v[182:183], s[84:85], 0, v[166:167]
	s_mov_b32 m0, s51
	s_nop 0
	global_load_lds_dwordx4 v[182:183], off
	s_mov_b32 m0, s86
	s_nop 0
	global_load_lds_dwordx4 v[184:185], off
	s_waitcnt vmcnt(8)
	s_waitcnt lgkmcnt(0)
	s_setprio 1
	s_barrier
	v_mfma_f32_16x16x128_f8f6f4 v[94:97], v[2:9], v[196:203], v[94:97]
	v_mfma_f32_16x16x128_f8f6f4 v[90:93], v[10:17], v[196:203], v[90:93]
	v_mfma_f32_16x16x128_f8f6f4 v[82:85], v[10:17], v[204:211], v[82:85]
	v_mfma_f32_16x16x128_f8f6f4 v[86:89], v[2:9], v[204:211], v[86:89]
	v_mfma_f32_16x16x128_f8f6f4 v[78:81], v[2:9], v[212:219], v[78:81]
	v_mfma_f32_16x16x128_f8f6f4 v[74:77], v[10:17], v[212:219], v[74:77]
	v_mfma_f32_16x16x128_f8f6f4 v[66:69], v[10:17], v[220:227], v[66:69]
	v_mfma_f32_16x16x128_f8f6f4 v[70:73], v[2:9], v[220:227], v[70:73]
	s_setprio 0
	s_setprio 1
	v_mfma_f32_16x16x128_f8f6f4 v[38:41], v[18:25], v[220:227], v[38:41]
	v_mfma_f32_16x16x128_f8f6f4 v[34:37], v[26:33], v[220:227], v[34:37]
	v_mfma_f32_16x16x128_f8f6f4 v[42:45], v[26:33], v[212:219], v[42:45]
	v_mfma_f32_16x16x128_f8f6f4 v[46:49], v[18:25], v[212:219], v[46:49]
	v_mfma_f32_16x16x128_f8f6f4 v[54:57], v[18:25], v[204:211], v[54:57]
	v_mfma_f32_16x16x128_f8f6f4 v[50:53], v[26:33], v[204:211], v[50:53]
	s_barrier
	v_mfma_f32_16x16x128_f8f6f4 v[58:61], v[26:33], v[196:203], v[58:61]
	v_mfma_f32_16x16x128_f8f6f4 v[62:65], v[18:25], v[196:203], v[62:65]
	s_setprio 0
	ds_read_b128 v[2:5], v188 offset:32768
	ds_read_b128 v[6:9], v188 offset:33792
	ds_read_b128 v[10:13], v188 offset:34816
	ds_read_b128 v[14:17], v188 offset:35840
	ds_read_b128 v[18:21], v188 offset:49152
	ds_read_b128 v[22:25], v188 offset:50176
	ds_read_b128 v[26:29], v188 offset:51200
	ds_read_b128 v[30:33], v188 offset:52224
	s_add_u32 s62, s84, 0x10000
	s_addc_u32 s63, s85, 0
	s_mov_b32 m0, s87
	v_lshl_add_u64 v[228:229], s[62:63], 0, v[166:167]
	ds_read_b128 v[196:199], v189 offset:32768
	ds_read_b128 v[200:203], v189 offset:33792
	ds_read_b128 v[204:207], v189 offset:34816
	ds_read_b128 v[208:211], v189 offset:35840
	ds_read_b128 v[212:215], v189 offset:36864
	ds_read_b128 v[216:219], v189 offset:37888
	ds_read_b128 v[220:223], v189 offset:38912
	ds_read_b128 v[224:227], v189 offset:39936
	global_load_lds_dwordx4 v[228:229], off
	v_lshl_add_u64 v[228:229], s[62:63], 0, v[168:169]
	s_mov_b32 m0, s88
	s_nop 0
	global_load_lds_dwordx4 v[228:229], off
	s_waitcnt vmcnt(8)
	s_waitcnt lgkmcnt(0)
	s_setprio 1
	s_barrier
	v_mfma_f32_16x16x128_f8f6f4 v[158:161], v[2:9], v[196:203], v[158:161]
	v_mfma_f32_16x16x128_f8f6f4 v[154:157], v[10:17], v[196:203], v[154:157]
	v_mfma_f32_16x16x128_f8f6f4 v[146:149], v[10:17], v[204:211], v[146:149]
	v_mfma_f32_16x16x128_f8f6f4 v[150:153], v[2:9], v[204:211], v[150:153]
	v_mfma_f32_16x16x128_f8f6f4 v[142:145], v[2:9], v[212:219], v[142:145]
	v_mfma_f32_16x16x128_f8f6f4 v[138:141], v[10:17], v[212:219], v[138:141]
	v_mfma_f32_16x16x128_f8f6f4 v[130:133], v[10:17], v[220:227], v[130:133]
	v_mfma_f32_16x16x128_f8f6f4 v[134:137], v[2:9], v[220:227], v[134:137]
	s_setprio 0
	s_setprio 1
	v_mfma_f32_16x16x128_f8f6f4 v[102:105], v[18:25], v[220:227], v[102:105]
	v_mfma_f32_16x16x128_f8f6f4 v[98:101], v[26:33], v[220:227], v[98:101]
	v_mfma_f32_16x16x128_f8f6f4 v[106:109], v[26:33], v[212:219], v[106:109]
	v_mfma_f32_16x16x128_f8f6f4 v[110:113], v[18:25], v[212:219], v[110:113]
	v_mfma_f32_16x16x128_f8f6f4 v[118:121], v[18:25], v[204:211], v[118:121]
	v_mfma_f32_16x16x128_f8f6f4 v[114:117], v[26:33], v[204:211], v[114:117]
	s_barrier
	v_mfma_f32_16x16x128_f8f6f4 v[122:125], v[26:33], v[196:203], v[122:125]
	v_mfma_f32_16x16x128_f8f6f4 v[126:129], v[18:25], v[196:203], v[126:129]
	s_setprio 0
	s_mov_b32 m0, s89
	v_lshl_add_u64 v[174:175], v[174:175], 0, s[40:41]
	s_add_u32 s62, s82, 0x10080
	ds_read_b128 v[196:199], v189 offset:49152
	ds_read_b128 v[200:203], v189 offset:50176
	ds_read_b128 v[204:207], v189 offset:51200
	ds_read_b128 v[208:211], v189 offset:52224
	ds_read_b128 v[212:215], v189 offset:53248
	ds_read_b128 v[216:219], v189 offset:54272
	ds_read_b128 v[220:223], v189 offset:55296
	ds_read_b128 v[224:227], v189 offset:56320
	global_load_lds_dwordx4 v[174:175], off
	v_lshl_add_u64 v[174:175], v[176:177], 0, s[40:41]
	s_mov_b32 m0, s90
	s_addc_u32 s63, s83, 0
	global_load_lds_dwordx4 v[174:175], off
	v_lshl_add_u64 v[174:175], s[62:63], 0, v[162:163]
	s_mov_b32 m0, s93
	s_nop 0
	global_load_lds_dwordx4 v[174:175], off
	v_lshl_add_u64 v[174:175], s[62:63], 0, v[164:165]
	s_mov_b32 m0, s95
	s_nop 0
	global_load_lds_dwordx4 v[174:175], off
	v_lshl_add_u64 v[174:175], v[182:183], 0, s[40:41]
	s_mov_b32 m0, s91
	s_nop 0
	global_load_lds_dwordx4 v[174:175], off
	v_lshl_add_u64 v[174:175], v[184:185], 0, s[40:41]
	s_mov_b32 m0, s92
	s_nop 0
	global_load_lds_dwordx4 v[174:175], off
	s_waitcnt vmcnt(8)
	s_waitcnt lgkmcnt(0)
	s_setprio 1
	s_barrier
	v_mfma_f32_16x16x128_f8f6f4 v[94:97], v[2:9], v[196:203], v[94:97]
	v_mfma_f32_16x16x128_f8f6f4 v[90:93], v[10:17], v[196:203], v[90:93]
	v_mfma_f32_16x16x128_f8f6f4 v[82:85], v[10:17], v[204:211], v[82:85]
	v_mfma_f32_16x16x128_f8f6f4 v[86:89], v[2:9], v[204:211], v[86:89]
	v_mfma_f32_16x16x128_f8f6f4 v[78:81], v[2:9], v[212:219], v[78:81]
	v_mfma_f32_16x16x128_f8f6f4 v[74:77], v[10:17], v[212:219], v[74:77]
	v_mfma_f32_16x16x128_f8f6f4 v[66:69], v[10:17], v[220:227], v[66:69]
	v_mfma_f32_16x16x128_f8f6f4 v[70:73], v[2:9], v[220:227], v[70:73]
	s_setprio 0
	s_setprio 1
	v_mfma_f32_16x16x128_f8f6f4 v[38:41], v[18:25], v[220:227], v[38:41]
	v_mfma_f32_16x16x128_f8f6f4 v[34:37], v[26:33], v[220:227], v[34:37]
	v_mfma_f32_16x16x128_f8f6f4 v[42:45], v[26:33], v[212:219], v[42:45]
	v_mfma_f32_16x16x128_f8f6f4 v[46:49], v[18:25], v[212:219], v[46:49]
	v_mfma_f32_16x16x128_f8f6f4 v[54:57], v[18:25], v[204:211], v[54:57]
	v_mfma_f32_16x16x128_f8f6f4 v[50:53], v[26:33], v[204:211], v[50:53]
	s_barrier
	v_mfma_f32_16x16x128_f8f6f4 v[58:61], v[26:33], v[196:203], v[58:61]
	v_mfma_f32_16x16x128_f8f6f4 v[62:65], v[18:25], v[196:203], v[62:65]
	s_setprio 0
	s_andn2_b64 vcc, exec, s[42:43]
	s_cbranch_vccnz .LBB0_618
	s_barrier

.LBB0_630:
	s_ashr_i32 s54, s48, 1
	s_ashr_i32 s51, s50, 31
	s_ashr_i32 s55, s54, 31
	s_lshl_b64 s[52:53], s[50:51], 19
	s_lshl_b64 s[54:55], s[54:55], 9
	s_waitcnt vmcnt(0)
	ds_read_b128 v[18:21], v181
	ds_read_b128 v[22:25], v181 offset:1024
	ds_read_b128 v[26:29], v181 offset:2048
	ds_read_b128 v[30:33], v181 offset:3072
	ds_read_b128 v[2:5], v181 offset:16384
	ds_read_b128 v[6:9], v181 offset:17408
	ds_read_b128 v[10:13], v181 offset:18432
	ds_read_b128 v[14:17], v181 offset:19456
	s_add_u32 s5, s26, s52
	s_addc_u32 s33, s27, s53
	s_add_u32 s52, s5, s54
	s_addc_u32 s53, s33, s55
	s_and_b64 s[54:55], s[2:3], exec
	s_cselect_b32 s81, s53, s75
	s_cselect_b32 s80, s52, s74
	s_ashr_i32 s49, s48, 31
	s_lshl_b64 s[54:55], s[48:49], 17
	v_readlane_b32 s5, v254, 9
	s_add_u32 s54, s5, s54
	v_readlane_b32 s5, v254, 10
	s_addc_u32 s55, s5, s55
	s_and_b64 s[62:63], s[2:3], exec
	s_cselect_b32 s79, s55, s77
	s_cselect_b32 s78, s54, s76
	s_add_u32 s62, s74, 0x40080
	s_addc_u32 s63, s75, 0
	s_add_i32 s33, s8, 0xc000
	v_lshl_add_u64 v[174:175], s[62:63], 0, v[166:167]
	s_mov_b32 m0, s33
	s_add_i32 s5, s8, 0xe000
	ds_read_b128 v[190:193], v187
	ds_read_b128 v[194:197], v187 offset:1024
	ds_read_b128 v[198:201], v187 offset:2048
	ds_read_b128 v[202:205], v187 offset:3072
	ds_read_b128 v[206:209], v187 offset:4096
	ds_read_b128 v[210:213], v187 offset:5120
	ds_read_b128 v[214:217], v187 offset:6144
	ds_read_b128 v[218:221], v187 offset:7168
	global_load_lds_dwordx4 v[174:175], off
	v_lshl_add_u64 v[174:175], s[62:63], 0, v[168:169]
	s_mov_b32 m0, s5
	s_nop 0
	global_load_lds_dwordx4 v[174:175], off
	s_waitcnt vmcnt(8)
	s_waitcnt lgkmcnt(0)
	s_setprio 1
	s_barrier
	v_mfma_f32_16x16x128_f8f6f4 v[158:161], v[18:25], v[190:197], 0
	v_mfma_f32_16x16x128_f8f6f4 v[154:157], v[26:33], v[190:197], 0
	v_mfma_f32_16x16x128_f8f6f4 v[146:149], v[26:33], v[198:205], 0
	v_mfma_f32_16x16x128_f8f6f4 v[150:153], v[18:25], v[198:205], 0
	v_mfma_f32_16x16x128_f8f6f4 v[142:145], v[18:25], v[206:213], 0
	v_mfma_f32_16x16x128_f8f6f4 v[138:141], v[26:33], v[206:213], 0
	v_mfma_f32_16x16x128_f8f6f4 v[130:133], v[26:33], v[214:221], 0
	v_mfma_f32_16x16x128_f8f6f4 v[134:137], v[18:25], v[214:221], 0
	s_setprio 0
	s_setprio 1
	v_mfma_f32_16x16x128_f8f6f4 v[102:105], v[2:9], v[214:221], 0
	v_mfma_f32_16x16x128_f8f6f4 v[98:101], v[10:17], v[214:221], 0
	v_mfma_f32_16x16x128_f8f6f4 v[106:109], v[10:17], v[206:213], 0
	v_mfma_f32_16x16x128_f8f6f4 v[110:113], v[2:9], v[206:213], 0
	v_mfma_f32_16x16x128_f8f6f4 v[118:121], v[2:9], v[198:205], 0
	v_mfma_f32_16x16x128_f8f6f4 v[114:117], v[10:17], v[198:205], 0
	s_barrier
	v_mfma_f32_16x16x128_f8f6f4 v[122:125], v[10:17], v[190:197], 0
	v_mfma_f32_16x16x128_f8f6f4 v[126:129], v[2:9], v[190:197], 0
	s_setprio 0
	v_lshl_add_u64 v[174:175], s[76:77], 0, v[162:163]
	s_mov_b32 m0, s9
	v_lshl_add_u64 v[176:177], v[174:175], 0, s[44:45]
	ds_read_b128 v[190:193], v187 offset:16384
	ds_read_b128 v[194:197], v187 offset:17408
	ds_read_b128 v[198:201], v187 offset:18432
	ds_read_b128 v[202:205], v187 offset:19456
	ds_read_b128 v[206:209], v187 offset:20480
	ds_read_b128 v[210:213], v187 offset:21504
	ds_read_b128 v[214:217], v187 offset:22528
	ds_read_b128 v[218:221], v187 offset:23552
	global_load_lds_dwordx4 v[176:177], off
	v_lshl_add_u64 v[176:177], s[76:77], 0, v[164:165]
	s_add_u32 s62, s76, 0x10100
	v_lshl_add_u64 v[182:183], v[176:177], 0, s[44:45]
	s_mov_b32 m0, s61
	s_addc_u32 s63, s77, 0
	global_load_lds_dwordx4 v[182:183], off
	v_lshl_add_u64 v[182:183], s[62:63], 0, v[162:163]
	s_mov_b32 m0, s68
	s_nop 0
	global_load_lds_dwordx4 v[182:183], off
	v_lshl_add_u64 v[182:183], s[62:63], 0, v[164:165]
	s_mov_b32 m0, s69
	s_nop 0
	global_load_lds_dwordx4 v[182:183], off
	v_lshl_add_u64 v[182:183], s[74:75], 0, v[166:167]
	v_lshl_add_u64 v[184:185], v[182:183], 0, s[44:45]
	s_mov_b32 m0, s8
	s_nop 0
	global_load_lds_dwordx4 v[184:185], off
	v_lshl_add_u64 v[184:185], s[74:75], 0, v[168:169]
	v_lshl_add_u64 v[222:223], v[184:185], 0, s[44:45]
	s_mov_b32 m0, s71
	s_nop 0
	global_load_lds_dwordx4 v[222:223], off
	s_waitcnt vmcnt(8)
	s_waitcnt lgkmcnt(0)
	s_setprio 1
	s_barrier
	v_mfma_f32_16x16x128_f8f6f4 v[94:97], v[18:25], v[190:197], 0
	v_mfma_f32_16x16x128_f8f6f4 v[90:93], v[26:33], v[190:197], 0
	v_mfma_f32_16x16x128_f8f6f4 v[82:85], v[26:33], v[198:205], 0
	v_mfma_f32_16x16x128_f8f6f4 v[86:89], v[18:25], v[198:205], 0
	v_mfma_f32_16x16x128_f8f6f4 v[78:81], v[18:25], v[206:213], 0
	v_mfma_f32_16x16x128_f8f6f4 v[74:77], v[26:33], v[206:213], 0
	v_mfma_f32_16x16x128_f8f6f4 v[66:69], v[26:33], v[214:221], 0
	v_mfma_f32_16x16x128_f8f6f4 v[70:73], v[18:25], v[214:221], 0
	s_setprio 0
	s_setprio 1
	v_mfma_f32_16x16x128_f8f6f4 v[38:41], v[2:9], v[214:221], 0
	v_mfma_f32_16x16x128_f8f6f4 v[34:37], v[10:17], v[214:221], 0
	v_mfma_f32_16x16x128_f8f6f4 v[42:45], v[10:17], v[206:213], 0
	v_mfma_f32_16x16x128_f8f6f4 v[46:49], v[2:9], v[206:213], 0
	v_mfma_f32_16x16x128_f8f6f4 v[54:57], v[2:9], v[198:205], 0
	v_mfma_f32_16x16x128_f8f6f4 v[50:53], v[10:17], v[198:205], 0
	s_barrier
	v_mfma_f32_16x16x128_f8f6f4 v[58:61], v[10:17], v[190:197], 0
	v_mfma_f32_16x16x128_f8f6f4 v[62:65], v[2:9], v[190:197], 0
	s_setprio 0
	ds_read_b128 v[2:5], v181 offset:32768
	ds_read_b128 v[6:9], v181 offset:33792
	ds_read_b128 v[10:13], v181 offset:34816
	ds_read_b128 v[14:17], v181 offset:35840
	ds_read_b128 v[18:21], v181 offset:49152
	ds_read_b128 v[22:25], v181 offset:50176
	ds_read_b128 v[26:29], v181 offset:51200
	ds_read_b128 v[30:33], v181 offset:52224
	s_add_u32 s62, s74, 0x40100
	s_addc_u32 s63, s75, 0
	s_mov_b32 m0, s73
	v_lshl_add_u64 v[222:223], s[62:63], 0, v[166:167]
	ds_read_b128 v[190:193], v187 offset:32768
	ds_read_b128 v[194:197], v187 offset:33792
	ds_read_b128 v[198:201], v187 offset:34816
	ds_read_b128 v[202:205], v187 offset:35840
	ds_read_b128 v[206:209], v187 offset:36864
	ds_read_b128 v[210:213], v187 offset:37888
	ds_read_b128 v[214:217], v187 offset:38912
	ds_read_b128 v[218:221], v187 offset:39936
	global_load_lds_dwordx4 v[222:223], off
	v_lshl_add_u64 v[222:223], s[62:63], 0, v[168:169]
	s_mov_b32 m0, s82
	s_nop 0
	global_load_lds_dwordx4 v[222:223], off
	s_waitcnt vmcnt(8)
	s_waitcnt lgkmcnt(0)
	s_setprio 1
	s_barrier
	v_mfma_f32_16x16x128_f8f6f4 v[158:161], v[2:9], v[190:197], v[158:161]
	v_mfma_f32_16x16x128_f8f6f4 v[154:157], v[10:17], v[190:197], v[154:157]
	v_mfma_f32_16x16x128_f8f6f4 v[146:149], v[10:17], v[198:205], v[146:149]
	v_mfma_f32_16x16x128_f8f6f4 v[150:153], v[2:9], v[198:205], v[150:153]
	v_mfma_f32_16x16x128_f8f6f4 v[142:145], v[2:9], v[206:213], v[142:145]
	v_mfma_f32_16x16x128_f8f6f4 v[138:141], v[10:17], v[206:213], v[138:141]
	v_mfma_f32_16x16x128_f8f6f4 v[130:133], v[10:17], v[214:221], v[130:133]
	v_mfma_f32_16x16x128_f8f6f4 v[134:137], v[2:9], v[214:221], v[134:137]
	s_setprio 0
	s_setprio 1
	v_mfma_f32_16x16x128_f8f6f4 v[102:105], v[18:25], v[214:221], v[102:105]
	v_mfma_f32_16x16x128_f8f6f4 v[98:101], v[26:33], v[214:221], v[98:101]
	v_mfma_f32_16x16x128_f8f6f4 v[106:109], v[26:33], v[206:213], v[106:109]
	v_mfma_f32_16x16x128_f8f6f4 v[110:113], v[18:25], v[206:213], v[110:113]
	v_mfma_f32_16x16x128_f8f6f4 v[118:121], v[18:25], v[198:205], v[118:121]
	v_mfma_f32_16x16x128_f8f6f4 v[114:117], v[26:33], v[198:205], v[114:117]
	s_barrier
	v_mfma_f32_16x16x128_f8f6f4 v[122:125], v[26:33], v[190:197], v[122:125]
	v_mfma_f32_16x16x128_f8f6f4 v[126:129], v[18:25], v[190:197], v[126:129]
	s_setprio 0
	s_mov_b32 m0, s83
	v_lshl_add_u64 v[174:175], v[174:175], 0, s[46:47]
	s_add_u32 s62, s76, 0x10180
	ds_read_b128 v[190:193], v187 offset:49152
	ds_read_b128 v[194:197], v187 offset:50176
	ds_read_b128 v[198:201], v187 offset:51200
	ds_read_b128 v[202:205], v187 offset:52224
	ds_read_b128 v[206:209], v187 offset:53248
	ds_read_b128 v[210:213], v187 offset:54272
	ds_read_b128 v[214:217], v187 offset:55296
	ds_read_b128 v[218:221], v187 offset:56320
	global_load_lds_dwordx4 v[174:175], off
	v_lshl_add_u64 v[174:175], v[176:177], 0, s[46:47]
	s_mov_b32 m0, s84
	s_addc_u32 s63, s77, 0
	global_load_lds_dwordx4 v[174:175], off
	v_lshl_add_u64 v[174:175], s[62:63], 0, v[162:163]
	s_mov_b32 m0, s87
	s_nop 0
	global_load_lds_dwordx4 v[174:175], off
	v_lshl_add_u64 v[174:175], s[62:63], 0, v[164:165]
	s_mov_b32 m0, s88
	s_nop 0
	global_load_lds_dwordx4 v[174:175], off
	v_lshl_add_u64 v[174:175], v[182:183], 0, s[46:47]
	s_mov_b32 m0, s85
	s_nop 0
	global_load_lds_dwordx4 v[174:175], off
	v_lshl_add_u64 v[174:175], v[184:185], 0, s[46:47]
	s_mov_b32 m0, s86
	s_nop 0
	global_load_lds_dwordx4 v[174:175], off
	s_waitcnt vmcnt(8)
	s_waitcnt lgkmcnt(0)
	s_setprio 1
	s_barrier
	v_mfma_f32_16x16x128_f8f6f4 v[94:97], v[2:9], v[190:197], v[94:97]
	v_mfma_f32_16x16x128_f8f6f4 v[90:93], v[10:17], v[190:197], v[90:93]
	v_mfma_f32_16x16x128_f8f6f4 v[82:85], v[10:17], v[198:205], v[82:85]
	v_mfma_f32_16x16x128_f8f6f4 v[86:89], v[2:9], v[198:205], v[86:89]
	v_mfma_f32_16x16x128_f8f6f4 v[78:81], v[2:9], v[206:213], v[78:81]
	v_mfma_f32_16x16x128_f8f6f4 v[74:77], v[10:17], v[206:213], v[74:77]
	v_mfma_f32_16x16x128_f8f6f4 v[66:69], v[10:17], v[214:221], v[66:69]
	v_mfma_f32_16x16x128_f8f6f4 v[70:73], v[2:9], v[214:221], v[70:73]
	s_setprio 0
	s_setprio 1
	v_mfma_f32_16x16x128_f8f6f4 v[38:41], v[18:25], v[214:221], v[38:41]
	v_mfma_f32_16x16x128_f8f6f4 v[34:37], v[26:33], v[214:221], v[34:37]
	v_mfma_f32_16x16x128_f8f6f4 v[42:45], v[26:33], v[206:213], v[42:45]
	v_mfma_f32_16x16x128_f8f6f4 v[46:49], v[18:25], v[206:213], v[46:49]
	v_mfma_f32_16x16x128_f8f6f4 v[54:57], v[18:25], v[198:205], v[54:57]
	v_mfma_f32_16x16x128_f8f6f4 v[50:53], v[26:33], v[198:205], v[50:53]
	s_barrier
	v_mfma_f32_16x16x128_f8f6f4 v[58:61], v[26:33], v[190:197], v[58:61]
	v_mfma_f32_16x16x128_f8f6f4 v[62:65], v[18:25], v[190:197], v[62:65]
	s_setprio 0
	ds_read_b128 v[2:5], v181
	ds_read_b128 v[6:9], v181 offset:1024
	ds_read_b128 v[10:13], v181 offset:2048
	ds_read_b128 v[14:17], v181 offset:3072
	ds_read_b128 v[18:21], v181 offset:16384
	ds_read_b128 v[22:25], v181 offset:17408
	ds_read_b128 v[26:29], v181 offset:18432
	ds_read_b128 v[30:33], v181 offset:19456
	s_add_u32 s62, s74, 0x40180
	s_addc_u32 s63, s75, 0
	s_mov_b32 m0, s33
	v_lshl_add_u64 v[174:175], s[62:63], 0, v[166:167]
	ds_read_b128 v[190:193], v187
	ds_read_b128 v[194:197], v187 offset:1024
	ds_read_b128 v[198:201], v187 offset:2048
	ds_read_b128 v[202:205], v187 offset:3072
	ds_read_b128 v[206:209], v187 offset:4096
	ds_read_b128 v[210:213], v187 offset:5120
	ds_read_b128 v[214:217], v187 offset:6144
	ds_read_b128 v[218:221], v187 offset:7168
	global_load_lds_dwordx4 v[174:175], off
	v_lshl_add_u64 v[174:175], s[62:63], 0, v[168:169]
	s_mov_b32 m0, s5
	s_nop 0
	global_load_lds_dwordx4 v[174:175], off
	s_waitcnt vmcnt(8)
	s_waitcnt lgkmcnt(0)
	s_setprio 1
	s_barrier
	v_mfma_f32_16x16x128_f8f6f4 v[158:161], v[2:9], v[190:197], v[158:161]
	v_mfma_f32_16x16x128_f8f6f4 v[154:157], v[10:17], v[190:197], v[154:157]
	v_mfma_f32_16x16x128_f8f6f4 v[146:149], v[10:17], v[198:205], v[146:149]
	v_mfma_f32_16x16x128_f8f6f4 v[150:153], v[2:9], v[198:205], v[150:153]
	v_mfma_f32_16x16x128_f8f6f4 v[142:145], v[2:9], v[206:213], v[142:145]
	v_mfma_f32_16x16x128_f8f6f4 v[138:141], v[10:17], v[206:213], v[138:141]
	v_mfma_f32_16x16x128_f8f6f4 v[130:133], v[10:17], v[214:221], v[130:133]
	v_mfma_f32_16x16x128_f8f6f4 v[134:137], v[2:9], v[214:221], v[134:137]
	s_setprio 0
	s_setprio 1
	v_mfma_f32_16x16x128_f8f6f4 v[102:105], v[18:25], v[214:221], v[102:105]
	v_mfma_f32_16x16x128_f8f6f4 v[98:101], v[26:33], v[214:221], v[98:101]
	v_mfma_f32_16x16x128_f8f6f4 v[106:109], v[26:33], v[206:213], v[106:109]
	v_mfma_f32_16x16x128_f8f6f4 v[110:113], v[18:25], v[206:213], v[110:113]
	v_mfma_f32_16x16x128_f8f6f4 v[118:121], v[18:25], v[198:205], v[118:121]
	v_mfma_f32_16x16x128_f8f6f4 v[114:117], v[26:33], v[198:205], v[114:117]
	s_barrier
	v_mfma_f32_16x16x128_f8f6f4 v[122:125], v[26:33], v[190:197], v[122:125]
	v_mfma_f32_16x16x128_f8f6f4 v[126:129], v[18:25], v[190:197], v[126:129]
	s_setprio 0
	s_mov_b32 m0, s9
	v_lshl_add_u64 v[174:175], s[78:79], 0, v[162:163]
	s_add_u32 s62, s78, 0x10000
	ds_read_b128 v[190:193], v187 offset:16384
	ds_read_b128 v[194:197], v187 offset:17408
	ds_read_b128 v[198:201], v187 offset:18432
	ds_read_b128 v[202:205], v187 offset:19456
	ds_read_b128 v[206:209], v187 offset:20480
	ds_read_b128 v[210:213], v187 offset:21504
	ds_read_b128 v[214:217], v187 offset:22528
	ds_read_b128 v[218:221], v187 offset:23552
	global_load_lds_dwordx4 v[174:175], off
	v_lshl_add_u64 v[176:177], s[78:79], 0, v[164:165]
	s_mov_b32 m0, s61
	s_addc_u32 s63, s79, 0
	global_load_lds_dwordx4 v[176:177], off
	v_lshl_add_u64 v[182:183], s[62:63], 0, v[162:163]
	s_mov_b32 m0, s68
	v_lshl_add_u64 v[184:185], s[80:81], 0, v[168:169]
	global_load_lds_dwordx4 v[182:183], off
	v_lshl_add_u64 v[182:183], s[62:63], 0, v[164:165]
	s_mov_b32 m0, s69
	s_nop 0
	global_load_lds_dwordx4 v[182:183], off
	v_lshl_add_u64 v[182:183], s[80:81], 0, v[166:167]
	s_mov_b32 m0, s8
	s_nop 0
	global_load_lds_dwordx4 v[182:183], off
	s_mov_b32 m0, s71
	s_nop 0
	global_load_lds_dwordx4 v[184:185], off
	s_waitcnt vmcnt(8)
	s_waitcnt lgkmcnt(0)
	s_setprio 1
	s_barrier
	v_mfma_f32_16x16x128_f8f6f4 v[94:97], v[2:9], v[190:197], v[94:97]
	v_mfma_f32_16x16x128_f8f6f4 v[90:93], v[10:17], v[190:197], v[90:93]
	v_mfma_f32_16x16x128_f8f6f4 v[82:85], v[10:17], v[198:205], v[82:85]
	v_mfma_f32_16x16x128_f8f6f4 v[86:89], v[2:9], v[198:205], v[86:89]
	v_mfma_f32_16x16x128_f8f6f4 v[78:81], v[2:9], v[206:213], v[78:81]
	v_mfma_f32_16x16x128_f8f6f4 v[74:77], v[10:17], v[206:213], v[74:77]
	v_mfma_f32_16x16x128_f8f6f4 v[66:69], v[10:17], v[214:221], v[66:69]
	v_mfma_f32_16x16x128_f8f6f4 v[70:73], v[2:9], v[214:221], v[70:73]
	s_setprio 0
	s_setprio 1
	v_mfma_f32_16x16x128_f8f6f4 v[38:41], v[18:25], v[214:221], v[38:41]
	v_mfma_f32_16x16x128_f8f6f4 v[34:37], v[26:33], v[214:221], v[34:37]
	v_mfma_f32_16x16x128_f8f6f4 v[42:45], v[26:33], v[206:213], v[42:45]
	v_mfma_f32_16x16x128_f8f6f4 v[46:49], v[18:25], v[206:213], v[46:49]
	v_mfma_f32_16x16x128_f8f6f4 v[54:57], v[18:25], v[198:205], v[54:57]
	v_mfma_f32_16x16x128_f8f6f4 v[50:53], v[26:33], v[198:205], v[50:53]
	s_barrier
	v_mfma_f32_16x16x128_f8f6f4 v[58:61], v[26:33], v[190:197], v[58:61]
	v_mfma_f32_16x16x128_f8f6f4 v[62:65], v[18:25], v[190:197], v[62:65]
	s_setprio 0
	ds_read_b128 v[2:5], v181 offset:32768
	ds_read_b128 v[6:9], v181 offset:33792
	ds_read_b128 v[10:13], v181 offset:34816
	ds_read_b128 v[14:17], v181 offset:35840
	ds_read_b128 v[18:21], v181 offset:49152
	ds_read_b128 v[22:25], v181 offset:50176
	ds_read_b128 v[26:29], v181 offset:51200
	ds_read_b128 v[30:33], v181 offset:52224
	s_add_u32 s62, s80, 0x40000
	s_addc_u32 s63, s81, 0
	s_mov_b32 m0, s73
	v_lshl_add_u64 v[222:223], s[62:63], 0, v[166:167]
	ds_read_b128 v[190:193], v187 offset:32768
	ds_read_b128 v[194:197], v187 offset:33792
	ds_read_b128 v[198:201], v187 offset:34816
	ds_read_b128 v[202:205], v187 offset:35840
	ds_read_b128 v[206:209], v187 offset:36864
	ds_read_b128 v[210:213], v187 offset:37888
	ds_read_b128 v[214:217], v187 offset:38912
	ds_read_b128 v[218:221], v187 offset:39936
	global_load_lds_dwordx4 v[222:223], off
	v_lshl_add_u64 v[222:223], s[62:63], 0, v[168:169]
	s_mov_b32 m0, s82
	s_nop 0
	global_load_lds_dwordx4 v[222:223], off
	s_waitcnt vmcnt(8)
	s_waitcnt lgkmcnt(0)
	s_setprio 1
	s_barrier
	v_mfma_f32_16x16x128_f8f6f4 v[158:161], v[2:9], v[190:197], v[158:161]
	v_mfma_f32_16x16x128_f8f6f4 v[154:157], v[10:17], v[190:197], v[154:157]
	v_mfma_f32_16x16x128_f8f6f4 v[146:149], v[10:17], v[198:205], v[146:149]
	v_mfma_f32_16x16x128_f8f6f4 v[150:153], v[2:9], v[198:205], v[150:153]
	v_mfma_f32_16x16x128_f8f6f4 v[142:145], v[2:9], v[206:213], v[142:145]
	v_mfma_f32_16x16x128_f8f6f4 v[138:141], v[10:17], v[206:213], v[138:141]
	v_mfma_f32_16x16x128_f8f6f4 v[130:133], v[10:17], v[214:221], v[130:133]
	v_mfma_f32_16x16x128_f8f6f4 v[134:137], v[2:9], v[214:221], v[134:137]
	s_setprio 0
	s_setprio 1
	v_mfma_f32_16x16x128_f8f6f4 v[102:105], v[18:25], v[214:221], v[102:105]
	v_mfma_f32_16x16x128_f8f6f4 v[98:101], v[26:33], v[214:221], v[98:101]
	v_mfma_f32_16x16x128_f8f6f4 v[106:109], v[26:33], v[206:213], v[106:109]
	v_mfma_f32_16x16x128_f8f6f4 v[110:113], v[18:25], v[206:213], v[110:113]
	v_mfma_f32_16x16x128_f8f6f4 v[118:121], v[18:25], v[198:205], v[118:121]
	v_mfma_f32_16x16x128_f8f6f4 v[114:117], v[26:33], v[198:205], v[114:117]
	s_barrier
	v_mfma_f32_16x16x128_f8f6f4 v[122:125], v[26:33], v[190:197], v[122:125]
	v_mfma_f32_16x16x128_f8f6f4 v[126:129], v[18:25], v[190:197], v[126:129]
	s_setprio 0
	s_mov_b32 m0, s83
	v_lshl_add_u64 v[174:175], v[174:175], 0, s[38:39]
	s_add_u32 s62, s78, 0x10080
	ds_read_b128 v[190:193], v187 offset:49152
	ds_read_b128 v[194:197], v187 offset:50176
	ds_read_b128 v[198:201], v187 offset:51200
	ds_read_b128 v[202:205], v187 offset:52224
	ds_read_b128 v[206:209], v187 offset:53248
	ds_read_b128 v[210:213], v187 offset:54272
	ds_read_b128 v[214:217], v187 offset:55296
	ds_read_b128 v[218:221], v187 offset:56320
	global_load_lds_dwordx4 v[174:175], off
	v_lshl_add_u64 v[174:175], v[176:177], 0, s[38:39]
	s_mov_b32 m0, s84
	s_addc_u32 s63, s79, 0
	global_load_lds_dwordx4 v[174:175], off
	v_lshl_add_u64 v[174:175], s[62:63], 0, v[162:163]
	s_mov_b32 m0, s87
	s_nop 0
	global_load_lds_dwordx4 v[174:175], off
	v_lshl_add_u64 v[174:175], s[62:63], 0, v[164:165]
	s_mov_b32 m0, s88
	s_nop 0
	global_load_lds_dwordx4 v[174:175], off
	v_lshl_add_u64 v[174:175], v[182:183], 0, s[38:39]
	s_mov_b32 m0, s85
	s_nop 0
	global_load_lds_dwordx4 v[174:175], off
	v_lshl_add_u64 v[174:175], v[184:185], 0, s[38:39]
	s_mov_b32 m0, s86
	s_nop 0
	global_load_lds_dwordx4 v[174:175], off
	s_waitcnt vmcnt(8)
	s_waitcnt lgkmcnt(0)
	s_setprio 1
	s_barrier
	v_mfma_f32_16x16x128_f8f6f4 v[94:97], v[2:9], v[190:197], v[94:97]
	v_mfma_f32_16x16x128_f8f6f4 v[90:93], v[10:17], v[190:197], v[90:93]
	v_mfma_f32_16x16x128_f8f6f4 v[82:85], v[10:17], v[198:205], v[82:85]
	v_mfma_f32_16x16x128_f8f6f4 v[86:89], v[2:9], v[198:205], v[86:89]
	v_mfma_f32_16x16x128_f8f6f4 v[78:81], v[2:9], v[206:213], v[78:81]
	v_mfma_f32_16x16x128_f8f6f4 v[74:77], v[10:17], v[206:213], v[74:77]
	v_mfma_f32_16x16x128_f8f6f4 v[66:69], v[10:17], v[214:221], v[66:69]
	v_mfma_f32_16x16x128_f8f6f4 v[70:73], v[2:9], v[214:221], v[70:73]
	s_setprio 0
	s_setprio 1
	v_mfma_f32_16x16x128_f8f6f4 v[38:41], v[18:25], v[214:221], v[38:41]
	v_mfma_f32_16x16x128_f8f6f4 v[34:37], v[26:33], v[214:221], v[34:37]
	v_mfma_f32_16x16x128_f8f6f4 v[42:45], v[26:33], v[206:213], v[42:45]
	v_mfma_f32_16x16x128_f8f6f4 v[46:49], v[18:25], v[206:213], v[46:49]
	v_mfma_f32_16x16x128_f8f6f4 v[54:57], v[18:25], v[198:205], v[54:57]
	v_mfma_f32_16x16x128_f8f6f4 v[50:53], v[26:33], v[198:205], v[50:53]
	s_barrier
	v_mfma_f32_16x16x128_f8f6f4 v[58:61], v[26:33], v[190:197], v[58:61]
	v_mfma_f32_16x16x128_f8f6f4 v[62:65], v[18:25], v[190:197], v[62:65]
	s_setprio 0
	s_andn2_b64 vcc, exec, s[40:41]
	s_cbranch_vccnz .LBB0_632
	s_barrier

.LBB0_791:
	ds_read_b128 v[2:5], v189
	ds_read_b128 v[6:9], v189 offset:1024
	ds_read_b128 v[192:195], v189 offset:2048
	ds_read_b128 v[196:199], v189 offset:3072
	ds_read_b128 v[200:203], v189 offset:16384
	ds_read_b128 v[204:207], v189 offset:17408
	ds_read_b128 v[208:211], v189 offset:18432
	ds_read_b128 v[212:215], v189 offset:19456
	s_add_u32 s37, s46, 0x100
	s_addc_u32 s39, s47, 0
	s_and_b64 s[50:51], s[48:49], exec
	s_cselect_b32 s51, s1, s39
	s_cselect_b32 s50, s0, s37
	s_add_u32 s37, s44, 0x100
	s_addc_u32 s39, s45, 0
	s_and_b64 s[48:49], s[48:49], exec
	s_cselect_b32 s49, s5, s39
	s_cselect_b32 s48, s4, s37
	s_add_u32 s88, s46, 0x80080
	s_addc_u32 s89, s47, 0
	s_add_i32 s37, s8, 0xc000
	v_lshl_add_u64 v[174:175], s[88:89], 0, v[154:155]
	s_mov_b32 m0, s37
	s_add_i32 s39, s8, 0xe000
	ds_read_b128 v[216:219], v190
	ds_read_b128 v[220:223], v190 offset:1024
	ds_read_b128 v[224:227], v190 offset:2048
	ds_read_b128 v[228:231], v190 offset:3072
	ds_read_b128 v[242:245], v190 offset:4096
	ds_read_b128 v[246:249], v190 offset:5120
	ds_read_b128 v[232:235], v190 offset:6144
	ds_read_b128 v[236:239], v190 offset:7168
	global_load_lds_dwordx4 v[174:175], off
	v_lshl_add_u64 v[174:175], s[88:89], 0, v[158:159]
	s_mov_b32 m0, s39
	s_nop 0
	global_load_lds_dwordx4 v[174:175], off
	s_waitcnt vmcnt(8)
	s_waitcnt lgkmcnt(0)
	s_setprio 1
	s_barrier
	v_mfma_f32_16x16x128_f8f6f4 v[134:137], v[2:9], v[216:223], 0
	v_mfma_f32_16x16x128_f8f6f4 v[130:133], v[192:199], v[216:223], 0
	v_mfma_f32_16x16x128_f8f6f4 v[122:125], v[192:199], v[224:231], 0
	v_mfma_f32_16x16x128_f8f6f4 v[126:129], v[2:9], v[224:231], 0
	v_mfma_f32_16x16x128_f8f6f4 v[118:121], v[2:9], v[242:249], 0
	v_mfma_f32_16x16x128_f8f6f4 v[114:117], v[192:199], v[242:249], 0
	v_mfma_f32_16x16x128_f8f6f4 v[106:109], v[192:199], v[232:239], 0
	v_mfma_f32_16x16x128_f8f6f4 v[110:113], v[2:9], v[232:239], 0
	s_setprio 0
	s_setprio 1
	v_mfma_f32_16x16x128_f8f6f4 v[78:81], v[200:207], v[232:239], 0
	v_mfma_f32_16x16x128_f8f6f4 v[74:77], v[208:215], v[232:239], 0
	v_mfma_f32_16x16x128_f8f6f4 v[82:85], v[208:215], v[242:249], 0
	v_mfma_f32_16x16x128_f8f6f4 v[86:89], v[200:207], v[242:249], 0
	v_mfma_f32_16x16x128_f8f6f4 v[94:97], v[200:207], v[224:231], 0
	v_mfma_f32_16x16x128_f8f6f4 v[90:93], v[208:215], v[224:231], 0
	s_barrier
	v_mfma_f32_16x16x128_f8f6f4 v[98:101], v[208:215], v[216:223], 0
	v_mfma_f32_16x16x128_f8f6f4 v[102:105], v[200:207], v[216:223], 0
	s_setprio 0
	s_mov_b32 m0, s9
	v_lshl_add_u64 v[174:175], s[48:49], 0, v[156:157]
	s_add_u32 s88, s48, 0x80000
	ds_read_b128 v[216:219], v190 offset:16384
	ds_read_b128 v[220:223], v190 offset:17408
	ds_read_b128 v[224:227], v190 offset:18432
	ds_read_b128 v[228:231], v190 offset:19456
	ds_read_b128 v[232:235], v190 offset:20480
	ds_read_b128 v[236:239], v190 offset:21504
	ds_read_b128 v[242:245], v190 offset:22528
	ds_read_b128 v[246:249], v190 offset:23552
	global_load_lds_dwordx4 v[174:175], off
	v_lshl_add_u64 v[176:177], s[48:49], 0, v[160:161]
	s_mov_b32 m0, s27
	s_addc_u32 s89, s49, 0
	global_load_lds_dwordx4 v[176:177], off
	v_lshl_add_u64 v[182:183], s[88:89], 0, v[156:157]
	s_mov_b32 m0, s33
	v_lshl_add_u64 v[184:185], s[50:51], 0, v[158:159]
	global_load_lds_dwordx4 v[182:183], off
	v_lshl_add_u64 v[182:183], s[88:89], 0, v[160:161]
	s_mov_b32 m0, s35
	s_nop 0
	global_load_lds_dwordx4 v[182:183], off
	v_lshl_add_u64 v[182:183], s[50:51], 0, v[154:155]
	s_mov_b32 m0, s8
	s_nop 0
	global_load_lds_dwordx4 v[182:183], off
	s_mov_b32 m0, s43
	s_nop 0
	global_load_lds_dwordx4 v[184:185], off
	s_waitcnt vmcnt(8)
	s_waitcnt lgkmcnt(0)
	s_setprio 1
	s_barrier
	v_mfma_f32_16x16x128_f8f6f4 v[70:73], v[2:9], v[216:223], 0
	v_mfma_f32_16x16x128_f8f6f4 v[66:69], v[192:199], v[216:223], 0
	v_mfma_f32_16x16x128_f8f6f4 v[58:61], v[192:199], v[224:231], 0
	v_mfma_f32_16x16x128_f8f6f4 v[62:65], v[2:9], v[224:231], 0
	v_mfma_f32_16x16x128_f8f6f4 v[54:57], v[2:9], v[232:239], 0
	v_mfma_f32_16x16x128_f8f6f4 v[50:53], v[192:199], v[232:239], 0
	v_mfma_f32_16x16x128_f8f6f4 v[42:45], v[192:199], v[242:249], 0
	v_mfma_f32_16x16x128_f8f6f4 v[46:49], v[2:9], v[242:249], 0
	s_setprio 0
	s_setprio 1
	v_mfma_f32_16x16x128_f8f6f4 v[14:17], v[200:207], v[242:249], 0
	v_mfma_f32_16x16x128_f8f6f4 v[10:13], v[208:215], v[242:249], 0
	v_mfma_f32_16x16x128_f8f6f4 v[18:21], v[208:215], v[232:239], 0
	v_mfma_f32_16x16x128_f8f6f4 v[22:25], v[200:207], v[232:239], 0
	v_mfma_f32_16x16x128_f8f6f4 v[30:33], v[200:207], v[224:231], 0
	v_mfma_f32_16x16x128_f8f6f4 v[26:29], v[208:215], v[224:231], 0
	s_barrier
	v_mfma_f32_16x16x128_f8f6f4 v[34:37], v[208:215], v[216:223], 0
	v_mfma_f32_16x16x128_f8f6f4 v[38:41], v[200:207], v[216:223], 0
	s_setprio 0
	ds_read_b128 v[2:5], v189 offset:32768
	ds_read_b128 v[6:9], v189 offset:33792
	ds_read_b128 v[192:195], v189 offset:34816
	ds_read_b128 v[196:199], v189 offset:35840
	ds_read_b128 v[200:203], v189 offset:49152
	ds_read_b128 v[204:207], v189 offset:50176
	ds_read_b128 v[208:211], v189 offset:51200
	ds_read_b128 v[212:215], v189 offset:52224
	s_add_u32 s50, s50, 0x80000
	s_addc_u32 s51, s51, 0
	s_mov_b32 m0, s52
	v_lshl_add_u64 v[186:187], s[50:51], 0, v[154:155]
	ds_read_b128 v[216:219], v190 offset:32768
	ds_read_b128 v[220:223], v190 offset:33792
	ds_read_b128 v[224:227], v190 offset:34816
	ds_read_b128 v[228:231], v190 offset:35840
	ds_read_b128 v[232:235], v190 offset:36864
	ds_read_b128 v[236:239], v190 offset:37888
	ds_read_b128 v[242:245], v190 offset:38912
	ds_read_b128 v[246:249], v190 offset:39936
	global_load_lds_dwordx4 v[186:187], off
	v_lshl_add_u64 v[186:187], s[50:51], 0, v[158:159]
	s_mov_b32 m0, s53
	s_nop 0
	global_load_lds_dwordx4 v[186:187], off
	s_waitcnt vmcnt(8)
	s_waitcnt lgkmcnt(0)
	s_setprio 1
	s_barrier
	v_mfma_f32_16x16x128_f8f6f4 v[134:137], v[2:9], v[216:223], v[134:137]
	v_mfma_f32_16x16x128_f8f6f4 v[130:133], v[192:199], v[216:223], v[130:133]
	v_mfma_f32_16x16x128_f8f6f4 v[122:125], v[192:199], v[224:231], v[122:125]
	v_mfma_f32_16x16x128_f8f6f4 v[126:129], v[2:9], v[224:231], v[126:129]
	v_mfma_f32_16x16x128_f8f6f4 v[118:121], v[2:9], v[232:239], v[118:121]
	v_mfma_f32_16x16x128_f8f6f4 v[114:117], v[192:199], v[232:239], v[114:117]
	v_mfma_f32_16x16x128_f8f6f4 v[106:109], v[192:199], v[242:249], v[106:109]
	v_mfma_f32_16x16x128_f8f6f4 v[110:113], v[2:9], v[242:249], v[110:113]
	s_setprio 0
	s_setprio 1
	v_mfma_f32_16x16x128_f8f6f4 v[78:81], v[200:207], v[242:249], v[78:81]
	v_mfma_f32_16x16x128_f8f6f4 v[74:77], v[208:215], v[242:249], v[74:77]
	v_mfma_f32_16x16x128_f8f6f4 v[82:85], v[208:215], v[232:239], v[82:85]
	v_mfma_f32_16x16x128_f8f6f4 v[86:89], v[200:207], v[232:239], v[86:89]
	v_mfma_f32_16x16x128_f8f6f4 v[94:97], v[200:207], v[224:231], v[94:97]
	v_mfma_f32_16x16x128_f8f6f4 v[90:93], v[208:215], v[224:231], v[90:93]
	s_barrier
	v_mfma_f32_16x16x128_f8f6f4 v[98:101], v[208:215], v[216:223], v[98:101]
	v_mfma_f32_16x16x128_f8f6f4 v[102:105], v[200:207], v[216:223], v[102:105]
	s_setprio 0
	s_mov_b32 m0, s70
	v_lshl_add_u64 v[174:175], v[174:175], 0, s[18:19]
	s_add_u32 s48, s48, 0x80080
	ds_read_b128 v[216:219], v190 offset:49152
	ds_read_b128 v[220:223], v190 offset:50176
	ds_read_b128 v[224:227], v190 offset:51200
	ds_read_b128 v[228:231], v190 offset:52224
	ds_read_b128 v[232:235], v190 offset:53248
	ds_read_b128 v[236:239], v190 offset:54272
	ds_read_b128 v[242:245], v190 offset:55296
	ds_read_b128 v[246:249], v190 offset:56320
	global_load_lds_dwordx4 v[174:175], off
	v_lshl_add_u64 v[174:175], v[176:177], 0, s[18:19]
	s_mov_b32 m0, s71
	s_addc_u32 s49, s49, 0
	global_load_lds_dwordx4 v[174:175], off
	v_lshl_add_u64 v[174:175], s[48:49], 0, v[156:157]
	s_mov_b32 m0, s74
	s_nop 0
	global_load_lds_dwordx4 v[174:175], off
	v_lshl_add_u64 v[174:175], s[48:49], 0, v[160:161]
	s_mov_b32 m0, s75
	s_nop 0
	global_load_lds_dwordx4 v[174:175], off
	v_lshl_add_u64 v[174:175], v[182:183], 0, s[18:19]
	s_mov_b32 m0, s72
	s_nop 0
	global_load_lds_dwordx4 v[174:175], off
	v_lshl_add_u64 v[174:175], v[184:185], 0, s[18:19]
	s_mov_b32 m0, s73
	s_nop 0
	global_load_lds_dwordx4 v[174:175], off
	s_waitcnt vmcnt(8)
	s_waitcnt lgkmcnt(0)
	s_setprio 1
	s_barrier
	v_mfma_f32_16x16x128_f8f6f4 v[70:73], v[2:9], v[216:223], v[70:73]
	v_mfma_f32_16x16x128_f8f6f4 v[66:69], v[192:199], v[216:223], v[66:69]
	v_mfma_f32_16x16x128_f8f6f4 v[58:61], v[192:199], v[224:231], v[58:61]
	v_mfma_f32_16x16x128_f8f6f4 v[62:65], v[2:9], v[224:231], v[62:65]
	v_mfma_f32_16x16x128_f8f6f4 v[54:57], v[2:9], v[232:239], v[54:57]
	v_mfma_f32_16x16x128_f8f6f4 v[50:53], v[192:199], v[232:239], v[50:53]
	v_mfma_f32_16x16x128_f8f6f4 v[42:45], v[192:199], v[242:249], v[42:45]
	v_mfma_f32_16x16x128_f8f6f4 v[46:49], v[2:9], v[242:249], v[46:49]
	s_setprio 0
	s_setprio 1
	v_mfma_f32_16x16x128_f8f6f4 v[14:17], v[200:207], v[242:249], v[14:17]
	v_mfma_f32_16x16x128_f8f6f4 v[10:13], v[208:215], v[242:249], v[10:13]
	v_mfma_f32_16x16x128_f8f6f4 v[18:21], v[208:215], v[232:239], v[18:21]
	v_mfma_f32_16x16x128_f8f6f4 v[22:25], v[200:207], v[232:239], v[22:25]
	v_mfma_f32_16x16x128_f8f6f4 v[30:33], v[200:207], v[224:231], v[30:33]
	v_mfma_f32_16x16x128_f8f6f4 v[26:29], v[208:215], v[224:231], v[26:29]
	s_barrier
	v_mfma_f32_16x16x128_f8f6f4 v[34:37], v[208:215], v[216:223], v[34:37]
	v_mfma_f32_16x16x128_f8f6f4 v[38:41], v[200:207], v[216:223], v[38:41]
	s_setprio 0
	s_cmp_lt_u32 s86, 3
	s_cbranch_scc1 .LBB0_796
	s_add_u32 s48, s55, s62
	s_addc_u32 s49, s61, s41
	s_add_u32 s46, s46, 0x80180
	s_addc_u32 s47, s47, 0
	s_add_u32 s41, s44, 0x200
	v_lshl_add_u64 v[174:175], v[172:173], 2, s[48:49]
	s_addc_u32 s50, s45, 0
	s_mov_b32 s51, 4
	s_cmp_eq_u32 s86, s51
	s_cselect_b64 s[44:45], -1, 0
	s_cmp_lg_u32 s86, s51
	s_cbranch_scc1 .LBB0_794

.LBB0_794:
	ds_read_b128 v[2:5], v189
	ds_read_b128 v[6:9], v189 offset:1024
	ds_read_b128 v[192:195], v189 offset:2048
	ds_read_b128 v[196:199], v189 offset:3072
	ds_read_b128 v[200:203], v189 offset:16384
	ds_read_b128 v[204:207], v189 offset:17408
	ds_read_b128 v[208:211], v189 offset:18432
	ds_read_b128 v[212:215], v189 offset:19456
	s_add_u32 s48, s46, 0xfff80080
	s_addc_u32 s49, s47, -1
	s_and_b64 s[44:45], s[44:45], exec
	s_cselect_b32 s44, s4, s41
	s_cselect_b32 s49, s1, s49
	s_cselect_b32 s48, s0, s48
	s_cselect_b32 s45, s5, s50
	s_mov_b32 m0, s37
	v_lshl_add_u64 v[176:177], s[46:47], 0, v[162:163]
	ds_read_b128 v[216:219], v190
	ds_read_b128 v[220:223], v190 offset:1024
	ds_read_b128 v[224:227], v190 offset:2048
	ds_read_b128 v[228:231], v190 offset:3072
	ds_read_b128 v[232:235], v190 offset:4096
	ds_read_b128 v[236:239], v190 offset:5120
	ds_read_b128 v[242:245], v190 offset:6144
	ds_read_b128 v[246:249], v190 offset:7168
	global_load_lds_dwordx4 v[176:177], off
	v_lshl_add_u64 v[176:177], s[46:47], 0, v[164:165]
	s_mov_b32 m0, s39
	s_nop 0
	global_load_lds_dwordx4 v[176:177], off
	s_waitcnt vmcnt(8)
	s_waitcnt lgkmcnt(0)
	s_setprio 1
	s_barrier
	v_mfma_f32_16x16x128_f8f6f4 v[134:137], v[2:9], v[216:223], v[134:137]
	v_mfma_f32_16x16x128_f8f6f4 v[130:133], v[192:199], v[216:223], v[130:133]
	v_mfma_f32_16x16x128_f8f6f4 v[122:125], v[192:199], v[224:231], v[122:125]
	v_mfma_f32_16x16x128_f8f6f4 v[126:129], v[2:9], v[224:231], v[126:129]
	v_mfma_f32_16x16x128_f8f6f4 v[118:121], v[2:9], v[232:239], v[118:121]
	v_mfma_f32_16x16x128_f8f6f4 v[114:117], v[192:199], v[232:239], v[114:117]
	v_mfma_f32_16x16x128_f8f6f4 v[106:109], v[192:199], v[242:249], v[106:109]
	v_mfma_f32_16x16x128_f8f6f4 v[110:113], v[2:9], v[242:249], v[110:113]
	s_setprio 0
	s_setprio 1
	v_mfma_f32_16x16x128_f8f6f4 v[78:81], v[200:207], v[242:249], v[78:81]
	v_mfma_f32_16x16x128_f8f6f4 v[74:77], v[208:215], v[242:249], v[74:77]
	v_mfma_f32_16x16x128_f8f6f4 v[82:85], v[208:215], v[232:239], v[82:85]
	v_mfma_f32_16x16x128_f8f6f4 v[86:89], v[200:207], v[232:239], v[86:89]
	v_mfma_f32_16x16x128_f8f6f4 v[94:97], v[200:207], v[224:231], v[94:97]
	v_mfma_f32_16x16x128_f8f6f4 v[90:93], v[208:215], v[224:231], v[90:93]
	s_barrier
	v_mfma_f32_16x16x128_f8f6f4 v[98:101], v[208:215], v[216:223], v[98:101]
	v_mfma_f32_16x16x128_f8f6f4 v[102:105], v[200:207], v[216:223], v[102:105]
	s_setprio 0
	s_mov_b32 m0, s9
	v_lshl_add_u64 v[176:177], s[44:45], 0, v[156:157]
	s_add_u32 s62, s44, 0x80000
	ds_read_b128 v[216:219], v190 offset:16384
	ds_read_b128 v[220:223], v190 offset:17408
	ds_read_b128 v[224:227], v190 offset:18432
	ds_read_b128 v[228:231], v190 offset:19456
	ds_read_b128 v[232:235], v190 offset:20480
	ds_read_b128 v[236:239], v190 offset:21504
	ds_read_b128 v[242:245], v190 offset:22528
	ds_read_b128 v[246:249], v190 offset:23552
	global_load_lds_dwordx4 v[176:177], off
	v_lshl_add_u64 v[182:183], s[44:45], 0, v[160:161]
	s_mov_b32 m0, s27
	s_addc_u32 s63, s45, 0
	global_load_lds_dwordx4 v[182:183], off
	v_lshl_add_u64 v[184:185], s[62:63], 0, v[156:157]
	s_mov_b32 m0, s33
	v_lshl_add_u64 v[186:187], s[48:49], 0, v[158:159]
	global_load_lds_dwordx4 v[184:185], off
	v_lshl_add_u64 v[184:185], s[62:63], 0, v[160:161]
	s_mov_b32 m0, s35
	s_nop 0
	global_load_lds_dwordx4 v[184:185], off
	v_lshl_add_u64 v[184:185], s[48:49], 0, v[154:155]
	s_mov_b32 m0, s8
	s_nop 0
	global_load_lds_dwordx4 v[184:185], off
	s_mov_b32 m0, s43
	s_nop 0
	global_load_lds_dwordx4 v[186:187], off
	s_waitcnt vmcnt(8)
	s_waitcnt lgkmcnt(0)
	s_setprio 1
	s_barrier
	v_mfma_f32_16x16x128_f8f6f4 v[70:73], v[2:9], v[216:223], v[70:73]
	v_mfma_f32_16x16x128_f8f6f4 v[66:69], v[192:199], v[216:223], v[66:69]
	v_mfma_f32_16x16x128_f8f6f4 v[58:61], v[192:199], v[224:231], v[58:61]
	v_mfma_f32_16x16x128_f8f6f4 v[62:65], v[2:9], v[224:231], v[62:65]
	v_mfma_f32_16x16x128_f8f6f4 v[54:57], v[2:9], v[232:239], v[54:57]
	v_mfma_f32_16x16x128_f8f6f4 v[50:53], v[192:199], v[232:239], v[50:53]
	v_mfma_f32_16x16x128_f8f6f4 v[42:45], v[192:199], v[242:249], v[42:45]
	v_mfma_f32_16x16x128_f8f6f4 v[46:49], v[2:9], v[242:249], v[46:49]
	s_setprio 0
	s_setprio 1
	v_mfma_f32_16x16x128_f8f6f4 v[14:17], v[200:207], v[242:249], v[14:17]
	v_mfma_f32_16x16x128_f8f6f4 v[10:13], v[208:215], v[242:249], v[10:13]
	v_mfma_f32_16x16x128_f8f6f4 v[18:21], v[208:215], v[232:239], v[18:21]
	v_mfma_f32_16x16x128_f8f6f4 v[22:25], v[200:207], v[232:239], v[22:25]
	v_mfma_f32_16x16x128_f8f6f4 v[30:33], v[200:207], v[224:231], v[30:33]
	v_mfma_f32_16x16x128_f8f6f4 v[26:29], v[208:215], v[224:231], v[26:29]
	s_barrier
	v_mfma_f32_16x16x128_f8f6f4 v[34:37], v[208:215], v[216:223], v[34:37]
	v_mfma_f32_16x16x128_f8f6f4 v[38:41], v[200:207], v[216:223], v[38:41]
	s_setprio 0
	ds_read_b128 v[192:195], v189 offset:32768
	ds_read_b128 v[196:199], v189 offset:33792
	ds_read_b128 v[200:203], v189 offset:34816
	ds_read_b128 v[204:207], v189 offset:35840
	ds_read_b128 v[2:5], v189 offset:49152
	ds_read_b128 v[6:9], v189 offset:50176
	ds_read_b128 v[208:211], v189 offset:51200
	ds_read_b128 v[212:215], v189 offset:52224
	s_add_u32 s48, s48, 0x80000
	s_addc_u32 s49, s49, 0
	s_mov_b32 m0, s52
	v_lshl_add_u64 v[252:253], s[48:49], 0, v[154:155]
	ds_read_b128 v[216:219], v190 offset:32768
	ds_read_b128 v[220:223], v190 offset:33792
	ds_read_b128 v[224:227], v190 offset:34816
	ds_read_b128 v[228:231], v190 offset:35840
	ds_read_b128 v[232:235], v190 offset:36864
	ds_read_b128 v[236:239], v190 offset:37888
	ds_read_b128 v[242:245], v190 offset:38912
	ds_read_b128 v[246:249], v190 offset:39936
	global_load_lds_dwordx4 v[252:253], off
	v_lshl_add_u64 v[252:253], s[48:49], 0, v[158:159]
	s_mov_b32 m0, s53
	s_nop 0
	global_load_lds_dwordx4 v[252:253], off
	s_waitcnt vmcnt(8)
	s_waitcnt lgkmcnt(0)
	s_setprio 1
	s_barrier
	v_mfma_f32_16x16x128_f8f6f4 v[134:137], v[192:199], v[216:223], v[134:137]
	v_mfma_f32_16x16x128_f8f6f4 v[130:133], v[200:207], v[216:223], v[130:133]
	v_mfma_f32_16x16x128_f8f6f4 v[122:125], v[200:207], v[224:231], v[122:125]
	v_mfma_f32_16x16x128_f8f6f4 v[126:129], v[192:199], v[224:231], v[126:129]
	v_mfma_f32_16x16x128_f8f6f4 v[118:121], v[192:199], v[232:239], v[118:121]
	v_mfma_f32_16x16x128_f8f6f4 v[114:117], v[200:207], v[232:239], v[114:117]
	v_mfma_f32_16x16x128_f8f6f4 v[106:109], v[200:207], v[242:249], v[106:109]
	v_mfma_f32_16x16x128_f8f6f4 v[110:113], v[192:199], v[242:249], v[110:113]
	s_setprio 0
	s_setprio 1
	v_mfma_f32_16x16x128_f8f6f4 v[78:81], v[2:9], v[242:249], v[78:81]
	v_mfma_f32_16x16x128_f8f6f4 v[74:77], v[208:215], v[242:249], v[74:77]
	v_mfma_f32_16x16x128_f8f6f4 v[82:85], v[208:215], v[232:239], v[82:85]
	v_mfma_f32_16x16x128_f8f6f4 v[86:89], v[2:9], v[232:239], v[86:89]
	v_mfma_f32_16x16x128_f8f6f4 v[94:97], v[2:9], v[224:231], v[94:97]
	v_mfma_f32_16x16x128_f8f6f4 v[90:93], v[208:215], v[224:231], v[90:93]
	s_barrier
	v_mfma_f32_16x16x128_f8f6f4 v[98:101], v[208:215], v[216:223], v[98:101]
	v_mfma_f32_16x16x128_f8f6f4 v[102:105], v[2:9], v[216:223], v[102:105]
	s_setprio 0
	s_mov_b32 m0, s70
	v_lshl_add_u64 v[176:177], v[176:177], 0, s[18:19]
	s_add_u32 s44, s44, 0x80080
	ds_read_b128 v[216:219], v190 offset:49152
	ds_read_b128 v[220:223], v190 offset:50176
	ds_read_b128 v[224:227], v190 offset:51200
	ds_read_b128 v[228:231], v190 offset:52224
	ds_read_b128 v[232:235], v190 offset:53248
	ds_read_b128 v[236:239], v190 offset:54272
	ds_read_b128 v[242:245], v190 offset:55296
	ds_read_b128 v[246:249], v190 offset:56320
	global_load_lds_dwordx4 v[176:177], off
	v_lshl_add_u64 v[176:177], v[182:183], 0, s[18:19]
	s_mov_b32 m0, s71
	s_addc_u32 s45, s45, 0
	global_load_lds_dwordx4 v[176:177], off
	v_lshl_add_u64 v[176:177], s[44:45], 0, v[156:157]
	s_mov_b32 m0, s74
	s_nop 0
	global_load_lds_dwordx4 v[176:177], off
	v_lshl_add_u64 v[176:177], s[44:45], 0, v[160:161]
	s_mov_b32 m0, s75
	s_nop 0
	global_load_lds_dwordx4 v[176:177], off
	v_lshl_add_u64 v[176:177], v[184:185], 0, s[18:19]
	s_mov_b32 m0, s72
	s_nop 0
	global_load_lds_dwordx4 v[176:177], off
	v_lshl_add_u64 v[176:177], v[186:187], 0, s[18:19]
	s_mov_b32 m0, s73
	s_nop 0
	global_load_lds_dwordx4 v[176:177], off
	s_waitcnt vmcnt(8)
	s_waitcnt lgkmcnt(0)
	s_setprio 1
	s_barrier
	v_mfma_f32_16x16x128_f8f6f4 v[70:73], v[192:199], v[216:223], v[70:73]
	v_mfma_f32_16x16x128_f8f6f4 v[66:69], v[200:207], v[216:223], v[66:69]
	v_mfma_f32_16x16x128_f8f6f4 v[58:61], v[200:207], v[224:231], v[58:61]
	v_mfma_f32_16x16x128_f8f6f4 v[62:65], v[192:199], v[224:231], v[62:65]
	v_mfma_f32_16x16x128_f8f6f4 v[54:57], v[192:199], v[232:239], v[54:57]
	v_mfma_f32_16x16x128_f8f6f4 v[50:53], v[200:207], v[232:239], v[50:53]
	v_mfma_f32_16x16x128_f8f6f4 v[42:45], v[200:207], v[242:249], v[42:45]
	v_mfma_f32_16x16x128_f8f6f4 v[46:49], v[192:199], v[242:249], v[46:49]
	s_setprio 0
	s_setprio 1
	v_mfma_f32_16x16x128_f8f6f4 v[14:17], v[2:9], v[242:249], v[14:17]
	v_mfma_f32_16x16x128_f8f6f4 v[10:13], v[208:215], v[242:249], v[10:13]
	v_mfma_f32_16x16x128_f8f6f4 v[18:21], v[208:215], v[232:239], v[18:21]
	v_mfma_f32_16x16x128_f8f6f4 v[22:25], v[2:9], v[232:239], v[22:25]
	v_mfma_f32_16x16x128_f8f6f4 v[30:33], v[2:9], v[224:231], v[30:33]
	v_mfma_f32_16x16x128_f8f6f4 v[26:29], v[208:215], v[224:231], v[26:29]
	s_barrier
	v_mfma_f32_16x16x128_f8f6f4 v[34:37], v[208:215], v[216:223], v[34:37]
	v_mfma_f32_16x16x128_f8f6f4 v[38:41], v[2:9], v[216:223], v[38:41]
	s_setprio 0
	s_add_i32 s44, s51, 2
	s_add_u32 s46, s46, 0x100
	s_addc_u32 s47, s47, 0
	s_add_u32 s41, s41, 0x100
	s_addc_u32 s50, s50, 0
	s_cmp_ge_i32 s51, s86
	s_cbranch_scc1 .LBB0_796
	s_mov_b32 s51, s44
	s_cmp_eq_u32 s86, s51
	s_cselect_b64 s[44:45], -1, 0
	s_cmp_lg_u32 s86, s51
	s_cbranch_scc0 .LBB0_793
	s_branch .LBB0_794

.LBB0_946:
	s_ashr_i32 s37, s36, 31
	ds_read_b128 v[18:21], v192
	ds_read_b128 v[22:25], v192 offset:1024
	ds_read_b128 v[26:29], v192 offset:2048
	ds_read_b128 v[30:33], v192 offset:3072
	ds_read_b128 v[2:5], v192 offset:16384
	ds_read_b128 v[6:9], v192 offset:17408
	ds_read_b128 v[10:13], v192 offset:18432
	ds_read_b128 v[14:17], v192 offset:19456
	s_lshl_b64 s[38:39], s[36:37], 20
	s_add_u32 s38, s22, s38
	s_addc_u32 s39, s23, s39
	s_and_b64 s[40:41], s[2:3], exec
	s_cselect_b32 s37, s39, s47
	s_cselect_b32 s84, s38, s46
	s_ashr_i32 s27, s26, 31
	s_lshl_b64 s[40:41], s[26:27], 20
	s_add_u32 s40, s25, s40
	s_addc_u32 s41, s35, s41
	s_and_b64 s[48:49], s[2:3], exec
	s_cselect_b32 s27, s41, s45
	s_cselect_b32 s85, s40, s44
	s_add_u32 s48, s46, 0x80080
	s_addc_u32 s49, s47, 0
	s_mov_b32 m0, s80
	v_lshl_add_u64 v[218:219], s[48:49], 0, v[164:165]
	ds_read_b128 v[184:187], v193
	ds_read_b128 v[188:191], v193 offset:1024
	ds_read_b128 v[194:197], v193 offset:2048
	ds_read_b128 v[198:201], v193 offset:3072
	ds_read_b128 v[202:205], v193 offset:4096
	ds_read_b128 v[206:209], v193 offset:5120
	ds_read_b128 v[210:213], v193 offset:6144
	ds_read_b128 v[214:217], v193 offset:7168
	global_load_lds_dwordx4 v[218:219], off
	v_lshl_add_u64 v[218:219], s[48:49], 0, v[168:169]
	s_mov_b32 m0, s81
	s_nop 0
	global_load_lds_dwordx4 v[218:219], off
	s_waitcnt vmcnt(8)
	s_waitcnt lgkmcnt(0)
	s_setprio 1
	s_barrier
	v_mfma_f32_16x16x128_f8f6f4 v[158:161], v[18:25], v[184:191], 0
	v_mfma_f32_16x16x128_f8f6f4 v[154:157], v[26:33], v[184:191], 0
	v_mfma_f32_16x16x128_f8f6f4 v[146:149], v[26:33], v[194:201], 0
	v_mfma_f32_16x16x128_f8f6f4 v[150:153], v[18:25], v[194:201], 0
	v_mfma_f32_16x16x128_f8f6f4 v[142:145], v[18:25], v[202:209], 0
	v_mfma_f32_16x16x128_f8f6f4 v[138:141], v[26:33], v[202:209], 0
	v_mfma_f32_16x16x128_f8f6f4 v[130:133], v[26:33], v[210:217], 0
	v_mfma_f32_16x16x128_f8f6f4 v[134:137], v[18:25], v[210:217], 0
	s_setprio 0
	s_setprio 1
	v_mfma_f32_16x16x128_f8f6f4 v[102:105], v[2:9], v[210:217], 0
	v_mfma_f32_16x16x128_f8f6f4 v[98:101], v[10:17], v[210:217], 0
	v_mfma_f32_16x16x128_f8f6f4 v[106:109], v[10:17], v[202:209], 0
	v_mfma_f32_16x16x128_f8f6f4 v[110:113], v[2:9], v[202:209], 0
	v_mfma_f32_16x16x128_f8f6f4 v[118:121], v[2:9], v[194:201], 0
	v_mfma_f32_16x16x128_f8f6f4 v[114:117], v[10:17], v[194:201], 0
	s_barrier
	v_mfma_f32_16x16x128_f8f6f4 v[122:125], v[10:17], v[184:191], 0
	v_mfma_f32_16x16x128_f8f6f4 v[126:129], v[2:9], v[184:191], 0
	s_setprio 0
	v_lshl_add_u64 v[184:185], s[44:45], 0, v[166:167]
	s_mov_b32 m0, s52
	v_lshl_add_u64 v[186:187], v[184:185], 0, s[14:15]
	ds_read_b128 v[194:197], v193 offset:16384
	ds_read_b128 v[198:201], v193 offset:17408
	ds_read_b128 v[202:205], v193 offset:18432
	ds_read_b128 v[206:209], v193 offset:19456
	ds_read_b128 v[210:213], v193 offset:20480
	ds_read_b128 v[214:217], v193 offset:21504
	ds_read_b128 v[218:221], v193 offset:22528
	ds_read_b128 v[222:225], v193 offset:23552
	global_load_lds_dwordx4 v[186:187], off
	v_lshl_add_u64 v[186:187], s[44:45], 0, v[170:171]
	s_add_u32 s48, s44, 0x80100
	v_lshl_add_u64 v[188:189], v[186:187], 0, s[14:15]
	s_mov_b32 m0, s53
	s_addc_u32 s49, s45, 0
	global_load_lds_dwordx4 v[188:189], off
	v_lshl_add_u64 v[188:189], s[48:49], 0, v[166:167]
	s_mov_b32 m0, s54
	s_nop 0
	global_load_lds_dwordx4 v[188:189], off
	v_lshl_add_u64 v[188:189], s[48:49], 0, v[170:171]
	s_mov_b32 m0, s55
	s_nop 0
	global_load_lds_dwordx4 v[188:189], off
	v_lshl_add_u64 v[188:189], s[46:47], 0, v[164:165]
	v_lshl_add_u64 v[190:191], v[188:189], 0, s[14:15]
	s_mov_b32 m0, s43
	s_nop 0
	global_load_lds_dwordx4 v[190:191], off
	v_lshl_add_u64 v[190:191], s[46:47], 0, v[168:169]
	v_lshl_add_u64 v[226:227], v[190:191], 0, s[14:15]
	s_mov_b32 m0, s61
	s_nop 0
	global_load_lds_dwordx4 v[226:227], off
	s_waitcnt vmcnt(8)
	s_waitcnt lgkmcnt(0)
	s_setprio 1
	s_barrier
	v_mfma_f32_16x16x128_f8f6f4 v[94:97], v[18:25], v[194:201], 0
	v_mfma_f32_16x16x128_f8f6f4 v[90:93], v[26:33], v[194:201], 0
	v_mfma_f32_16x16x128_f8f6f4 v[82:85], v[26:33], v[202:209], 0
	v_mfma_f32_16x16x128_f8f6f4 v[86:89], v[18:25], v[202:209], 0
	v_mfma_f32_16x16x128_f8f6f4 v[78:81], v[18:25], v[210:217], 0
	v_mfma_f32_16x16x128_f8f6f4 v[74:77], v[26:33], v[210:217], 0
	v_mfma_f32_16x16x128_f8f6f4 v[66:69], v[26:33], v[218:225], 0
	v_mfma_f32_16x16x128_f8f6f4 v[70:73], v[18:25], v[218:225], 0
	s_setprio 0
	s_setprio 1
	v_mfma_f32_16x16x128_f8f6f4 v[38:41], v[2:9], v[218:225], 0
	v_mfma_f32_16x16x128_f8f6f4 v[34:37], v[10:17], v[218:225], 0
	v_mfma_f32_16x16x128_f8f6f4 v[42:45], v[10:17], v[210:217], 0
	v_mfma_f32_16x16x128_f8f6f4 v[46:49], v[2:9], v[210:217], 0
	v_mfma_f32_16x16x128_f8f6f4 v[54:57], v[2:9], v[202:209], 0
	v_mfma_f32_16x16x128_f8f6f4 v[50:53], v[10:17], v[202:209], 0
	s_barrier
	v_mfma_f32_16x16x128_f8f6f4 v[58:61], v[10:17], v[194:201], 0
	v_mfma_f32_16x16x128_f8f6f4 v[62:65], v[2:9], v[194:201], 0
	s_setprio 0
	ds_read_b128 v[18:21], v192 offset:32768
	ds_read_b128 v[22:25], v192 offset:33792
	ds_read_b128 v[26:29], v192 offset:34816
	ds_read_b128 v[30:33], v192 offset:35840
	ds_read_b128 v[2:5], v192 offset:49152
	ds_read_b128 v[6:9], v192 offset:50176
	ds_read_b128 v[10:13], v192 offset:51200
	ds_read_b128 v[14:17], v192 offset:52224
	s_add_u32 s48, s46, 0x80100
	s_addc_u32 s49, s47, 0
	s_mov_b32 m0, s68
	v_lshl_add_u64 v[226:227], s[48:49], 0, v[164:165]
	ds_read_b128 v[194:197], v193 offset:32768
	ds_read_b128 v[198:201], v193 offset:33792
	ds_read_b128 v[202:205], v193 offset:34816
	ds_read_b128 v[206:209], v193 offset:35840
	ds_read_b128 v[210:213], v193 offset:36864
	ds_read_b128 v[214:217], v193 offset:37888
	ds_read_b128 v[218:221], v193 offset:38912
	ds_read_b128 v[222:225], v193 offset:39936
	global_load_lds_dwordx4 v[226:227], off
	v_lshl_add_u64 v[226:227], s[48:49], 0, v[168:169]
	s_mov_b32 m0, s69
	s_nop 0
	global_load_lds_dwordx4 v[226:227], off
	s_waitcnt vmcnt(8)
	s_waitcnt lgkmcnt(0)
	s_setprio 1
	s_barrier
	v_mfma_f32_16x16x128_f8f6f4 v[158:161], v[18:25], v[194:201], v[158:161]
	v_mfma_f32_16x16x128_f8f6f4 v[154:157], v[26:33], v[194:201], v[154:157]
	v_mfma_f32_16x16x128_f8f6f4 v[146:149], v[26:33], v[202:209], v[146:149]
	v_mfma_f32_16x16x128_f8f6f4 v[150:153], v[18:25], v[202:209], v[150:153]
	v_mfma_f32_16x16x128_f8f6f4 v[142:145], v[18:25], v[210:217], v[142:145]
	v_mfma_f32_16x16x128_f8f6f4 v[138:141], v[26:33], v[210:217], v[138:141]
	v_mfma_f32_16x16x128_f8f6f4 v[130:133], v[26:33], v[218:225], v[130:133]
	v_mfma_f32_16x16x128_f8f6f4 v[134:137], v[18:25], v[218:225], v[134:137]
	s_setprio 0
	s_setprio 1
	v_mfma_f32_16x16x128_f8f6f4 v[102:105], v[2:9], v[218:225], v[102:105]
	v_mfma_f32_16x16x128_f8f6f4 v[98:101], v[10:17], v[218:225], v[98:101]
	v_mfma_f32_16x16x128_f8f6f4 v[106:109], v[10:17], v[210:217], v[106:109]
	v_mfma_f32_16x16x128_f8f6f4 v[110:113], v[2:9], v[210:217], v[110:113]
	v_mfma_f32_16x16x128_f8f6f4 v[118:121], v[2:9], v[202:209], v[118:121]
	v_mfma_f32_16x16x128_f8f6f4 v[114:117], v[10:17], v[202:209], v[114:117]
	s_barrier
	v_mfma_f32_16x16x128_f8f6f4 v[122:125], v[10:17], v[194:201], v[122:125]
	v_mfma_f32_16x16x128_f8f6f4 v[126:129], v[2:9], v[194:201], v[126:129]
	s_setprio 0
	s_mov_b32 m0, s74
	v_lshl_add_u64 v[184:185], v[184:185], 0, s[18:19]
	s_add_u32 s48, s44, 0x80180
	ds_read_b128 v[194:197], v193 offset:49152
	ds_read_b128 v[198:201], v193 offset:50176
	ds_read_b128 v[202:205], v193 offset:51200
	ds_read_b128 v[206:209], v193 offset:52224
	ds_read_b128 v[210:213], v193 offset:53248
	ds_read_b128 v[214:217], v193 offset:54272
	ds_read_b128 v[218:221], v193 offset:55296
	ds_read_b128 v[222:225], v193 offset:56320
	global_load_lds_dwordx4 v[184:185], off
	v_lshl_add_u64 v[184:185], v[186:187], 0, s[18:19]
	s_mov_b32 m0, s75
	s_addc_u32 s49, s45, 0
	global_load_lds_dwordx4 v[184:185], off
	v_lshl_add_u64 v[184:185], s[48:49], 0, v[166:167]
	s_mov_b32 m0, s78
	s_nop 0
	global_load_lds_dwordx4 v[184:185], off
	v_lshl_add_u64 v[184:185], s[48:49], 0, v[170:171]
	s_mov_b32 m0, s79
	s_nop 0
	global_load_lds_dwordx4 v[184:185], off
	v_lshl_add_u64 v[184:185], v[188:189], 0, s[18:19]
	s_mov_b32 m0, s76
	s_nop 0
	global_load_lds_dwordx4 v[184:185], off
	v_lshl_add_u64 v[184:185], v[190:191], 0, s[18:19]
	s_mov_b32 m0, s77
	s_nop 0
	global_load_lds_dwordx4 v[184:185], off
	s_waitcnt vmcnt(8)
	s_waitcnt lgkmcnt(0)
	s_setprio 1
	s_barrier
	v_mfma_f32_16x16x128_f8f6f4 v[94:97], v[18:25], v[194:201], v[94:97]
	v_mfma_f32_16x16x128_f8f6f4 v[90:93], v[26:33], v[194:201], v[90:93]
	v_mfma_f32_16x16x128_f8f6f4 v[82:85], v[26:33], v[202:209], v[82:85]
	v_mfma_f32_16x16x128_f8f6f4 v[86:89], v[18:25], v[202:209], v[86:89]
	v_mfma_f32_16x16x128_f8f6f4 v[78:81], v[18:25], v[210:217], v[78:81]
	v_mfma_f32_16x16x128_f8f6f4 v[74:77], v[26:33], v[210:217], v[74:77]
	v_mfma_f32_16x16x128_f8f6f4 v[66:69], v[26:33], v[218:225], v[66:69]
	v_mfma_f32_16x16x128_f8f6f4 v[70:73], v[18:25], v[218:225], v[70:73]
	s_setprio 0
	s_setprio 1
	v_mfma_f32_16x16x128_f8f6f4 v[38:41], v[2:9], v[218:225], v[38:41]
	v_mfma_f32_16x16x128_f8f6f4 v[34:37], v[10:17], v[218:225], v[34:37]
	v_mfma_f32_16x16x128_f8f6f4 v[42:45], v[10:17], v[210:217], v[42:45]
	v_mfma_f32_16x16x128_f8f6f4 v[46:49], v[2:9], v[210:217], v[46:49]
	v_mfma_f32_16x16x128_f8f6f4 v[54:57], v[2:9], v[202:209], v[54:57]
	v_mfma_f32_16x16x128_f8f6f4 v[50:53], v[10:17], v[202:209], v[50:53]
	s_barrier
	v_mfma_f32_16x16x128_f8f6f4 v[58:61], v[10:17], v[194:201], v[58:61]
	v_mfma_f32_16x16x128_f8f6f4 v[62:65], v[2:9], v[194:201], v[62:65]
	s_setprio 0
	s_add_u32 s46, s46, 0x80180
	s_addc_u32 s47, s47, 0
	s_add_u32 s62, s44, 0x200
	s_addc_u32 s63, s45, 0
	s_mov_b32 s86, 0
.LBB0_947:
	ds_read_b128 v[2:5], v192
	ds_read_b128 v[6:9], v192 offset:1024
	ds_read_b128 v[18:21], v192 offset:2048
	ds_read_b128 v[22:25], v192 offset:3072
	ds_read_b128 v[26:29], v192 offset:16384
	ds_read_b128 v[30:33], v192 offset:17408
	ds_read_b128 v[184:187], v192 offset:18432
	ds_read_b128 v[188:191], v192 offset:19456
	s_add_u32 s44, s46, 0xfff80080
	s_addc_u32 s45, s47, -1
	s_cmp_eq_u32 s86, 28
	s_cselect_b32 s49, s37, s45
	s_cselect_b32 s48, s84, s44
	s_cselect_b32 s45, s27, s63
	s_cselect_b32 s44, s85, s62
	s_mov_b32 m0, s80
	v_lshl_add_u64 v[218:219], s[46:47], 0, v[172:173]
	ds_read_b128 v[10:13], v193
	ds_read_b128 v[14:17], v193 offset:1024
	ds_read_b128 v[194:197], v193 offset:2048
	ds_read_b128 v[198:201], v193 offset:3072
	ds_read_b128 v[202:205], v193 offset:4096
	ds_read_b128 v[206:209], v193 offset:5120
	ds_read_b128 v[210:213], v193 offset:6144
	ds_read_b128 v[214:217], v193 offset:7168
	global_load_lds_dwordx4 v[218:219], off
	v_lshl_add_u64 v[218:219], s[46:47], 0, v[174:175]
	s_mov_b32 m0, s81
	s_nop 0
	global_load_lds_dwordx4 v[218:219], off
	s_waitcnt vmcnt(8)
	s_waitcnt lgkmcnt(0)
	s_setprio 1
	s_barrier
	v_mfma_f32_16x16x128_f8f6f4 v[158:161], v[2:9], v[10:17], v[158:161]
	v_mfma_f32_16x16x128_f8f6f4 v[154:157], v[18:25], v[10:17], v[154:157]
	v_mfma_f32_16x16x128_f8f6f4 v[146:149], v[18:25], v[194:201], v[146:149]
	v_mfma_f32_16x16x128_f8f6f4 v[150:153], v[2:9], v[194:201], v[150:153]
	v_mfma_f32_16x16x128_f8f6f4 v[142:145], v[2:9], v[202:209], v[142:145]
	v_mfma_f32_16x16x128_f8f6f4 v[138:141], v[18:25], v[202:209], v[138:141]
	v_mfma_f32_16x16x128_f8f6f4 v[130:133], v[18:25], v[210:217], v[130:133]
	v_mfma_f32_16x16x128_f8f6f4 v[134:137], v[2:9], v[210:217], v[134:137]
	s_setprio 0
	s_setprio 1
	v_mfma_f32_16x16x128_f8f6f4 v[102:105], v[26:33], v[210:217], v[102:105]
	v_mfma_f32_16x16x128_f8f6f4 v[98:101], v[184:191], v[210:217], v[98:101]
	v_mfma_f32_16x16x128_f8f6f4 v[106:109], v[184:191], v[202:209], v[106:109]
	v_mfma_f32_16x16x128_f8f6f4 v[110:113], v[26:33], v[202:209], v[110:113]
	v_mfma_f32_16x16x128_f8f6f4 v[118:121], v[26:33], v[194:201], v[118:121]
	v_mfma_f32_16x16x128_f8f6f4 v[114:117], v[184:191], v[194:201], v[114:117]
	s_barrier
	v_mfma_f32_16x16x128_f8f6f4 v[122:125], v[184:191], v[10:17], v[122:125]
	v_mfma_f32_16x16x128_f8f6f4 v[126:129], v[26:33], v[10:17], v[126:129]
	s_setprio 0
	s_mov_b32 m0, s52
	v_lshl_add_u64 v[10:11], s[44:45], 0, v[166:167]
	s_add_u32 s88, s44, 0x80000
	ds_read_b128 v[194:197], v193 offset:16384
	ds_read_b128 v[198:201], v193 offset:17408
	ds_read_b128 v[202:205], v193 offset:18432
	ds_read_b128 v[206:209], v193 offset:19456
	ds_read_b128 v[210:213], v193 offset:20480
	ds_read_b128 v[214:217], v193 offset:21504
	ds_read_b128 v[218:221], v193 offset:22528
	ds_read_b128 v[222:225], v193 offset:23552
	global_load_lds_dwordx4 v[10:11], off
	v_lshl_add_u64 v[12:13], s[44:45], 0, v[170:171]
	s_mov_b32 m0, s53
	s_addc_u32 s89, s45, 0
	global_load_lds_dwordx4 v[12:13], off
	v_lshl_add_u64 v[14:15], s[88:89], 0, v[166:167]
	s_mov_b32 m0, s54
	v_lshl_add_u64 v[16:17], s[48:49], 0, v[168:169]
	global_load_lds_dwordx4 v[14:15], off
	v_lshl_add_u64 v[14:15], s[88:89], 0, v[170:171]
	s_mov_b32 m0, s55
	s_nop 0
	global_load_lds_dwordx4 v[14:15], off
	v_lshl_add_u64 v[14:15], s[48:49], 0, v[164:165]
	s_mov_b32 m0, s43
	s_nop 0
	global_load_lds_dwordx4 v[14:15], off
	s_mov_b32 m0, s61
	s_nop 0
	global_load_lds_dwordx4 v[16:17], off
	s_waitcnt vmcnt(8)
	s_waitcnt lgkmcnt(0)
	s_setprio 1
	s_barrier
	v_mfma_f32_16x16x128_f8f6f4 v[94:97], v[2:9], v[194:201], v[94:97]
	v_mfma_f32_16x16x128_f8f6f4 v[90:93], v[18:25], v[194:201], v[90:93]
	v_mfma_f32_16x16x128_f8f6f4 v[82:85], v[18:25], v[202:209], v[82:85]
	v_mfma_f32_16x16x128_f8f6f4 v[86:89], v[2:9], v[202:209], v[86:89]
	v_mfma_f32_16x16x128_f8f6f4 v[78:81], v[2:9], v[210:217], v[78:81]
	v_mfma_f32_16x16x128_f8f6f4 v[74:77], v[18:25], v[210:217], v[74:77]
	v_mfma_f32_16x16x128_f8f6f4 v[66:69], v[18:25], v[218:225], v[66:69]
	v_mfma_f32_16x16x128_f8f6f4 v[70:73], v[2:9], v[218:225], v[70:73]
	s_setprio 0
	s_setprio 1
	v_mfma_f32_16x16x128_f8f6f4 v[38:41], v[26:33], v[218:225], v[38:41]
	v_mfma_f32_16x16x128_f8f6f4 v[34:37], v[184:191], v[218:225], v[34:37]
	v_mfma_f32_16x16x128_f8f6f4 v[42:45], v[184:191], v[210:217], v[42:45]
	v_mfma_f32_16x16x128_f8f6f4 v[46:49], v[26:33], v[210:217], v[46:49]
	v_mfma_f32_16x16x128_f8f6f4 v[54:57], v[26:33], v[202:209], v[54:57]
	v_mfma_f32_16x16x128_f8f6f4 v[50:53], v[184:191], v[202:209], v[50:53]
	s_barrier
	v_mfma_f32_16x16x128_f8f6f4 v[58:61], v[184:191], v[194:201], v[58:61]
	v_mfma_f32_16x16x128_f8f6f4 v[62:65], v[26:33], v[194:201], v[62:65]
	s_setprio 0
	ds_read_b128 v[18:21], v192 offset:32768
	ds_read_b128 v[22:25], v192 offset:33792
	ds_read_b128 v[26:29], v192 offset:34816
	ds_read_b128 v[30:33], v192 offset:35840
	ds_read_b128 v[2:5], v192 offset:49152
	ds_read_b128 v[6:9], v192 offset:50176
	ds_read_b128 v[184:187], v192 offset:51200
	ds_read_b128 v[188:191], v192 offset:52224
	s_add_u32 s48, s48, 0x80000
	s_addc_u32 s49, s49, 0
	s_mov_b32 m0, s68
	v_lshl_add_u64 v[226:227], s[48:49], 0, v[164:165]
	ds_read_b128 v[194:197], v193 offset:32768
	ds_read_b128 v[198:201], v193 offset:33792
	ds_read_b128 v[202:205], v193 offset:34816
	ds_read_b128 v[206:209], v193 offset:35840
	ds_read_b128 v[210:213], v193 offset:36864
	ds_read_b128 v[214:217], v193 offset:37888
	ds_read_b128 v[218:221], v193 offset:38912
	ds_read_b128 v[222:225], v193 offset:39936
	global_load_lds_dwordx4 v[226:227], off
	v_lshl_add_u64 v[226:227], s[48:49], 0, v[168:169]
	s_mov_b32 m0, s69
	s_nop 0
	global_load_lds_dwordx4 v[226:227], off
	s_waitcnt vmcnt(8)
	s_waitcnt lgkmcnt(0)
	s_setprio 1
	s_barrier
	v_mfma_f32_16x16x128_f8f6f4 v[158:161], v[18:25], v[194:201], v[158:161]
	v_mfma_f32_16x16x128_f8f6f4 v[154:157], v[26:33], v[194:201], v[154:157]
	v_mfma_f32_16x16x128_f8f6f4 v[146:149], v[26:33], v[202:209], v[146:149]
	v_mfma_f32_16x16x128_f8f6f4 v[150:153], v[18:25], v[202:209], v[150:153]
	v_mfma_f32_16x16x128_f8f6f4 v[142:145], v[18:25], v[210:217], v[142:145]
	v_mfma_f32_16x16x128_f8f6f4 v[138:141], v[26:33], v[210:217], v[138:141]
	v_mfma_f32_16x16x128_f8f6f4 v[130:133], v[26:33], v[218:225], v[130:133]
	v_mfma_f32_16x16x128_f8f6f4 v[134:137], v[18:25], v[218:225], v[134:137]
	s_setprio 0
	s_setprio 1
	v_mfma_f32_16x16x128_f8f6f4 v[102:105], v[2:9], v[218:225], v[102:105]
	v_mfma_f32_16x16x128_f8f6f4 v[98:101], v[184:191], v[218:225], v[98:101]
	v_mfma_f32_16x16x128_f8f6f4 v[106:109], v[184:191], v[210:217], v[106:109]
	v_mfma_f32_16x16x128_f8f6f4 v[110:113], v[2:9], v[210:217], v[110:113]
	v_mfma_f32_16x16x128_f8f6f4 v[118:121], v[2:9], v[202:209], v[118:121]
	v_mfma_f32_16x16x128_f8f6f4 v[114:117], v[184:191], v[202:209], v[114:117]
	s_barrier
	v_mfma_f32_16x16x128_f8f6f4 v[122:125], v[184:191], v[194:201], v[122:125]
	v_mfma_f32_16x16x128_f8f6f4 v[126:129], v[2:9], v[194:201], v[126:129]
	s_setprio 0
	s_mov_b32 m0, s74
	v_lshl_add_u64 v[10:11], v[10:11], 0, s[4:5]
	s_add_u32 s44, s44, 0x80080
	ds_read_b128 v[194:197], v193 offset:49152
	ds_read_b128 v[198:201], v193 offset:50176
	ds_read_b128 v[202:205], v193 offset:51200
	ds_read_b128 v[206:209], v193 offset:52224
	ds_read_b128 v[210:213], v193 offset:53248
	ds_read_b128 v[214:217], v193 offset:54272
	ds_read_b128 v[218:221], v193 offset:55296
	ds_read_b128 v[222:225], v193 offset:56320
	global_load_lds_dwordx4 v[10:11], off
	v_lshl_add_u64 v[10:11], v[12:13], 0, s[4:5]
	s_mov_b32 m0, s75
	s_addc_u32 s45, s45, 0
	global_load_lds_dwordx4 v[10:11], off
	v_lshl_add_u64 v[10:11], s[44:45], 0, v[166:167]
	s_mov_b32 m0, s78
	s_nop 0
	global_load_lds_dwordx4 v[10:11], off
	v_lshl_add_u64 v[10:11], s[44:45], 0, v[170:171]
	s_mov_b32 m0, s79
	s_nop 0
	global_load_lds_dwordx4 v[10:11], off
	v_lshl_add_u64 v[10:11], v[14:15], 0, s[4:5]
	s_mov_b32 m0, s76
	s_nop 0
	global_load_lds_dwordx4 v[10:11], off
	v_lshl_add_u64 v[10:11], v[16:17], 0, s[4:5]
	s_mov_b32 m0, s77
	s_nop 0
	global_load_lds_dwordx4 v[10:11], off
	s_waitcnt vmcnt(8)
	s_waitcnt lgkmcnt(0)
	s_setprio 1
	s_barrier
	v_mfma_f32_16x16x128_f8f6f4 v[94:97], v[18:25], v[194:201], v[94:97]
	v_mfma_f32_16x16x128_f8f6f4 v[90:93], v[26:33], v[194:201], v[90:93]
	v_mfma_f32_16x16x128_f8f6f4 v[82:85], v[26:33], v[202:209], v[82:85]
	v_mfma_f32_16x16x128_f8f6f4 v[86:89], v[18:25], v[202:209], v[86:89]
	v_mfma_f32_16x16x128_f8f6f4 v[78:81], v[18:25], v[210:217], v[78:81]
	v_mfma_f32_16x16x128_f8f6f4 v[74:77], v[26:33], v[210:217], v[74:77]
	v_mfma_f32_16x16x128_f8f6f4 v[66:69], v[26:33], v[218:225], v[66:69]
	v_mfma_f32_16x16x128_f8f6f4 v[70:73], v[18:25], v[218:225], v[70:73]
	s_setprio 0
	s_setprio 1
	v_mfma_f32_16x16x128_f8f6f4 v[38:41], v[2:9], v[218:225], v[38:41]
	v_mfma_f32_16x16x128_f8f6f4 v[34:37], v[184:191], v[218:225], v[34:37]
	v_mfma_f32_16x16x128_f8f6f4 v[42:45], v[184:191], v[210:217], v[42:45]
	v_mfma_f32_16x16x128_f8f6f4 v[46:49], v[2:9], v[210:217], v[46:49]
	v_mfma_f32_16x16x128_f8f6f4 v[54:57], v[2:9], v[202:209], v[54:57]
	v_mfma_f32_16x16x128_f8f6f4 v[50:53], v[184:191], v[202:209], v[50:53]
	s_barrier
	v_mfma_f32_16x16x128_f8f6f4 v[58:61], v[184:191], v[194:201], v[58:61]
	v_mfma_f32_16x16x128_f8f6f4 v[62:65], v[2:9], v[194:201], v[62:65]
	s_setprio 0
	s_add_i32 s86, s86, 2
	s_add_u32 s46, s46, 0x100
	s_addc_u32 s47, s47, 0
	s_add_u32 s62, s62, 0x100
	s_addc_u32 s63, s63, 0
	s_cmp_gt_u32 s86, 29
	s_cbranch_scc0 .LBB0_947
	s_and_b64 vcc, exec, s[6:7]
	s_cbranch_vccz .LBB0_950
	s_barrier

.LBB0_1031:
	ds_read_b128 v[2:5], v189
	ds_read_b128 v[6:9], v189 offset:1024
	ds_read_b128 v[192:195], v189 offset:2048
	ds_read_b128 v[196:199], v189 offset:3072
	ds_read_b128 v[200:203], v189 offset:16384
	ds_read_b128 v[204:207], v189 offset:17408
	ds_read_b128 v[208:211], v189 offset:18432
	ds_read_b128 v[212:215], v189 offset:19456
	s_add_u32 s25, s36, 0x100
	s_addc_u32 s83, s37, 0
	s_and_b64 s[40:41], s[38:39], exec
	s_cselect_b32 s41, s1, s83
	s_cselect_b32 s40, s0, s25
	s_add_u32 s25, s26, 0x100
	s_addc_u32 s83, s27, 0
	s_and_b64 s[38:39], s[38:39], exec
	s_cselect_b32 s39, s5, s83
	s_cselect_b32 s38, s4, s25
	s_add_u32 s84, s36, 0x158080
	s_addc_u32 s85, s37, 0
	s_add_i32 s25, s23, 0xc000
	v_lshl_add_u64 v[174:175], s[84:85], 0, v[154:155]
	s_mov_b32 m0, s25
	s_add_i32 s83, s23, 0xe000
	ds_read_b128 v[216:219], v190
	ds_read_b128 v[220:223], v190 offset:1024
	ds_read_b128 v[224:227], v190 offset:2048
	ds_read_b128 v[228:231], v190 offset:3072
	ds_read_b128 v[232:235], v190 offset:4096
	ds_read_b128 v[236:239], v190 offset:5120
	ds_read_b128 v[240:243], v190 offset:6144
	ds_read_b128 v[244:247], v190 offset:7168
	global_load_lds_dwordx4 v[174:175], off
	v_lshl_add_u64 v[174:175], s[84:85], 0, v[158:159]
	s_mov_b32 m0, s83
	s_nop 0
	global_load_lds_dwordx4 v[174:175], off
	s_waitcnt vmcnt(8)
	s_waitcnt lgkmcnt(0)
	s_setprio 1
	s_barrier
	v_mfma_f32_16x16x128_f8f6f4 v[134:137], v[2:9], v[216:223], 0
	v_mfma_f32_16x16x128_f8f6f4 v[130:133], v[192:199], v[216:223], 0
	v_mfma_f32_16x16x128_f8f6f4 v[122:125], v[192:199], v[224:231], 0
	v_mfma_f32_16x16x128_f8f6f4 v[126:129], v[2:9], v[224:231], 0
	v_mfma_f32_16x16x128_f8f6f4 v[118:121], v[2:9], v[232:239], 0
	v_mfma_f32_16x16x128_f8f6f4 v[114:117], v[192:199], v[232:239], 0
	v_mfma_f32_16x16x128_f8f6f4 v[106:109], v[192:199], v[240:247], 0
	v_mfma_f32_16x16x128_f8f6f4 v[110:113], v[2:9], v[240:247], 0
	s_setprio 0
	s_setprio 1
	v_mfma_f32_16x16x128_f8f6f4 v[78:81], v[200:207], v[240:247], 0
	v_mfma_f32_16x16x128_f8f6f4 v[74:77], v[208:215], v[240:247], 0
	v_mfma_f32_16x16x128_f8f6f4 v[82:85], v[208:215], v[232:239], 0
	v_mfma_f32_16x16x128_f8f6f4 v[86:89], v[200:207], v[232:239], 0
	v_mfma_f32_16x16x128_f8f6f4 v[94:97], v[200:207], v[224:231], 0
	v_mfma_f32_16x16x128_f8f6f4 v[90:93], v[208:215], v[224:231], 0
	s_barrier
	v_mfma_f32_16x16x128_f8f6f4 v[98:101], v[208:215], v[216:223], 0
	v_mfma_f32_16x16x128_f8f6f4 v[102:105], v[200:207], v[216:223], 0
	s_setprio 0
	s_mov_b32 m0, s33
	v_lshl_add_u64 v[174:175], s[38:39], 0, v[156:157]
	s_add_u32 s84, s38, 0x158000
	ds_read_b128 v[216:219], v190 offset:16384
	ds_read_b128 v[220:223], v190 offset:17408
	ds_read_b128 v[224:227], v190 offset:18432
	ds_read_b128 v[228:231], v190 offset:19456
	ds_read_b128 v[232:235], v190 offset:20480
	ds_read_b128 v[236:239], v190 offset:21504
	ds_read_b128 v[240:243], v190 offset:22528
	ds_read_b128 v[244:247], v190 offset:23552
	global_load_lds_dwordx4 v[174:175], off
	v_lshl_add_u64 v[176:177], s[38:39], 0, v[160:161]
	s_mov_b32 m0, s35
	s_addc_u32 s85, s39, 0
	global_load_lds_dwordx4 v[176:177], off
	v_lshl_add_u64 v[182:183], s[84:85], 0, v[156:157]
	s_mov_b32 m0, s42
	v_lshl_add_u64 v[184:185], s[40:41], 0, v[158:159]
	global_load_lds_dwordx4 v[182:183], off
	v_lshl_add_u64 v[182:183], s[84:85], 0, v[160:161]
	s_mov_b32 m0, s43
	s_nop 0
	global_load_lds_dwordx4 v[182:183], off
	v_lshl_add_u64 v[182:183], s[40:41], 0, v[154:155]
	s_mov_b32 m0, s23
	s_nop 0
	global_load_lds_dwordx4 v[182:183], off
	s_mov_b32 m0, s44
	s_nop 0
	global_load_lds_dwordx4 v[184:185], off
	s_waitcnt vmcnt(8)
	s_waitcnt lgkmcnt(0)
	s_setprio 1
	s_barrier
	v_mfma_f32_16x16x128_f8f6f4 v[70:73], v[2:9], v[216:223], 0
	v_mfma_f32_16x16x128_f8f6f4 v[66:69], v[192:199], v[216:223], 0
	v_mfma_f32_16x16x128_f8f6f4 v[58:61], v[192:199], v[224:231], 0
	v_mfma_f32_16x16x128_f8f6f4 v[62:65], v[2:9], v[224:231], 0
	v_mfma_f32_16x16x128_f8f6f4 v[54:57], v[2:9], v[232:239], 0
	v_mfma_f32_16x16x128_f8f6f4 v[50:53], v[192:199], v[232:239], 0
	v_mfma_f32_16x16x128_f8f6f4 v[42:45], v[192:199], v[240:247], 0
	v_mfma_f32_16x16x128_f8f6f4 v[46:49], v[2:9], v[240:247], 0
	s_setprio 0
	s_setprio 1
	v_mfma_f32_16x16x128_f8f6f4 v[14:17], v[200:207], v[240:247], 0
	v_mfma_f32_16x16x128_f8f6f4 v[10:13], v[208:215], v[240:247], 0
	v_mfma_f32_16x16x128_f8f6f4 v[18:21], v[208:215], v[232:239], 0
	v_mfma_f32_16x16x128_f8f6f4 v[22:25], v[200:207], v[232:239], 0
	v_mfma_f32_16x16x128_f8f6f4 v[30:33], v[200:207], v[224:231], 0
	v_mfma_f32_16x16x128_f8f6f4 v[26:29], v[208:215], v[224:231], 0
	s_barrier
	v_mfma_f32_16x16x128_f8f6f4 v[34:37], v[208:215], v[216:223], 0
	v_mfma_f32_16x16x128_f8f6f4 v[38:41], v[200:207], v[216:223], 0
	s_setprio 0
	ds_read_b128 v[2:5], v189 offset:32768
	ds_read_b128 v[6:9], v189 offset:33792
	ds_read_b128 v[192:195], v189 offset:34816
	ds_read_b128 v[196:199], v189 offset:35840
	ds_read_b128 v[200:203], v189 offset:49152
	ds_read_b128 v[204:207], v189 offset:50176
	ds_read_b128 v[208:211], v189 offset:51200
	ds_read_b128 v[212:215], v189 offset:52224
	s_add_u32 s40, s40, 0x158000
	s_addc_u32 s41, s41, 0
	s_mov_b32 m0, s45
	v_lshl_add_u64 v[186:187], s[40:41], 0, v[154:155]
	ds_read_b128 v[216:219], v190 offset:32768
	ds_read_b128 v[220:223], v190 offset:33792
	ds_read_b128 v[224:227], v190 offset:34816
	ds_read_b128 v[228:231], v190 offset:35840
	ds_read_b128 v[232:235], v190 offset:36864
	ds_read_b128 v[236:239], v190 offset:37888
	ds_read_b128 v[240:243], v190 offset:38912
	ds_read_b128 v[244:247], v190 offset:39936
	global_load_lds_dwordx4 v[186:187], off
	v_lshl_add_u64 v[186:187], s[40:41], 0, v[158:159]
	s_mov_b32 m0, s46
	s_nop 0
	global_load_lds_dwordx4 v[186:187], off
	s_waitcnt vmcnt(8)
	s_waitcnt lgkmcnt(0)
	s_setprio 1
	s_barrier
	v_mfma_f32_16x16x128_f8f6f4 v[134:137], v[2:9], v[216:223], v[134:137]
	v_mfma_f32_16x16x128_f8f6f4 v[130:133], v[192:199], v[216:223], v[130:133]
	v_mfma_f32_16x16x128_f8f6f4 v[122:125], v[192:199], v[224:231], v[122:125]
	v_mfma_f32_16x16x128_f8f6f4 v[126:129], v[2:9], v[224:231], v[126:129]
	v_mfma_f32_16x16x128_f8f6f4 v[118:121], v[2:9], v[232:239], v[118:121]
	v_mfma_f32_16x16x128_f8f6f4 v[114:117], v[192:199], v[232:239], v[114:117]
	v_mfma_f32_16x16x128_f8f6f4 v[106:109], v[192:199], v[240:247], v[106:109]
	v_mfma_f32_16x16x128_f8f6f4 v[110:113], v[2:9], v[240:247], v[110:113]
	s_setprio 0
	s_setprio 1
	v_mfma_f32_16x16x128_f8f6f4 v[78:81], v[200:207], v[240:247], v[78:81]
	v_mfma_f32_16x16x128_f8f6f4 v[74:77], v[208:215], v[240:247], v[74:77]
	v_mfma_f32_16x16x128_f8f6f4 v[82:85], v[208:215], v[232:239], v[82:85]
	v_mfma_f32_16x16x128_f8f6f4 v[86:89], v[200:207], v[232:239], v[86:89]
	v_mfma_f32_16x16x128_f8f6f4 v[94:97], v[200:207], v[224:231], v[94:97]
	v_mfma_f32_16x16x128_f8f6f4 v[90:93], v[208:215], v[224:231], v[90:93]
	s_barrier
	v_mfma_f32_16x16x128_f8f6f4 v[98:101], v[208:215], v[216:223], v[98:101]
	v_mfma_f32_16x16x128_f8f6f4 v[102:105], v[200:207], v[216:223], v[102:105]
	s_setprio 0
	s_mov_b32 m0, s52
	v_lshl_add_u64 v[174:175], v[174:175], 0, s[14:15]
	s_add_u32 s38, s38, 0x158080
	ds_read_b128 v[216:219], v190 offset:49152
	ds_read_b128 v[220:223], v190 offset:50176
	ds_read_b128 v[224:227], v190 offset:51200
	ds_read_b128 v[228:231], v190 offset:52224
	ds_read_b128 v[232:235], v190 offset:53248
	ds_read_b128 v[236:239], v190 offset:54272
	ds_read_b128 v[240:243], v190 offset:55296
	ds_read_b128 v[244:247], v190 offset:56320
	global_load_lds_dwordx4 v[174:175], off
	v_lshl_add_u64 v[174:175], v[176:177], 0, s[14:15]
	s_mov_b32 m0, s53
	s_addc_u32 s39, s39, 0
	global_load_lds_dwordx4 v[174:175], off
	v_lshl_add_u64 v[174:175], s[38:39], 0, v[156:157]
	s_mov_b32 m0, s56
	s_nop 0
	global_load_lds_dwordx4 v[174:175], off
	v_lshl_add_u64 v[174:175], s[38:39], 0, v[160:161]
	s_mov_b32 m0, s57
	s_nop 0
	global_load_lds_dwordx4 v[174:175], off
	v_lshl_add_u64 v[174:175], v[182:183], 0, s[14:15]
	s_mov_b32 m0, s54
	s_nop 0
	global_load_lds_dwordx4 v[174:175], off
	v_lshl_add_u64 v[174:175], v[184:185], 0, s[14:15]
	s_mov_b32 m0, s55
	s_nop 0
	global_load_lds_dwordx4 v[174:175], off
	s_waitcnt vmcnt(8)
	s_waitcnt lgkmcnt(0)
	s_setprio 1
	s_barrier
	v_mfma_f32_16x16x128_f8f6f4 v[70:73], v[2:9], v[216:223], v[70:73]
	v_mfma_f32_16x16x128_f8f6f4 v[66:69], v[192:199], v[216:223], v[66:69]
	v_mfma_f32_16x16x128_f8f6f4 v[58:61], v[192:199], v[224:231], v[58:61]
	v_mfma_f32_16x16x128_f8f6f4 v[62:65], v[2:9], v[224:231], v[62:65]
	v_mfma_f32_16x16x128_f8f6f4 v[54:57], v[2:9], v[232:239], v[54:57]
	v_mfma_f32_16x16x128_f8f6f4 v[50:53], v[192:199], v[232:239], v[50:53]
	v_mfma_f32_16x16x128_f8f6f4 v[42:45], v[192:199], v[240:247], v[42:45]
	v_mfma_f32_16x16x128_f8f6f4 v[46:49], v[2:9], v[240:247], v[46:49]
	s_setprio 0
	s_setprio 1
	v_mfma_f32_16x16x128_f8f6f4 v[14:17], v[200:207], v[240:247], v[14:17]
	v_mfma_f32_16x16x128_f8f6f4 v[10:13], v[208:215], v[240:247], v[10:13]
	v_mfma_f32_16x16x128_f8f6f4 v[18:21], v[208:215], v[232:239], v[18:21]
	v_mfma_f32_16x16x128_f8f6f4 v[22:25], v[200:207], v[232:239], v[22:25]
	v_mfma_f32_16x16x128_f8f6f4 v[30:33], v[200:207], v[224:231], v[30:33]
	v_mfma_f32_16x16x128_f8f6f4 v[26:29], v[208:215], v[224:231], v[26:29]
	s_barrier
	v_mfma_f32_16x16x128_f8f6f4 v[34:37], v[208:215], v[216:223], v[34:37]
	v_mfma_f32_16x16x128_f8f6f4 v[38:41], v[200:207], v[216:223], v[38:41]
	s_setprio 0
	s_cmp_lt_u32 s82, 3
	s_cbranch_scc1 .LBB0_1036
	s_add_u32 s38, s48, s63
	s_addc_u32 s39, s49, s62
	s_add_u32 s36, s36, 0x158180
	s_addc_u32 s37, s37, 0
	s_add_u32 s40, s26, 0x200
	v_lshl_add_u64 v[174:175], v[172:173], 2, s[38:39]
	s_addc_u32 s41, s27, 0
	s_mov_b32 s84, 4
	s_cmp_eq_u32 s82, s84
	s_cselect_b64 s[26:27], -1, 0
	s_cmp_lg_u32 s82, s84
	s_cbranch_scc1 .LBB0_1034

.LBB0_1034:
	ds_read_b128 v[2:5], v189
	ds_read_b128 v[6:9], v189 offset:1024
	ds_read_b128 v[192:195], v189 offset:2048
	ds_read_b128 v[196:199], v189 offset:3072
	ds_read_b128 v[200:203], v189 offset:16384
	ds_read_b128 v[204:207], v189 offset:17408
	ds_read_b128 v[208:211], v189 offset:18432
	ds_read_b128 v[212:215], v189 offset:19456
	s_add_u32 s38, s36, 0xffea8080
	s_addc_u32 s39, s37, -1
	s_and_b64 s[26:27], s[26:27], exec
	s_cselect_b32 s26, s4, s40
	s_cselect_b32 s39, s1, s39
	s_cselect_b32 s38, s0, s38
	s_cselect_b32 s27, s5, s41
	s_mov_b32 m0, s25
	v_lshl_add_u64 v[176:177], s[36:37], 0, v[162:163]
	ds_read_b128 v[216:219], v190
	ds_read_b128 v[220:223], v190 offset:1024
	ds_read_b128 v[224:227], v190 offset:2048
	ds_read_b128 v[228:231], v190 offset:3072
	ds_read_b128 v[232:235], v190 offset:4096
	ds_read_b128 v[236:239], v190 offset:5120
	ds_read_b128 v[240:243], v190 offset:6144
	ds_read_b128 v[244:247], v190 offset:7168
	global_load_lds_dwordx4 v[176:177], off
	v_lshl_add_u64 v[176:177], s[36:37], 0, v[164:165]
	s_mov_b32 m0, s83
	s_nop 0
	global_load_lds_dwordx4 v[176:177], off
	s_waitcnt vmcnt(8)
	s_waitcnt lgkmcnt(0)
	s_setprio 1
	s_barrier
	v_mfma_f32_16x16x128_f8f6f4 v[134:137], v[2:9], v[216:223], v[134:137]
	v_mfma_f32_16x16x128_f8f6f4 v[130:133], v[192:199], v[216:223], v[130:133]
	v_mfma_f32_16x16x128_f8f6f4 v[122:125], v[192:199], v[224:231], v[122:125]
	v_mfma_f32_16x16x128_f8f6f4 v[126:129], v[2:9], v[224:231], v[126:129]
	v_mfma_f32_16x16x128_f8f6f4 v[118:121], v[2:9], v[232:239], v[118:121]
	v_mfma_f32_16x16x128_f8f6f4 v[114:117], v[192:199], v[232:239], v[114:117]
	v_mfma_f32_16x16x128_f8f6f4 v[106:109], v[192:199], v[240:247], v[106:109]
	v_mfma_f32_16x16x128_f8f6f4 v[110:113], v[2:9], v[240:247], v[110:113]
	s_setprio 0
	s_setprio 1
	v_mfma_f32_16x16x128_f8f6f4 v[78:81], v[200:207], v[240:247], v[78:81]
	v_mfma_f32_16x16x128_f8f6f4 v[74:77], v[208:215], v[240:247], v[74:77]
	v_mfma_f32_16x16x128_f8f6f4 v[82:85], v[208:215], v[232:239], v[82:85]
	v_mfma_f32_16x16x128_f8f6f4 v[86:89], v[200:207], v[232:239], v[86:89]
	v_mfma_f32_16x16x128_f8f6f4 v[94:97], v[200:207], v[224:231], v[94:97]
	v_mfma_f32_16x16x128_f8f6f4 v[90:93], v[208:215], v[224:231], v[90:93]
	s_barrier
	v_mfma_f32_16x16x128_f8f6f4 v[98:101], v[208:215], v[216:223], v[98:101]
	v_mfma_f32_16x16x128_f8f6f4 v[102:105], v[200:207], v[216:223], v[102:105]
	s_setprio 0
	s_mov_b32 m0, s33
	v_lshl_add_u64 v[176:177], s[26:27], 0, v[156:157]
	s_add_u32 s62, s26, 0x158000
	ds_read_b128 v[216:219], v190 offset:16384
	ds_read_b128 v[220:223], v190 offset:17408
	ds_read_b128 v[224:227], v190 offset:18432
	ds_read_b128 v[228:231], v190 offset:19456
	ds_read_b128 v[232:235], v190 offset:20480
	ds_read_b128 v[236:239], v190 offset:21504
	ds_read_b128 v[240:243], v190 offset:22528
	ds_read_b128 v[244:247], v190 offset:23552
	global_load_lds_dwordx4 v[176:177], off
	v_lshl_add_u64 v[182:183], s[26:27], 0, v[160:161]
	s_mov_b32 m0, s35
	s_addc_u32 s63, s27, 0
	global_load_lds_dwordx4 v[182:183], off
	v_lshl_add_u64 v[184:185], s[62:63], 0, v[156:157]
	s_mov_b32 m0, s42
	v_lshl_add_u64 v[186:187], s[38:39], 0, v[158:159]
	global_load_lds_dwordx4 v[184:185], off
	v_lshl_add_u64 v[184:185], s[62:63], 0, v[160:161]
	s_mov_b32 m0, s43
	s_nop 0
	global_load_lds_dwordx4 v[184:185], off
	v_lshl_add_u64 v[184:185], s[38:39], 0, v[154:155]
	s_mov_b32 m0, s23
	s_nop 0
	global_load_lds_dwordx4 v[184:185], off
	s_mov_b32 m0, s44
	s_nop 0
	global_load_lds_dwordx4 v[186:187], off
	s_waitcnt vmcnt(8)
	s_waitcnt lgkmcnt(0)
	s_setprio 1
	s_barrier
	v_mfma_f32_16x16x128_f8f6f4 v[70:73], v[2:9], v[216:223], v[70:73]
	v_mfma_f32_16x16x128_f8f6f4 v[66:69], v[192:199], v[216:223], v[66:69]
	v_mfma_f32_16x16x128_f8f6f4 v[58:61], v[192:199], v[224:231], v[58:61]
	v_mfma_f32_16x16x128_f8f6f4 v[62:65], v[2:9], v[224:231], v[62:65]
	v_mfma_f32_16x16x128_f8f6f4 v[54:57], v[2:9], v[232:239], v[54:57]
	v_mfma_f32_16x16x128_f8f6f4 v[50:53], v[192:199], v[232:239], v[50:53]
	v_mfma_f32_16x16x128_f8f6f4 v[42:45], v[192:199], v[240:247], v[42:45]
	v_mfma_f32_16x16x128_f8f6f4 v[46:49], v[2:9], v[240:247], v[46:49]
	s_setprio 0
	s_setprio 1
	v_mfma_f32_16x16x128_f8f6f4 v[14:17], v[200:207], v[240:247], v[14:17]
	v_mfma_f32_16x16x128_f8f6f4 v[10:13], v[208:215], v[240:247], v[10:13]
	v_mfma_f32_16x16x128_f8f6f4 v[18:21], v[208:215], v[232:239], v[18:21]
	v_mfma_f32_16x16x128_f8f6f4 v[22:25], v[200:207], v[232:239], v[22:25]
	v_mfma_f32_16x16x128_f8f6f4 v[30:33], v[200:207], v[224:231], v[30:33]
	v_mfma_f32_16x16x128_f8f6f4 v[26:29], v[208:215], v[224:231], v[26:29]
	s_barrier
	v_mfma_f32_16x16x128_f8f6f4 v[34:37], v[208:215], v[216:223], v[34:37]
	v_mfma_f32_16x16x128_f8f6f4 v[38:41], v[200:207], v[216:223], v[38:41]
	s_setprio 0
	ds_read_b128 v[192:195], v189 offset:32768
	ds_read_b128 v[196:199], v189 offset:33792
	ds_read_b128 v[200:203], v189 offset:34816
	ds_read_b128 v[204:207], v189 offset:35840
	ds_read_b128 v[2:5], v189 offset:49152
	ds_read_b128 v[6:9], v189 offset:50176
	ds_read_b128 v[208:211], v189 offset:51200
	ds_read_b128 v[212:215], v189 offset:52224
	s_add_u32 s38, s38, 0x158000
	s_addc_u32 s39, s39, 0
	s_mov_b32 m0, s45
	v_lshl_add_u64 v[248:249], s[38:39], 0, v[154:155]
	ds_read_b128 v[216:219], v190 offset:32768
	ds_read_b128 v[220:223], v190 offset:33792
	ds_read_b128 v[224:227], v190 offset:34816
	ds_read_b128 v[228:231], v190 offset:35840
	ds_read_b128 v[232:235], v190 offset:36864
	ds_read_b128 v[236:239], v190 offset:37888
	ds_read_b128 v[240:243], v190 offset:38912
	ds_read_b128 v[244:247], v190 offset:39936
	global_load_lds_dwordx4 v[248:249], off
	v_lshl_add_u64 v[248:249], s[38:39], 0, v[158:159]
	s_mov_b32 m0, s46
	s_nop 0
	global_load_lds_dwordx4 v[248:249], off
	s_waitcnt vmcnt(8)
	s_waitcnt lgkmcnt(0)
	s_setprio 1
	s_barrier
	v_mfma_f32_16x16x128_f8f6f4 v[134:137], v[192:199], v[216:223], v[134:137]
	v_mfma_f32_16x16x128_f8f6f4 v[130:133], v[200:207], v[216:223], v[130:133]
	v_mfma_f32_16x16x128_f8f6f4 v[122:125], v[200:207], v[224:231], v[122:125]
	v_mfma_f32_16x16x128_f8f6f4 v[126:129], v[192:199], v[224:231], v[126:129]
	v_mfma_f32_16x16x128_f8f6f4 v[118:121], v[192:199], v[232:239], v[118:121]
	v_mfma_f32_16x16x128_f8f6f4 v[114:117], v[200:207], v[232:239], v[114:117]
	v_mfma_f32_16x16x128_f8f6f4 v[106:109], v[200:207], v[240:247], v[106:109]
	v_mfma_f32_16x16x128_f8f6f4 v[110:113], v[192:199], v[240:247], v[110:113]
	s_setprio 0
	s_setprio 1
	v_mfma_f32_16x16x128_f8f6f4 v[78:81], v[2:9], v[240:247], v[78:81]
	v_mfma_f32_16x16x128_f8f6f4 v[74:77], v[208:215], v[240:247], v[74:77]
	v_mfma_f32_16x16x128_f8f6f4 v[82:85], v[208:215], v[232:239], v[82:85]
	v_mfma_f32_16x16x128_f8f6f4 v[86:89], v[2:9], v[232:239], v[86:89]
	v_mfma_f32_16x16x128_f8f6f4 v[94:97], v[2:9], v[224:231], v[94:97]
	v_mfma_f32_16x16x128_f8f6f4 v[90:93], v[208:215], v[224:231], v[90:93]
	s_barrier
	v_mfma_f32_16x16x128_f8f6f4 v[98:101], v[208:215], v[216:223], v[98:101]
	v_mfma_f32_16x16x128_f8f6f4 v[102:105], v[2:9], v[216:223], v[102:105]
	s_setprio 0
	s_mov_b32 m0, s52
	v_lshl_add_u64 v[176:177], v[176:177], 0, s[14:15]
	s_add_u32 s26, s26, 0x158080
	ds_read_b128 v[216:219], v190 offset:49152
	ds_read_b128 v[220:223], v190 offset:50176
	ds_read_b128 v[224:227], v190 offset:51200
	ds_read_b128 v[228:231], v190 offset:52224
	ds_read_b128 v[232:235], v190 offset:53248
	ds_read_b128 v[236:239], v190 offset:54272
	ds_read_b128 v[240:243], v190 offset:55296
	ds_read_b128 v[244:247], v190 offset:56320
	global_load_lds_dwordx4 v[176:177], off
	v_lshl_add_u64 v[176:177], v[182:183], 0, s[14:15]
	s_mov_b32 m0, s53
	s_addc_u32 s27, s27, 0
	global_load_lds_dwordx4 v[176:177], off
	v_lshl_add_u64 v[176:177], s[26:27], 0, v[156:157]
	s_mov_b32 m0, s56
	s_nop 0
	global_load_lds_dwordx4 v[176:177], off
	v_lshl_add_u64 v[176:177], s[26:27], 0, v[160:161]
	s_mov_b32 m0, s57
	s_nop 0
	global_load_lds_dwordx4 v[176:177], off
	v_lshl_add_u64 v[176:177], v[184:185], 0, s[14:15]
	s_mov_b32 m0, s54
	s_nop 0
	global_load_lds_dwordx4 v[176:177], off
	v_lshl_add_u64 v[176:177], v[186:187], 0, s[14:15]
	s_mov_b32 m0, s55
	s_nop 0
	global_load_lds_dwordx4 v[176:177], off
	s_waitcnt vmcnt(8)
	s_waitcnt lgkmcnt(0)
	s_setprio 1
	s_barrier
	v_mfma_f32_16x16x128_f8f6f4 v[70:73], v[192:199], v[216:223], v[70:73]
	v_mfma_f32_16x16x128_f8f6f4 v[66:69], v[200:207], v[216:223], v[66:69]
	v_mfma_f32_16x16x128_f8f6f4 v[58:61], v[200:207], v[224:231], v[58:61]
	v_mfma_f32_16x16x128_f8f6f4 v[62:65], v[192:199], v[224:231], v[62:65]
	v_mfma_f32_16x16x128_f8f6f4 v[54:57], v[192:199], v[232:239], v[54:57]
	v_mfma_f32_16x16x128_f8f6f4 v[50:53], v[200:207], v[232:239], v[50:53]
	v_mfma_f32_16x16x128_f8f6f4 v[42:45], v[200:207], v[240:247], v[42:45]
	v_mfma_f32_16x16x128_f8f6f4 v[46:49], v[192:199], v[240:247], v[46:49]
	s_setprio 0
	s_setprio 1
	v_mfma_f32_16x16x128_f8f6f4 v[14:17], v[2:9], v[240:247], v[14:17]
	v_mfma_f32_16x16x128_f8f6f4 v[10:13], v[208:215], v[240:247], v[10:13]
	v_mfma_f32_16x16x128_f8f6f4 v[18:21], v[208:215], v[232:239], v[18:21]
	v_mfma_f32_16x16x128_f8f6f4 v[22:25], v[2:9], v[232:239], v[22:25]
	v_mfma_f32_16x16x128_f8f6f4 v[30:33], v[2:9], v[224:231], v[30:33]
	v_mfma_f32_16x16x128_f8f6f4 v[26:29], v[208:215], v[224:231], v[26:29]
	s_barrier
	v_mfma_f32_16x16x128_f8f6f4 v[34:37], v[208:215], v[216:223], v[34:37]
	v_mfma_f32_16x16x128_f8f6f4 v[38:41], v[2:9], v[216:223], v[38:41]
	s_setprio 0
	s_add_i32 s26, s84, 2
	s_add_u32 s36, s36, 0x100
	s_addc_u32 s37, s37, 0
	s_add_u32 s40, s40, 0x100
	s_addc_u32 s41, s41, 0
	s_cmp_ge_i32 s84, s82
	s_cbranch_scc1 .LBB0_1036
	s_mov_b32 s84, s26
	s_cmp_eq_u32 s82, s84
	s_cselect_b64 s[26:27], -1, 0
	s_cmp_lg_u32 s82, s84
	s_cbranch_scc0 .LBB0_1033
	s_branch .LBB0_1034
